# Waitcnt placement: the vmcnt and lgkmcnt waits before each GEMM barrier merged into one s_waitcnt (one fewer instruction between the last wait and the barrier), 44 sites; on top of v40
# speedup vs baseline: 1.0011x; 1.0011x over previous
; #define PG8_STAGE(bufoff, gbase, voff) do { _Pragma("unroll") for (int _i = 0; _i < 2; ++_i) \
;         __builtin_amdgcn_global_load_lds((const unsigned*)((const char*)(gbase) + (voff)[_i]), (PG8_LAS unsigned*)(lds + (bufoff) + ldsw + _i * 8192), 16, 0, 0); } while (0)
; #define PG8_LDA(dst, b, h) do { _Pragma("unroll") for (int m = 0; m < 4; ++m) _Pragma("unroll") for (int k = 0; k < 2; ++k) dst[m][k] = *(const PG8_LAS bf16x8*)(lds + PG8_SA(b, h) + aoff + m * 2048 + k * 1024); } while (0)
; #define PG8_LDB(dst, b, h) do { _Pragma("unroll") for (int n = 0; n < 2; ++n) _Pragma("unroll") for (int k = 0; k < 2; ++k) dst[n][k] = *(const PG8_LAS bf16x8*)(lds + PG8_SB(b, h) + boff + n * 2048 + k * 1024); } while (0)
; #define PG8_BAR __builtin_amdgcn_s_barrier()
; template <class Epi, class Sched, bool ALIGN_EPI = false, bool SP2 = false>
; __device__ __forceinline__ void gemm_phase(PG8_LAS unsigned char* lds, const Gemm g, const Sched& S, const Epi& E) {
;     ...
;             const bool last = (t == nt - 2);
;             const char* a1 = cA + (size_t)(t + 1) * kstep;
;             const char* a2 = last ? nA : cA + (size_t)(t + 2) * kstep; const char* b2 = last ? nB : cB + (size_t)(t + 2) * kstep;
;             const char* a3 = a2 + kstep; const char* b3 = b2 + kstep;
;             if (last && has_next) S.a_ready(nxt);
;             if constexpr (SP2) {
;             PG8_LDB(B0, 0, 0); PG8_LDB(B1, 0, 1); PG8_SCHED; PG8_LDA(At, 0, 0); PG8_STAGE(PG8_SA(1, 1), a1 + hstepA, voffA);
;             PG8_WAIT_V(8); PG8_WAIT_L(0); PG8_BAR; PG8_MMA(0, 0, At, B0); PG8_MMA(0, 1, At, B1); PG8_BAR; PG8_SCHED;
;             PG8_LDA(At, 0, 1); PG8_STAGE(PG8_SB(0, 0), b2, voffB); PG8_STAGE(PG8_SB(0, 1), b2 + hstepB, voffB); PG8_STAGE(PG8_SA(0, 0), a2, voffA);
;             PG8_WAIT_V(8); PG8_WAIT_L(0); PG8_BAR; PG8_MMA(1, 0, At, B0); PG8_MMA(1, 1, At, B1); PG8_BAR; PG8_SCHED;
;             PG8_LDB(B0, 1, 0); PG8_LDB(B1, 1, 1); PG8_SCHED; PG8_LDA(At, 1, 0); PG8_STAGE(PG8_SA(0, 1), a2 + hstepA, voffA);
;             PG8_WAIT_V(8); PG8_WAIT_L(0); PG8_BAR; PG8_MMA(0, 0, At, B0); PG8_MMA(0, 1, At, B1); PG8_BAR; PG8_SCHED;
;             PG8_LDA(At, 1, 1); PG8_STAGE(PG8_SB(1, 0), b3, voffB); PG8_STAGE(PG8_SB(1, 1), b3 + hstepB, voffB); PG8_STAGE(PG8_SA(1, 0), a3, voffA);
;             PG8_WAIT_V(8); PG8_WAIT_L(0); PG8_BAR; PG8_MMA(1, 0, At, B0); PG8_MMA(1, 1, At, B1); PG8_BAR; PG8_SCHED;
.LBB0_254:
	s_add_u32 s28, s26, 0xfffc0080
	s_addc_u32 s29, s27, -1
	s_add_i32 s53, 0, 0x10000
	s_cmp_eq_u32 s52, 12
	s_cselect_b32 s31, s7, s29
	s_cselect_b32 s30, s9, s28
	v_add_u32_e32 v150, s53, v153
	s_cselect_b32 s29, s19, s51
	s_cselect_b32 s28, s21, s50
	s_add_i32 s56, 0, 0x14000
	ds_read_b128 v[142:145], v150
	ds_read_b128 v[146:149], v150 offset:1024
	ds_read_b128 v[158:161], v150 offset:2048
	ds_read_b128 v[162:165], v150 offset:3072
	v_add_u32_e32 v150, s56, v153
	ds_read_b128 v[166:169], v150
	ds_read_b128 v[170:173], v150 offset:1024
	ds_read_b128 v[174:177], v150 offset:2048
	ds_read_b128 v[178:181], v150 offset:3072
	s_add_i32 m0, s40, 0xc000
	ds_read_b128 v[182:185], v156
	ds_read_b128 v[202:205], v156 offset:1024
	ds_read_b128 v[206:209], v156 offset:2048
	ds_read_b128 v[210:213], v156 offset:3072
	ds_read_b128 v[232:235], v156 offset:4096
	ds_read_b128 v[236:239], v156 offset:5120
	ds_read_b128 v[240:243], v156 offset:6144
	ds_read_b128 v[244:247], v156 offset:7168
	global_load_lds_dwordx4 v138, s[26:27]
	s_add_i32 m0, s40, 0xe000
	s_nop 0
	global_load_lds_dwordx4 v140, s[26:27]
	s_waitcnt vmcnt(8) lgkmcnt(0)
	s_barrier
	s_setprio 1
	v_mfma_f32_16x16x32_bf16 v[126:129], v[142:145], v[182:185], v[126:129]
	v_mfma_f32_16x16x32_bf16 v[122:125], v[158:161], v[182:185], v[122:125]
	v_mfma_f32_16x16x32_bf16 v[110:113], v[142:145], v[206:209], v[110:113]
	v_mfma_f32_16x16x32_bf16 v[106:109], v[158:161], v[206:209], v[106:109]
	v_mfma_f32_16x16x32_bf16 v[94:97], v[142:145], v[232:235], v[94:97]
	v_mfma_f32_16x16x32_bf16 v[90:93], v[158:161], v[232:235], v[90:93]
	v_mfma_f32_16x16x32_bf16 v[78:81], v[142:145], v[240:243], v[78:81]
	v_mfma_f32_16x16x32_bf16 v[74:77], v[158:161], v[240:243], v[74:77]
	v_mfma_f32_16x16x32_bf16 v[126:129], v[146:149], v[202:205], v[126:129]
	v_mfma_f32_16x16x32_bf16 v[122:125], v[162:165], v[202:205], v[122:125]
	v_mfma_f32_16x16x32_bf16 v[110:113], v[146:149], v[210:213], v[110:113]
	v_mfma_f32_16x16x32_bf16 v[106:109], v[162:165], v[210:213], v[106:109]
	v_mfma_f32_16x16x32_bf16 v[94:97], v[146:149], v[236:239], v[94:97]
	v_mfma_f32_16x16x32_bf16 v[90:93], v[162:165], v[236:239], v[90:93]
	v_mfma_f32_16x16x32_bf16 v[78:81], v[146:149], v[244:247], v[78:81]
	v_mfma_f32_16x16x32_bf16 v[74:77], v[162:165], v[244:247], v[74:77]
	s_setprio 0
	s_setprio 1
	v_mfma_f32_16x16x32_bf16 v[118:121], v[166:169], v[182:185], v[118:121]
	v_mfma_f32_16x16x32_bf16 v[114:117], v[174:177], v[182:185], v[114:117]
	v_mfma_f32_16x16x32_bf16 v[102:105], v[166:169], v[206:209], v[102:105]
	v_mfma_f32_16x16x32_bf16 v[98:101], v[174:177], v[206:209], v[98:101]
	v_mfma_f32_16x16x32_bf16 v[86:89], v[166:169], v[232:235], v[86:89]
	v_mfma_f32_16x16x32_bf16 v[82:85], v[174:177], v[232:235], v[82:85]
	v_mfma_f32_16x16x32_bf16 v[70:73], v[166:169], v[240:243], v[70:73]
	v_mfma_f32_16x16x32_bf16 v[66:69], v[174:177], v[240:243], v[66:69]
	v_mfma_f32_16x16x32_bf16 v[118:121], v[170:173], v[202:205], v[118:121]
	v_mfma_f32_16x16x32_bf16 v[114:117], v[178:181], v[202:205], v[114:117]
	v_mfma_f32_16x16x32_bf16 v[102:105], v[170:173], v[210:213], v[102:105]
	v_mfma_f32_16x16x32_bf16 v[98:101], v[178:181], v[210:213], v[98:101]
	v_mfma_f32_16x16x32_bf16 v[86:89], v[170:173], v[236:239], v[86:89]
	v_mfma_f32_16x16x32_bf16 v[82:85], v[178:181], v[236:239], v[82:85]
	v_mfma_f32_16x16x32_bf16 v[70:73], v[170:173], v[244:247], v[70:73]
	v_mfma_f32_16x16x32_bf16 v[66:69], v[178:181], v[244:247], v[66:69]
	s_setprio 0
	s_barrier
	s_add_i32 s53, s53, s39
	s_mov_b32 m0, s53
	ds_read_b128 v[182:185], v156 offset:16384
	ds_read_b128 v[202:205], v156 offset:17408
	ds_read_b128 v[206:209], v156 offset:18432
	ds_read_b128 v[210:213], v156 offset:19456
	ds_read_b128 v[232:235], v156 offset:20480
	ds_read_b128 v[236:239], v156 offset:21504
	ds_read_b128 v[240:243], v156 offset:22528
	ds_read_b128 v[244:247], v156 offset:23552
	s_add_u32 s60, s28, 0x80
	s_addc_u32 s61, s29, 0
	s_add_u32 s62, s30, 0x80
	s_addc_u32 s63, s31, 0
	global_load_lds_dwordx4 v132, s[28:29]
	s_add_i32 m0, s53, 0x2000
	s_add_u32 s54, s28, 0x40000
	s_addc_u32 s55, s29, 0
	s_add_i32 s53, s56, s39
	global_load_lds_dwordx4 v136, s[28:29]
	s_mov_b32 m0, s53
	s_nop 0
	global_load_lds_dwordx4 v132, s[54:55]
	s_add_i32 m0, s53, 0x2000
	s_nop 0
	global_load_lds_dwordx4 v136, s[54:55]
	s_mov_b32 m0, s40
	s_nop 0
	global_load_lds_dwordx4 v130, s[30:31]
	s_mov_b32 m0, s41
	s_nop 0
	global_load_lds_dwordx4 v134, s[30:31]
	s_waitcnt vmcnt(8) lgkmcnt(0)
	s_barrier
	s_setprio 1
	v_mfma_f32_16x16x32_bf16 v[62:65], v[142:145], v[182:185], v[62:65]
	v_mfma_f32_16x16x32_bf16 v[58:61], v[158:161], v[182:185], v[58:61]
	v_mfma_f32_16x16x32_bf16 v[46:49], v[142:145], v[206:209], v[46:49]
	v_mfma_f32_16x16x32_bf16 v[42:45], v[158:161], v[206:209], v[42:45]
	v_mfma_f32_16x16x32_bf16 v[30:33], v[142:145], v[232:235], v[30:33]
	v_mfma_f32_16x16x32_bf16 v[26:29], v[158:161], v[232:235], v[26:29]
	v_mfma_f32_16x16x32_bf16 v[14:17], v[142:145], v[240:243], v[14:17]
	v_mfma_f32_16x16x32_bf16 v[10:13], v[158:161], v[240:243], v[10:13]
	v_mfma_f32_16x16x32_bf16 v[62:65], v[146:149], v[202:205], v[62:65]
	v_mfma_f32_16x16x32_bf16 v[58:61], v[162:165], v[202:205], v[58:61]
	v_mfma_f32_16x16x32_bf16 v[46:49], v[146:149], v[210:213], v[46:49]
	v_mfma_f32_16x16x32_bf16 v[42:45], v[162:165], v[210:213], v[42:45]
	v_mfma_f32_16x16x32_bf16 v[30:33], v[146:149], v[236:239], v[30:33]
	v_mfma_f32_16x16x32_bf16 v[26:29], v[162:165], v[236:239], v[26:29]
	v_mfma_f32_16x16x32_bf16 v[14:17], v[146:149], v[244:247], v[14:17]
	v_mfma_f32_16x16x32_bf16 v[10:13], v[162:165], v[244:247], v[10:13]
	s_setprio 0
	s_setprio 1
	v_mfma_f32_16x16x32_bf16 v[54:57], v[166:169], v[182:185], v[54:57]
	v_mfma_f32_16x16x32_bf16 v[50:53], v[174:177], v[182:185], v[50:53]
	v_mfma_f32_16x16x32_bf16 v[38:41], v[166:169], v[206:209], v[38:41]
	v_mfma_f32_16x16x32_bf16 v[34:37], v[174:177], v[206:209], v[34:37]
	v_mfma_f32_16x16x32_bf16 v[22:25], v[166:169], v[232:235], v[22:25]
	v_mfma_f32_16x16x32_bf16 v[18:21], v[174:177], v[232:235], v[18:21]
	v_mfma_f32_16x16x32_bf16 v[6:9], v[166:169], v[240:243], v[6:9]
	v_mfma_f32_16x16x32_bf16 v[2:5], v[174:177], v[240:243], v[2:5]
	v_mfma_f32_16x16x32_bf16 v[54:57], v[170:173], v[202:205], v[54:57]
	v_mfma_f32_16x16x32_bf16 v[50:53], v[178:181], v[202:205], v[50:53]
	v_mfma_f32_16x16x32_bf16 v[38:41], v[170:173], v[210:213], v[38:41]
	v_mfma_f32_16x16x32_bf16 v[34:37], v[178:181], v[210:213], v[34:37]
	v_mfma_f32_16x16x32_bf16 v[22:25], v[170:173], v[236:239], v[22:25]
	v_mfma_f32_16x16x32_bf16 v[18:21], v[178:181], v[236:239], v[18:21]
	v_mfma_f32_16x16x32_bf16 v[6:9], v[170:173], v[244:247], v[6:9]
	v_mfma_f32_16x16x32_bf16 v[2:5], v[178:181], v[244:247], v[2:5]
	s_setprio 0
	s_barrier
; #define PG8_STAGE(bufoff, gbase, voff) do { _Pragma("unroll") for (int _i = 0; _i < 2; ++_i) \
;         __builtin_amdgcn_global_load_lds((const unsigned*)((const char*)(gbase) + (voff)[_i]), (PG8_LAS unsigned*)(lds + (bufoff) + ldsw + _i * 8192), 16, 0, 0); } while (0)
; #define PG8_LDA(dst, b, h) do { _Pragma("unroll") for (int m = 0; m < 4; ++m) _Pragma("unroll") for (int k = 0; k < 2; ++k) dst[m][k] = *(const PG8_LAS bf16x8*)(lds + PG8_SA(b, h) + aoff + m * 2048 + k * 1024); } while (0)
; #define PG8_LDB(dst, b, h) do { _Pragma("unroll") for (int n = 0; n < 2; ++n) _Pragma("unroll") for (int k = 0; k < 2; ++k) dst[n][k] = *(const PG8_LAS bf16x8*)(lds + PG8_SB(b, h) + boff + n * 2048 + k * 1024); } while (0)
; #define PG8_MMA(ai, bj, At, Bt) do { __builtin_amdgcn_s_setprio(1); _Pragma("unroll") for (int m = 0; m < 4; ++m) _Pragma("unroll") for (int n = 0; n < 2; ++n) _Pragma("unroll") for (int k = 0; k < 2; ++k) \
;         acc[ai][bj][m][n] = __builtin_amdgcn_mfma_f32_16x16x32_bf16(Bt[n][k], At[m][k], acc[ai][bj][m][n], 0, 0, 0); __builtin_amdgcn_s_setprio(0); } while (0)
; template <class Epi, class Sched, bool ALIGN_EPI = false, bool SP2 = false>
; __device__ __forceinline__ void gemm_phase(PG8_LAS unsigned char* lds, const Gemm g, const Sched& S, const Epi& E) {
;     ...
;         for (int t = 0; t < nt; t += 2) {
;     ...
;             PG8_LDB(B0, 0, 0); PG8_LDB(B1, 0, 1); PG8_SCHED; PG8_LDA(At, 0, 0); PG8_STAGE(PG8_SA(1, 1), a1 + hstepA, voffA);
;             PG8_WAIT_V(8); PG8_WAIT_L(0); PG8_BAR; PG8_MMA(0, 0, At, B0); PG8_MMA(0, 1, At, B1); PG8_BAR; PG8_SCHED;
;             PG8_LDA(At, 0, 1); PG8_STAGE(PG8_SB(0, 0), b2, voffB); PG8_STAGE(PG8_SB(0, 1), b2 + hstepB, voffB); PG8_STAGE(PG8_SA(0, 0), a2, voffA);
;             PG8_WAIT_V(8); PG8_WAIT_L(0); PG8_BAR; PG8_MMA(1, 0, At, B0); PG8_MMA(1, 1, At, B1); PG8_BAR; PG8_SCHED;
;             PG8_LDB(B0, 1, 0); PG8_LDB(B1, 1, 1); PG8_SCHED; PG8_LDA(At, 1, 0); PG8_STAGE(PG8_SA(0, 1), a2 + hstepA, voffA);
;             PG8_WAIT_V(8); PG8_WAIT_L(0); PG8_BAR; PG8_MMA(0, 0, At, B0); PG8_MMA(0, 1, At, B1); PG8_BAR; PG8_SCHED;
;             PG8_LDA(At, 1, 1); PG8_STAGE(PG8_SB(1, 0), b3, voffB); PG8_STAGE(PG8_SB(1, 1), b3 + hstepB, voffB); PG8_STAGE(PG8_SA(1, 0), a3, voffA);
;             PG8_WAIT_V(8); PG8_WAIT_L(0); PG8_BAR; PG8_MMA(1, 0, At, B0); PG8_MMA(1, 1, At, B1); PG8_BAR; PG8_SCHED;
	s_add_i32 s53, 0, 0x18000
	v_add_u32_e32 v157, s53, v153
	s_add_i32 s54, 0, 0x1c000
	ds_read_b128 v[142:145], v157
	ds_read_b128 v[146:149], v157 offset:1024
	ds_read_b128 v[158:161], v157 offset:2048
	ds_read_b128 v[162:165], v157 offset:3072
	v_add_u32_e32 v157, s54, v153
	ds_read_b128 v[166:169], v157
	ds_read_b128 v[170:173], v157 offset:1024
	ds_read_b128 v[174:177], v157 offset:2048
	ds_read_b128 v[178:181], v157 offset:3072
	s_add_u32 s30, s30, 0x40000
	s_addc_u32 s31, s31, 0
	s_mov_b32 m0, s42
	ds_read_b128 v[182:185], v156 offset:32768
	ds_read_b128 v[202:205], v156 offset:33792
	ds_read_b128 v[206:209], v156 offset:34816
	ds_read_b128 v[210:213], v156 offset:35840
	ds_read_b128 v[232:235], v156 offset:36864
	ds_read_b128 v[236:239], v156 offset:37888
	ds_read_b128 v[240:243], v156 offset:38912
	ds_read_b128 v[244:247], v156 offset:39936
	global_load_lds_dwordx4 v130, s[30:31]
	s_mov_b32 m0, s43
	s_nop 0
	global_load_lds_dwordx4 v134, s[30:31]
	s_waitcnt vmcnt(8) lgkmcnt(0)
	s_barrier
	s_setprio 1
	v_mfma_f32_16x16x32_bf16 v[126:129], v[142:145], v[182:185], v[126:129]
	v_mfma_f32_16x16x32_bf16 v[122:125], v[158:161], v[182:185], v[122:125]
	v_mfma_f32_16x16x32_bf16 v[110:113], v[142:145], v[206:209], v[110:113]
	v_mfma_f32_16x16x32_bf16 v[106:109], v[158:161], v[206:209], v[106:109]
	v_mfma_f32_16x16x32_bf16 v[94:97], v[142:145], v[232:235], v[94:97]
	v_mfma_f32_16x16x32_bf16 v[90:93], v[158:161], v[232:235], v[90:93]
	v_mfma_f32_16x16x32_bf16 v[78:81], v[142:145], v[240:243], v[78:81]
	v_mfma_f32_16x16x32_bf16 v[74:77], v[158:161], v[240:243], v[74:77]
	v_mfma_f32_16x16x32_bf16 v[126:129], v[146:149], v[202:205], v[126:129]
	v_mfma_f32_16x16x32_bf16 v[122:125], v[162:165], v[202:205], v[122:125]
	v_mfma_f32_16x16x32_bf16 v[110:113], v[146:149], v[210:213], v[110:113]
	v_mfma_f32_16x16x32_bf16 v[106:109], v[162:165], v[210:213], v[106:109]
	v_mfma_f32_16x16x32_bf16 v[94:97], v[146:149], v[236:239], v[94:97]
	v_mfma_f32_16x16x32_bf16 v[90:93], v[162:165], v[236:239], v[90:93]
	v_mfma_f32_16x16x32_bf16 v[78:81], v[146:149], v[244:247], v[78:81]
	v_mfma_f32_16x16x32_bf16 v[74:77], v[162:165], v[244:247], v[74:77]
	s_setprio 0
	s_setprio 1
	v_mfma_f32_16x16x32_bf16 v[118:121], v[166:169], v[182:185], v[118:121]
	v_mfma_f32_16x16x32_bf16 v[114:117], v[174:177], v[182:185], v[114:117]
	v_mfma_f32_16x16x32_bf16 v[102:105], v[166:169], v[206:209], v[102:105]
	v_mfma_f32_16x16x32_bf16 v[98:101], v[174:177], v[206:209], v[98:101]
	v_mfma_f32_16x16x32_bf16 v[86:89], v[166:169], v[232:235], v[86:89]
	v_mfma_f32_16x16x32_bf16 v[82:85], v[174:177], v[232:235], v[82:85]
	v_mfma_f32_16x16x32_bf16 v[70:73], v[166:169], v[240:243], v[70:73]
	v_mfma_f32_16x16x32_bf16 v[66:69], v[174:177], v[240:243], v[66:69]
	v_mfma_f32_16x16x32_bf16 v[118:121], v[170:173], v[202:205], v[118:121]
	v_mfma_f32_16x16x32_bf16 v[114:117], v[178:181], v[202:205], v[114:117]
	v_mfma_f32_16x16x32_bf16 v[102:105], v[170:173], v[210:213], v[102:105]
	v_mfma_f32_16x16x32_bf16 v[98:101], v[178:181], v[210:213], v[98:101]
	v_mfma_f32_16x16x32_bf16 v[86:89], v[170:173], v[236:239], v[86:89]
	v_mfma_f32_16x16x32_bf16 v[82:85], v[178:181], v[236:239], v[82:85]
	v_mfma_f32_16x16x32_bf16 v[70:73], v[170:173], v[244:247], v[70:73]
	v_mfma_f32_16x16x32_bf16 v[66:69], v[178:181], v[244:247], v[66:69]
	s_setprio 0
	s_barrier
	s_add_i32 s30, s53, s39
	s_mov_b32 m0, s30
	ds_read_b128 v[182:185], v156 offset:49152
	ds_read_b128 v[202:205], v156 offset:50176
	ds_read_b128 v[206:209], v156 offset:51200
	ds_read_b128 v[210:213], v156 offset:52224
	ds_read_b128 v[232:235], v156 offset:53248
	ds_read_b128 v[236:239], v156 offset:54272
	ds_read_b128 v[240:243], v156 offset:55296
	ds_read_b128 v[244:247], v156 offset:56320
	global_load_lds_dwordx4 v132, s[60:61]
	s_add_i32 m0, s30, 0x2000
	s_add_u32 s28, s28, 0x40080
	s_addc_u32 s29, s29, 0
	s_add_i32 s30, s54, s39
	global_load_lds_dwordx4 v136, s[60:61]
	s_mov_b32 m0, s30
	s_nop 0
	global_load_lds_dwordx4 v132, s[28:29]
	s_add_i32 m0, s30, 0x2000
	s_nop 0
	global_load_lds_dwordx4 v136, s[28:29]
	s_mov_b32 m0, s45
	s_nop 0
	global_load_lds_dwordx4 v130, s[62:63]
	s_mov_b32 m0, s46
	s_nop 0
	global_load_lds_dwordx4 v134, s[62:63]
	s_waitcnt vmcnt(8) lgkmcnt(0)
	s_barrier
	s_setprio 1
	v_mfma_f32_16x16x32_bf16 v[62:65], v[142:145], v[182:185], v[62:65]
	v_mfma_f32_16x16x32_bf16 v[58:61], v[158:161], v[182:185], v[58:61]
	v_mfma_f32_16x16x32_bf16 v[46:49], v[142:145], v[206:209], v[46:49]
	v_mfma_f32_16x16x32_bf16 v[42:45], v[158:161], v[206:209], v[42:45]
	v_mfma_f32_16x16x32_bf16 v[30:33], v[142:145], v[232:235], v[30:33]
	v_mfma_f32_16x16x32_bf16 v[26:29], v[158:161], v[232:235], v[26:29]
	v_mfma_f32_16x16x32_bf16 v[14:17], v[142:145], v[240:243], v[14:17]
	v_mfma_f32_16x16x32_bf16 v[10:13], v[158:161], v[240:243], v[10:13]
	v_mfma_f32_16x16x32_bf16 v[62:65], v[146:149], v[202:205], v[62:65]
	v_mfma_f32_16x16x32_bf16 v[58:61], v[162:165], v[202:205], v[58:61]
	v_mfma_f32_16x16x32_bf16 v[46:49], v[146:149], v[210:213], v[46:49]
	v_mfma_f32_16x16x32_bf16 v[42:45], v[162:165], v[210:213], v[42:45]
	v_mfma_f32_16x16x32_bf16 v[30:33], v[146:149], v[236:239], v[30:33]
	v_mfma_f32_16x16x32_bf16 v[26:29], v[162:165], v[236:239], v[26:29]
	v_mfma_f32_16x16x32_bf16 v[14:17], v[146:149], v[244:247], v[14:17]
	v_mfma_f32_16x16x32_bf16 v[10:13], v[162:165], v[244:247], v[10:13]
	s_setprio 0
	s_setprio 1
	v_mfma_f32_16x16x32_bf16 v[54:57], v[166:169], v[182:185], v[54:57]
	v_mfma_f32_16x16x32_bf16 v[50:53], v[174:177], v[182:185], v[50:53]
	v_mfma_f32_16x16x32_bf16 v[38:41], v[166:169], v[206:209], v[38:41]
	v_mfma_f32_16x16x32_bf16 v[34:37], v[174:177], v[206:209], v[34:37]
	v_mfma_f32_16x16x32_bf16 v[22:25], v[166:169], v[232:235], v[22:25]
	v_mfma_f32_16x16x32_bf16 v[18:21], v[174:177], v[232:235], v[18:21]
	v_mfma_f32_16x16x32_bf16 v[6:9], v[166:169], v[240:243], v[6:9]
	v_mfma_f32_16x16x32_bf16 v[2:5], v[174:177], v[240:243], v[2:5]
	v_mfma_f32_16x16x32_bf16 v[54:57], v[170:173], v[202:205], v[54:57]
	v_mfma_f32_16x16x32_bf16 v[50:53], v[178:181], v[202:205], v[50:53]
	v_mfma_f32_16x16x32_bf16 v[38:41], v[170:173], v[210:213], v[38:41]
	v_mfma_f32_16x16x32_bf16 v[34:37], v[178:181], v[210:213], v[34:37]
	v_mfma_f32_16x16x32_bf16 v[22:25], v[170:173], v[236:239], v[22:25]
	v_mfma_f32_16x16x32_bf16 v[18:21], v[178:181], v[236:239], v[18:21]
	v_mfma_f32_16x16x32_bf16 v[6:9], v[170:173], v[244:247], v[6:9]
	v_mfma_f32_16x16x32_bf16 v[2:5], v[178:181], v[244:247], v[2:5]
	s_setprio 0
	s_barrier
	s_add_i32 s52, s52, 2
	s_add_u32 s26, s26, 0x100
	s_addc_u32 s27, s27, 0
	s_add_u32 s50, s50, 0x100
	s_addc_u32 s51, s51, 0
	s_cmp_gt_u32 s52, 13
	s_cbranch_scc0 .LBB0_254
	s_and_b64 vcc, exec, s[16:17]
	s_cbranch_vccz .LBB0_257
	s_barrier

; #define PG8_STAGE(bufoff, gbase, voff) do { _Pragma("unroll") for (int _i = 0; _i < 2; ++_i) \
;         __builtin_amdgcn_global_load_lds((const unsigned*)((const char*)(gbase) + (voff)[_i]), (PG8_LAS unsigned*)(lds + (bufoff) + ldsw + _i * 8192), 16, 0, 0); } while (0)
; #define PG8_LDA(dst, b, h) do { _Pragma("unroll") for (int m = 0; m < 4; ++m) _Pragma("unroll") for (int k = 0; k < 2; ++k) dst[m][k] = *(const PG8_LAS bf16x8*)(lds + PG8_SA(b, h) + aoff + m * 2048 + k * 1024); } while (0)
; #define PG8_LDB(dst, b, h) do { _Pragma("unroll") for (int n = 0; n < 2; ++n) _Pragma("unroll") for (int k = 0; k < 2; ++k) dst[n][k] = *(const PG8_LAS bf16x8*)(lds + PG8_SB(b, h) + boff + n * 2048 + k * 1024); } while (0)
; #define PG8_BAR __builtin_amdgcn_s_barrier()
; template <class Epi, class Sched, bool ALIGN_EPI = false, bool SP2 = false>
; __device__ __forceinline__ void gemm_phase(PG8_LAS unsigned char* lds, const Gemm g, const Sched& S, const Epi& E) {
;     ...
;             const bool last = (t == nt - 2);
;             const char* a1 = cA + (size_t)(t + 1) * kstep;
;             const char* a2 = last ? nA : cA + (size_t)(t + 2) * kstep; const char* b2 = last ? nB : cB + (size_t)(t + 2) * kstep;
;             const char* a3 = a2 + kstep; const char* b3 = b2 + kstep;
;             if (last && has_next) S.a_ready(nxt);
;             if constexpr (SP2) {
;             PG8_LDB(B0, 0, 0); PG8_LDB(B1, 0, 1); PG8_SCHED; PG8_LDA(At, 0, 0); PG8_STAGE(PG8_SA(1, 1), a1 + hstepA, voffA);
;             PG8_WAIT_V(8); PG8_WAIT_L(0); PG8_BAR; PG8_MMA(0, 0, At, B0); PG8_MMA(0, 1, At, B1); PG8_BAR; PG8_SCHED;
;             PG8_LDA(At, 0, 1); PG8_STAGE(PG8_SB(0, 0), b2, voffB); PG8_STAGE(PG8_SB(0, 1), b2 + hstepB, voffB); PG8_STAGE(PG8_SA(0, 0), a2, voffA);
;             PG8_WAIT_V(8); PG8_WAIT_L(0); PG8_BAR; PG8_MMA(1, 0, At, B0); PG8_MMA(1, 1, At, B1); PG8_BAR; PG8_SCHED;
;             PG8_LDB(B0, 1, 0); PG8_LDB(B1, 1, 1); PG8_SCHED; PG8_LDA(At, 1, 0); PG8_STAGE(PG8_SA(0, 1), a2 + hstepA, voffA);
;             PG8_WAIT_V(8); PG8_WAIT_L(0); PG8_BAR; PG8_MMA(0, 0, At, B0); PG8_MMA(0, 1, At, B1); PG8_BAR; PG8_SCHED;
;             PG8_LDA(At, 1, 1); PG8_STAGE(PG8_SB(1, 0), b3, voffB); PG8_STAGE(PG8_SB(1, 1), b3 + hstepB, voffB); PG8_STAGE(PG8_SA(1, 0), a3, voffA);
;             PG8_WAIT_V(8); PG8_WAIT_L(0); PG8_BAR; PG8_MMA(1, 0, At, B0); PG8_MMA(1, 1, At, B1); PG8_BAR; PG8_SCHED;
.LBB0_448:
	s_add_u32 s16, s38, s14
	s_addc_u32 s17, s39, s15
	s_add_u32 s16, s16, 0x4e00100
	s_addc_u32 s17, s17, 0
	s_add_u32 s43, s40, s14
	s_addc_u32 s44, s41, s15
	s_add_i32 s45, 0, 0x10000
	v_add_u32_e32 v96, s45, v82
	ds_read_b128 v[84:87], v96
	ds_read_b128 v[88:91], v96 offset:1024
	ds_read_b128 v[92:95], v96 offset:2048
	ds_read_b128 v[96:99], v96 offset:3072
	s_cmpk_eq_i32 s14, 0x700
	s_cselect_b32 s19, s13, s17
	s_cselect_b32 s18, s12, s16
	s_cselect_b32 s17, s5, s44
	s_cselect_b32 s16, s4, s43
	v_lshl_add_u64 v[132:133], v[76:77], 0, s[14:15]
	s_add_i32 m0, s25, 0xc000
	ds_read_b128 v[100:103], v83
	ds_read_b128 v[104:107], v83 offset:1024
	ds_read_b128 v[108:111], v83 offset:2048
	ds_read_b128 v[112:115], v83 offset:3072
	ds_read_b128 v[116:119], v83 offset:4096
	ds_read_b128 v[120:123], v83 offset:5120
	ds_read_b128 v[124:127], v83 offset:6144
	ds_read_b128 v[128:131], v83 offset:7168
	global_load_lds_dwordx4 v[132:133], off
	v_lshl_add_u64 v[132:133], v[78:79], 0, s[14:15]
	s_add_i32 m0, s25, 0xe000
	s_nop 0
	global_load_lds_dwordx4 v[132:133], off
	s_waitcnt vmcnt(8) lgkmcnt(0)
	s_barrier
	s_setprio 1
	v_mfma_f32_16x16x32_bf16 v[62:65], v[84:87], v[100:103], v[62:65]
	v_mfma_f32_16x16x32_bf16 v[58:61], v[92:95], v[100:103], v[58:61]
	v_mfma_f32_16x16x32_bf16 v[54:57], v[84:87], v[108:111], v[54:57]
	v_mfma_f32_16x16x32_bf16 v[50:53], v[92:95], v[108:111], v[50:53]
	v_mfma_f32_16x16x32_bf16 v[46:49], v[84:87], v[116:119], v[46:49]
	v_mfma_f32_16x16x32_bf16 v[42:45], v[92:95], v[116:119], v[42:45]
	v_mfma_f32_16x16x32_bf16 v[38:41], v[84:87], v[124:127], v[38:41]
	v_mfma_f32_16x16x32_bf16 v[34:37], v[92:95], v[124:127], v[34:37]
	v_mfma_f32_16x16x32_bf16 v[62:65], v[88:91], v[104:107], v[62:65]
	v_mfma_f32_16x16x32_bf16 v[58:61], v[96:99], v[104:107], v[58:61]
	v_mfma_f32_16x16x32_bf16 v[54:57], v[88:91], v[112:115], v[54:57]
	v_mfma_f32_16x16x32_bf16 v[50:53], v[96:99], v[112:115], v[50:53]
	v_mfma_f32_16x16x32_bf16 v[46:49], v[88:91], v[120:123], v[46:49]
	v_mfma_f32_16x16x32_bf16 v[42:45], v[96:99], v[120:123], v[42:45]
	v_mfma_f32_16x16x32_bf16 v[38:41], v[88:91], v[128:131], v[38:41]
	v_mfma_f32_16x16x32_bf16 v[34:37], v[96:99], v[128:131], v[34:37]
	s_setprio 0
	s_setprio 1
	s_setprio 0
	s_barrier
	s_add_i32 s43, s45, s24
	v_lshl_add_u64 v[132:133], s[16:17], 0, v[72:73]
	s_mov_b32 m0, s43
	ds_read_b128 v[100:103], v83 offset:16384
	ds_read_b128 v[104:107], v83 offset:17408
	ds_read_b128 v[108:111], v83 offset:18432
	ds_read_b128 v[112:115], v83 offset:19456
	ds_read_b128 v[116:119], v83 offset:20480
	ds_read_b128 v[120:123], v83 offset:21504
	ds_read_b128 v[124:127], v83 offset:22528
	ds_read_b128 v[128:131], v83 offset:23552
	global_load_lds_dwordx4 v[132:133], off
	s_add_i32 m0, s43, 0x2000
	s_add_u32 s44, s16, 0x40000
	v_lshl_add_u64 v[134:135], s[16:17], 0, v[68:69]
	s_addc_u32 s45, s17, 0
	global_load_lds_dwordx4 v[134:135], off
	v_lshl_add_u64 v[136:137], s[44:45], 0, v[72:73]
	s_mov_b32 m0, s26
	v_lshl_add_u64 v[138:139], s[18:19], 0, v[70:71]
	global_load_lds_dwordx4 v[136:137], off
	v_lshl_add_u64 v[136:137], s[44:45], 0, v[68:69]
	s_mov_b32 m0, s27
	s_nop 0
	global_load_lds_dwordx4 v[136:137], off
	v_lshl_add_u64 v[136:137], s[18:19], 0, v[74:75]
	s_mov_b32 m0, s25
	s_nop 0
	global_load_lds_dwordx4 v[136:137], off
	s_mov_b32 m0, s28
	s_nop 0
	global_load_lds_dwordx4 v[138:139], off
	s_waitcnt vmcnt(8) lgkmcnt(0)
	s_barrier
	s_setprio 1
	v_mfma_f32_16x16x32_bf16 v[30:33], v[84:87], v[100:103], v[30:33]
	v_mfma_f32_16x16x32_bf16 v[26:29], v[92:95], v[100:103], v[26:29]
	v_mfma_f32_16x16x32_bf16 v[22:25], v[84:87], v[108:111], v[22:25]
	v_mfma_f32_16x16x32_bf16 v[18:21], v[92:95], v[108:111], v[18:21]
	v_mfma_f32_16x16x32_bf16 v[14:17], v[84:87], v[116:119], v[14:17]
	v_mfma_f32_16x16x32_bf16 v[10:13], v[92:95], v[116:119], v[10:13]
	v_mfma_f32_16x16x32_bf16 v[6:9], v[84:87], v[124:127], v[6:9]
	v_mfma_f32_16x16x32_bf16 v[2:5], v[92:95], v[124:127], v[2:5]
	v_mfma_f32_16x16x32_bf16 v[30:33], v[88:91], v[104:107], v[30:33]
	v_mfma_f32_16x16x32_bf16 v[26:29], v[96:99], v[104:107], v[26:29]
	v_mfma_f32_16x16x32_bf16 v[22:25], v[88:91], v[112:115], v[22:25]
	v_mfma_f32_16x16x32_bf16 v[18:21], v[96:99], v[112:115], v[18:21]
	v_mfma_f32_16x16x32_bf16 v[14:17], v[88:91], v[120:123], v[14:17]
	v_mfma_f32_16x16x32_bf16 v[10:13], v[96:99], v[120:123], v[10:13]
	v_mfma_f32_16x16x32_bf16 v[6:9], v[88:91], v[128:131], v[6:9]
	v_mfma_f32_16x16x32_bf16 v[2:5], v[96:99], v[128:131], v[2:5]
	s_setprio 0
	s_setprio 1
	s_setprio 0
	s_barrier
; #define PG8_STAGE(bufoff, gbase, voff) do { _Pragma("unroll") for (int _i = 0; _i < 2; ++_i) \
;         __builtin_amdgcn_global_load_lds((const unsigned*)((const char*)(gbase) + (voff)[_i]), (PG8_LAS unsigned*)(lds + (bufoff) + ldsw + _i * 8192), 16, 0, 0); } while (0)
; #define PG8_LDA(dst, b, h) do { _Pragma("unroll") for (int m = 0; m < 4; ++m) _Pragma("unroll") for (int k = 0; k < 2; ++k) dst[m][k] = *(const PG8_LAS bf16x8*)(lds + PG8_SA(b, h) + aoff + m * 2048 + k * 1024); } while (0)
; #define PG8_LDB(dst, b, h) do { _Pragma("unroll") for (int n = 0; n < 2; ++n) _Pragma("unroll") for (int k = 0; k < 2; ++k) dst[n][k] = *(const PG8_LAS bf16x8*)(lds + PG8_SB(b, h) + boff + n * 2048 + k * 1024); } while (0)
; #define PG8_MMA(ai, bj, At, Bt) do { __builtin_amdgcn_s_setprio(1); _Pragma("unroll") for (int m = 0; m < 4; ++m) _Pragma("unroll") for (int n = 0; n < 2; ++n) _Pragma("unroll") for (int k = 0; k < 2; ++k) \
;         acc[ai][bj][m][n] = __builtin_amdgcn_mfma_f32_16x16x32_bf16(Bt[n][k], At[m][k], acc[ai][bj][m][n], 0, 0, 0); __builtin_amdgcn_s_setprio(0); } while (0)
; template <class Epi, class Sched, bool ALIGN_EPI = false, bool SP2 = false>
; __device__ __forceinline__ void gemm_phase(PG8_LAS unsigned char* lds, const Gemm g, const Sched& S, const Epi& E) {
;     ...
;         for (int t = 0; t < nt; t += 2) {
;     ...
;             PG8_LDB(B0, 0, 0); PG8_LDB(B1, 0, 1); PG8_SCHED; PG8_LDA(At, 0, 0); PG8_STAGE(PG8_SA(1, 1), a1 + hstepA, voffA);
;             PG8_WAIT_V(8); PG8_WAIT_L(0); PG8_BAR; PG8_MMA(0, 0, At, B0); PG8_MMA(0, 1, At, B1); PG8_BAR; PG8_SCHED;
;             PG8_LDA(At, 0, 1); PG8_STAGE(PG8_SB(0, 0), b2, voffB); PG8_STAGE(PG8_SB(0, 1), b2 + hstepB, voffB); PG8_STAGE(PG8_SA(0, 0), a2, voffA);
;             PG8_WAIT_V(8); PG8_WAIT_L(0); PG8_BAR; PG8_MMA(1, 0, At, B0); PG8_MMA(1, 1, At, B1); PG8_BAR; PG8_SCHED;
;             PG8_LDB(B0, 1, 0); PG8_LDB(B1, 1, 1); PG8_SCHED; PG8_LDA(At, 1, 0); PG8_STAGE(PG8_SA(0, 1), a2 + hstepA, voffA);
;             PG8_WAIT_V(8); PG8_WAIT_L(0); PG8_BAR; PG8_MMA(0, 0, At, B0); PG8_MMA(0, 1, At, B1); PG8_BAR; PG8_SCHED;
;             PG8_LDA(At, 1, 1); PG8_STAGE(PG8_SB(1, 0), b3, voffB); PG8_STAGE(PG8_SB(1, 1), b3 + hstepB, voffB); PG8_STAGE(PG8_SA(1, 0), a3, voffA);
;             PG8_WAIT_V(8); PG8_WAIT_L(0); PG8_BAR; PG8_MMA(1, 0, At, B0); PG8_MMA(1, 1, At, B1); PG8_BAR; PG8_SCHED;
	s_add_i32 s43, 0, 0x18000
	v_add_u32_e32 v96, s43, v82
	ds_read_b128 v[84:87], v96
	ds_read_b128 v[88:91], v96 offset:1024
	ds_read_b128 v[92:95], v96 offset:2048
	ds_read_b128 v[96:99], v96 offset:3072
	s_add_u32 s18, s18, 0x40000
	s_addc_u32 s19, s19, 0
	s_mov_b32 m0, s29
	v_lshl_add_u64 v[140:141], s[18:19], 0, v[74:75]
	ds_read_b128 v[100:103], v83 offset:32768
	ds_read_b128 v[104:107], v83 offset:33792
	ds_read_b128 v[108:111], v83 offset:34816
	ds_read_b128 v[112:115], v83 offset:35840
	ds_read_b128 v[116:119], v83 offset:36864
	ds_read_b128 v[120:123], v83 offset:37888
	ds_read_b128 v[124:127], v83 offset:38912
	ds_read_b128 v[128:131], v83 offset:39936
	global_load_lds_dwordx4 v[140:141], off
	v_lshl_add_u64 v[140:141], s[18:19], 0, v[70:71]
	s_mov_b32 m0, s30
	s_nop 0
	global_load_lds_dwordx4 v[140:141], off
	s_waitcnt vmcnt(8) lgkmcnt(0)
	s_barrier
	s_setprio 1
	v_mfma_f32_16x16x32_bf16 v[62:65], v[84:87], v[100:103], v[62:65]
	v_mfma_f32_16x16x32_bf16 v[58:61], v[92:95], v[100:103], v[58:61]
	v_mfma_f32_16x16x32_bf16 v[54:57], v[84:87], v[108:111], v[54:57]
	v_mfma_f32_16x16x32_bf16 v[50:53], v[92:95], v[108:111], v[50:53]
	v_mfma_f32_16x16x32_bf16 v[46:49], v[84:87], v[116:119], v[46:49]
	v_mfma_f32_16x16x32_bf16 v[42:45], v[92:95], v[116:119], v[42:45]
	v_mfma_f32_16x16x32_bf16 v[38:41], v[84:87], v[124:127], v[38:41]
	v_mfma_f32_16x16x32_bf16 v[34:37], v[92:95], v[124:127], v[34:37]
	v_mfma_f32_16x16x32_bf16 v[62:65], v[88:91], v[104:107], v[62:65]
	v_mfma_f32_16x16x32_bf16 v[58:61], v[96:99], v[104:107], v[58:61]
	v_mfma_f32_16x16x32_bf16 v[54:57], v[88:91], v[112:115], v[54:57]
	v_mfma_f32_16x16x32_bf16 v[50:53], v[96:99], v[112:115], v[50:53]
	v_mfma_f32_16x16x32_bf16 v[46:49], v[88:91], v[120:123], v[46:49]
	v_mfma_f32_16x16x32_bf16 v[42:45], v[96:99], v[120:123], v[42:45]
	v_mfma_f32_16x16x32_bf16 v[38:41], v[88:91], v[128:131], v[38:41]
	v_mfma_f32_16x16x32_bf16 v[34:37], v[96:99], v[128:131], v[34:37]
	s_setprio 0
	s_setprio 1
	s_setprio 0
	s_barrier
	s_add_i32 s18, s43, s24
	v_lshl_add_u64 v[132:133], v[132:133], 0, s[96:97]
	s_mov_b32 m0, s18
	ds_read_b128 v[100:103], v83 offset:49152
	ds_read_b128 v[104:107], v83 offset:50176
	ds_read_b128 v[108:111], v83 offset:51200
	ds_read_b128 v[112:115], v83 offset:52224
	ds_read_b128 v[116:119], v83 offset:53248
	ds_read_b128 v[120:123], v83 offset:54272
	ds_read_b128 v[124:127], v83 offset:55296
	ds_read_b128 v[128:131], v83 offset:56320
	global_load_lds_dwordx4 v[132:133], off
	s_add_i32 m0, s18, 0x2000
	s_add_u32 s16, s16, 0x40080
	v_lshl_add_u64 v[132:133], v[134:135], 0, s[96:97]
	s_addc_u32 s17, s17, 0
	global_load_lds_dwordx4 v[132:133], off
	v_lshl_add_u64 v[132:133], s[16:17], 0, v[72:73]
	s_mov_b32 m0, s36
	s_nop 0
	global_load_lds_dwordx4 v[132:133], off
	v_lshl_add_u64 v[132:133], s[16:17], 0, v[68:69]
	s_mov_b32 m0, s37
	s_nop 0
	global_load_lds_dwordx4 v[132:133], off
	v_lshl_add_u64 v[132:133], v[136:137], 0, s[96:97]
	s_mov_b32 m0, s34
	s_nop 0
	global_load_lds_dwordx4 v[132:133], off
	v_lshl_add_u64 v[132:133], v[138:139], 0, s[96:97]
	s_mov_b32 m0, s35
	s_nop 0
	global_load_lds_dwordx4 v[132:133], off
	s_waitcnt vmcnt(8) lgkmcnt(0)
	s_barrier
	s_setprio 1
	v_mfma_f32_16x16x32_bf16 v[30:33], v[84:87], v[100:103], v[30:33]
	v_mfma_f32_16x16x32_bf16 v[26:29], v[92:95], v[100:103], v[26:29]
	v_mfma_f32_16x16x32_bf16 v[22:25], v[84:87], v[108:111], v[22:25]
	v_mfma_f32_16x16x32_bf16 v[18:21], v[92:95], v[108:111], v[18:21]
	v_mfma_f32_16x16x32_bf16 v[14:17], v[84:87], v[116:119], v[14:17]
	v_mfma_f32_16x16x32_bf16 v[10:13], v[92:95], v[116:119], v[10:13]
	v_mfma_f32_16x16x32_bf16 v[6:9], v[84:87], v[124:127], v[6:9]
	v_mfma_f32_16x16x32_bf16 v[2:5], v[92:95], v[124:127], v[2:5]
	v_mfma_f32_16x16x32_bf16 v[30:33], v[88:91], v[104:107], v[30:33]
	v_mfma_f32_16x16x32_bf16 v[26:29], v[96:99], v[104:107], v[26:29]
	v_mfma_f32_16x16x32_bf16 v[22:25], v[88:91], v[112:115], v[22:25]
	v_mfma_f32_16x16x32_bf16 v[18:21], v[96:99], v[112:115], v[18:21]
	v_mfma_f32_16x16x32_bf16 v[14:17], v[88:91], v[120:123], v[14:17]
	v_mfma_f32_16x16x32_bf16 v[10:13], v[96:99], v[120:123], v[10:13]
	v_mfma_f32_16x16x32_bf16 v[6:9], v[88:91], v[128:131], v[6:9]
	v_mfma_f32_16x16x32_bf16 v[2:5], v[96:99], v[128:131], v[2:5]
	s_setprio 0
	s_setprio 1
	s_setprio 0
	s_barrier
	s_add_i32 s42, s42, 2
	s_add_u32 s14, s14, 0x100
	s_addc_u32 s15, s15, 0
	s_cmp_gt_u32 s42, 13
	s_cbranch_scc0 .LBB0_448
	s_cmpk_lt_u32 s23, 0x100
	s_cbranch_scc0 .LBB0_451
	s_barrier

; #define PG8_STAGE(bufoff, gbase, voff) do { _Pragma("unroll") for (int _i = 0; _i < 2; ++_i) \
;         __builtin_amdgcn_global_load_lds((const unsigned*)((const char*)(gbase) + (voff)[_i]), (PG8_LAS unsigned*)(lds + (bufoff) + ldsw + _i * 8192), 16, 0, 0); } while (0)
; #define PG8_LDA(dst, b, h) do { _Pragma("unroll") for (int m = 0; m < 4; ++m) _Pragma("unroll") for (int k = 0; k < 2; ++k) dst[m][k] = *(const PG8_LAS bf16x8*)(lds + PG8_SA(b, h) + aoff + m * 2048 + k * 1024); } while (0)
; #define PG8_LDB(dst, b, h) do { _Pragma("unroll") for (int n = 0; n < 2; ++n) _Pragma("unroll") for (int k = 0; k < 2; ++k) dst[n][k] = *(const PG8_LAS bf16x8*)(lds + PG8_SB(b, h) + boff + n * 2048 + k * 1024); } while (0)
; #define PG8_BAR __builtin_amdgcn_s_barrier()
; template <class Epi, class Sched, bool ALIGN_EPI = false, bool SP2 = false>
; __device__ __forceinline__ void gemm_phase(PG8_LAS unsigned char* lds, const Gemm g, const Sched& S, const Epi& E) {
;     ...
;             const bool last = (t == nt - 2);
;             const char* a1 = cA + (size_t)(t + 1) * kstep;
;             const char* a2 = last ? nA : cA + (size_t)(t + 2) * kstep; const char* b2 = last ? nB : cB + (size_t)(t + 2) * kstep;
;             const char* a3 = a2 + kstep; const char* b3 = b2 + kstep;
;             if (last && has_next) S.a_ready(nxt);
;             if constexpr (SP2) {
;             PG8_LDB(B0, 0, 0); PG8_LDB(B1, 0, 1); PG8_SCHED; PG8_LDA(At, 0, 0); PG8_STAGE(PG8_SA(1, 1), a1 + hstepA, voffA);
;             PG8_WAIT_V(8); PG8_WAIT_L(0); PG8_BAR; PG8_MMA(0, 0, At, B0); PG8_MMA(0, 1, At, B1); PG8_BAR; PG8_SCHED;
;             PG8_LDA(At, 0, 1); PG8_STAGE(PG8_SB(0, 0), b2, voffB); PG8_STAGE(PG8_SB(0, 1), b2 + hstepB, voffB); PG8_STAGE(PG8_SA(0, 0), a2, voffA);
;             PG8_WAIT_V(8); PG8_WAIT_L(0); PG8_BAR; PG8_MMA(1, 0, At, B0); PG8_MMA(1, 1, At, B1); PG8_BAR; PG8_SCHED;
;             PG8_LDB(B0, 1, 0); PG8_LDB(B1, 1, 1); PG8_SCHED; PG8_LDA(At, 1, 0); PG8_STAGE(PG8_SA(0, 1), a2 + hstepA, voffA);
;             PG8_WAIT_V(8); PG8_WAIT_L(0); PG8_BAR; PG8_MMA(0, 0, At, B0); PG8_MMA(0, 1, At, B1); PG8_BAR; PG8_SCHED;
;             PG8_LDA(At, 1, 1); PG8_STAGE(PG8_SB(1, 0), b3, voffB); PG8_STAGE(PG8_SB(1, 1), b3 + hstepB, voffB); PG8_STAGE(PG8_SA(1, 0), a3, voffA);
;             PG8_WAIT_V(8); PG8_WAIT_L(0); PG8_BAR; PG8_MMA(1, 0, At, B0); PG8_MMA(1, 1, At, B1); PG8_BAR; PG8_SCHED;
.LBB0_530:
	s_add_u32 s12, s1, s8
	s_addc_u32 s13, s28, s9
	s_add_u32 s12, s12, 0xfe00100
	s_addc_u32 s13, s13, 0
	s_add_u32 s34, s29, s8
	s_addc_u32 s35, s30, s9
	s_add_i32 s36, 0, 0x10000
	s_cmpk_eq_i32 s8, 0x700
	s_cselect_b32 s15, s7, s13
	s_cselect_b32 s14, s6, s12
	v_add_u32_e32 v145, s36, v143
	s_cselect_b32 s13, s5, s35
	s_cselect_b32 s12, s4, s34
	s_add_i32 s37, 0, 0x14000
	ds_read_b128 v[146:149], v145
	ds_read_b128 v[150:153], v145 offset:1024
	ds_read_b128 v[154:157], v145 offset:2048
	ds_read_b128 v[158:161], v145 offset:3072
	v_add_u32_e32 v145, s37, v143
	ds_read_b128 v[162:165], v145
	ds_read_b128 v[166:169], v145 offset:1024
	ds_read_b128 v[170:173], v145 offset:2048
	ds_read_b128 v[174:177], v145 offset:3072
	v_lshl_add_u64 v[186:187], v[138:139], 0, s[8:9]
	s_add_i32 m0, s21, 0xc000
	ds_read_b128 v[178:181], v144
	ds_read_b128 v[182:185], v144 offset:1024
	ds_read_b128 v[202:205], v144 offset:2048
	ds_read_b128 v[206:209], v144 offset:3072
	ds_read_b128 v[210:213], v144 offset:4096
	ds_read_b128 v[232:235], v144 offset:5120
	ds_read_b128 v[236:239], v144 offset:6144
	ds_read_b128 v[240:243], v144 offset:7168
	global_load_lds_dwordx4 v[186:187], off
	v_lshl_add_u64 v[186:187], v[140:141], 0, s[8:9]
	s_add_i32 m0, s21, 0xe000
	s_nop 0
	global_load_lds_dwordx4 v[186:187], off
	s_waitcnt vmcnt(8) lgkmcnt(0)
	s_barrier
	s_setprio 1
	v_mfma_f32_16x16x32_bf16 v[126:129], v[146:149], v[178:181], v[126:129]
	v_mfma_f32_16x16x32_bf16 v[122:125], v[154:157], v[178:181], v[122:125]
	v_mfma_f32_16x16x32_bf16 v[118:121], v[146:149], v[202:205], v[118:121]
	v_mfma_f32_16x16x32_bf16 v[114:117], v[154:157], v[202:205], v[114:117]
	v_mfma_f32_16x16x32_bf16 v[110:113], v[146:149], v[210:213], v[110:113]
	v_mfma_f32_16x16x32_bf16 v[106:109], v[154:157], v[210:213], v[106:109]
	v_mfma_f32_16x16x32_bf16 v[102:105], v[146:149], v[236:239], v[102:105]
	v_mfma_f32_16x16x32_bf16 v[98:101], v[154:157], v[236:239], v[98:101]
	v_mfma_f32_16x16x32_bf16 v[126:129], v[150:153], v[182:185], v[126:129]
	v_mfma_f32_16x16x32_bf16 v[122:125], v[158:161], v[182:185], v[122:125]
	v_mfma_f32_16x16x32_bf16 v[118:121], v[150:153], v[206:209], v[118:121]
	v_mfma_f32_16x16x32_bf16 v[114:117], v[158:161], v[206:209], v[114:117]
	v_mfma_f32_16x16x32_bf16 v[110:113], v[150:153], v[232:235], v[110:113]
	v_mfma_f32_16x16x32_bf16 v[106:109], v[158:161], v[232:235], v[106:109]
	v_mfma_f32_16x16x32_bf16 v[102:105], v[150:153], v[240:243], v[102:105]
	v_mfma_f32_16x16x32_bf16 v[98:101], v[158:161], v[240:243], v[98:101]
	s_setprio 0
	s_setprio 1
	v_mfma_f32_16x16x32_bf16 v[94:97], v[162:165], v[178:181], v[94:97]
	v_mfma_f32_16x16x32_bf16 v[86:89], v[170:173], v[178:181], v[86:89]
	v_mfma_f32_16x16x32_bf16 v[78:81], v[162:165], v[202:205], v[78:81]
	v_mfma_f32_16x16x32_bf16 v[74:77], v[170:173], v[202:205], v[74:77]
	v_mfma_f32_16x16x32_bf16 v[70:73], v[162:165], v[210:213], v[70:73]
	v_mfma_f32_16x16x32_bf16 v[62:65], v[170:173], v[210:213], v[62:65]
	v_mfma_f32_16x16x32_bf16 v[54:57], v[162:165], v[236:239], v[54:57]
	v_mfma_f32_16x16x32_bf16 v[50:53], v[170:173], v[236:239], v[50:53]
	v_mfma_f32_16x16x32_bf16 v[94:97], v[166:169], v[182:185], v[94:97]
	v_mfma_f32_16x16x32_bf16 v[86:89], v[174:177], v[182:185], v[86:89]
	v_mfma_f32_16x16x32_bf16 v[78:81], v[166:169], v[206:209], v[78:81]
	v_mfma_f32_16x16x32_bf16 v[74:77], v[174:177], v[206:209], v[74:77]
	v_mfma_f32_16x16x32_bf16 v[70:73], v[166:169], v[232:235], v[70:73]
	v_mfma_f32_16x16x32_bf16 v[62:65], v[174:177], v[232:235], v[62:65]
	v_mfma_f32_16x16x32_bf16 v[54:57], v[166:169], v[240:243], v[54:57]
	v_mfma_f32_16x16x32_bf16 v[50:53], v[174:177], v[240:243], v[50:53]
	s_setprio 0
	s_barrier
	s_add_i32 s34, s36, s20
	s_mov_b32 m0, s34
	ds_read_b128 v[178:181], v144 offset:16384
	ds_read_b128 v[182:185], v144 offset:17408
	ds_read_b128 v[202:205], v144 offset:18432
	ds_read_b128 v[206:209], v144 offset:19456
	ds_read_b128 v[210:213], v144 offset:20480
	ds_read_b128 v[232:235], v144 offset:21504
	ds_read_b128 v[236:239], v144 offset:22528
	ds_read_b128 v[240:243], v144 offset:23552
	s_add_u32 s60, s12, 0x80
	s_addc_u32 s61, s13, 0
	s_add_u32 s62, s14, 0x80
	s_addc_u32 s63, s15, 0
	global_load_lds_dwordx4 v134, s[12:13]
	s_add_i32 m0, s34, 0x2000
	s_add_u32 s34, s12, 0x80000
	s_addc_u32 s35, s13, 0
	s_add_i32 s36, s37, s20
	global_load_lds_dwordx4 v130, s[12:13]
	s_mov_b32 m0, s36
	s_nop 0
	global_load_lds_dwordx4 v134, s[34:35]
	s_add_i32 m0, s36, 0x2000
	s_nop 0
	global_load_lds_dwordx4 v130, s[34:35]
	s_mov_b32 m0, s21
	s_nop 0
	global_load_lds_dwordx4 v136, s[14:15]
	s_mov_b32 m0, s22
	s_nop 0
	global_load_lds_dwordx4 v132, s[14:15]
	s_waitcnt vmcnt(8) lgkmcnt(0)
	s_barrier
; #define PG8_STAGE(bufoff, gbase, voff) do { _Pragma("unroll") for (int _i = 0; _i < 2; ++_i) \
;         __builtin_amdgcn_global_load_lds((const unsigned*)((const char*)(gbase) + (voff)[_i]), (PG8_LAS unsigned*)(lds + (bufoff) + ldsw + _i * 8192), 16, 0, 0); } while (0)
; #define PG8_LDA(dst, b, h) do { _Pragma("unroll") for (int m = 0; m < 4; ++m) _Pragma("unroll") for (int k = 0; k < 2; ++k) dst[m][k] = *(const PG8_LAS bf16x8*)(lds + PG8_SA(b, h) + aoff + m * 2048 + k * 1024); } while (0)
; #define PG8_LDB(dst, b, h) do { _Pragma("unroll") for (int n = 0; n < 2; ++n) _Pragma("unroll") for (int k = 0; k < 2; ++k) dst[n][k] = *(const PG8_LAS bf16x8*)(lds + PG8_SB(b, h) + boff + n * 2048 + k * 1024); } while (0)
; #define PG8_MMA(ai, bj, At, Bt) do { __builtin_amdgcn_s_setprio(1); _Pragma("unroll") for (int m = 0; m < 4; ++m) _Pragma("unroll") for (int n = 0; n < 2; ++n) _Pragma("unroll") for (int k = 0; k < 2; ++k) \
;         acc[ai][bj][m][n] = __builtin_amdgcn_mfma_f32_16x16x32_bf16(Bt[n][k], At[m][k], acc[ai][bj][m][n], 0, 0, 0); __builtin_amdgcn_s_setprio(0); } while (0)
; #define PG8_WAIT_V(n) asm volatile("s_waitcnt vmcnt(" #n ")" ::: "memory")
; template <class Epi, class Sched, bool ALIGN_EPI = false, bool SP2 = false>
; __device__ __forceinline__ void gemm_phase(PG8_LAS unsigned char* lds, const Gemm g, const Sched& S, const Epi& E) {
;     ...
;             PG8_LDB(B0, 0, 0); PG8_LDB(B1, 0, 1); PG8_SCHED; PG8_LDA(At, 0, 0); PG8_STAGE(PG8_SA(1, 1), a1 + hstepA, voffA);
;             PG8_WAIT_V(8); PG8_WAIT_L(0); PG8_BAR; PG8_MMA(0, 0, At, B0); PG8_MMA(0, 1, At, B1); PG8_BAR; PG8_SCHED;
;             PG8_LDA(At, 0, 1); PG8_STAGE(PG8_SB(0, 0), b2, voffB); PG8_STAGE(PG8_SB(0, 1), b2 + hstepB, voffB); PG8_STAGE(PG8_SA(0, 0), a2, voffA);
;             PG8_WAIT_V(8); PG8_WAIT_L(0); PG8_BAR; PG8_MMA(1, 0, At, B0); PG8_MMA(1, 1, At, B1); PG8_BAR; PG8_SCHED;
;             PG8_LDB(B0, 1, 0); PG8_LDB(B1, 1, 1); PG8_SCHED; PG8_LDA(At, 1, 0); PG8_STAGE(PG8_SA(0, 1), a2 + hstepA, voffA);
;             PG8_WAIT_V(8); PG8_WAIT_L(0); PG8_BAR; PG8_MMA(0, 0, At, B0); PG8_MMA(0, 1, At, B1); PG8_BAR; PG8_SCHED;
;             PG8_LDA(At, 1, 1); PG8_STAGE(PG8_SB(1, 0), b3, voffB); PG8_STAGE(PG8_SB(1, 1), b3 + hstepB, voffB); PG8_STAGE(PG8_SA(1, 0), a3, voffA);
;             PG8_WAIT_V(8); PG8_WAIT_L(0); PG8_BAR; PG8_MMA(1, 0, At, B0); PG8_MMA(1, 1, At, B1); PG8_BAR; PG8_SCHED;
	s_setprio 1
	v_mfma_f32_16x16x32_bf16 v[90:93], v[146:149], v[178:181], v[90:93]
	v_mfma_f32_16x16x32_bf16 v[82:85], v[154:157], v[178:181], v[82:85]
	v_mfma_f32_16x16x32_bf16 v[66:69], v[146:149], v[202:205], v[66:69]
	v_mfma_f32_16x16x32_bf16 v[58:61], v[154:157], v[202:205], v[58:61]
	v_mfma_f32_16x16x32_bf16 v[46:49], v[146:149], v[210:213], v[46:49]
	v_mfma_f32_16x16x32_bf16 v[42:45], v[154:157], v[210:213], v[42:45]
	v_mfma_f32_16x16x32_bf16 v[38:41], v[146:149], v[236:239], v[38:41]
	v_mfma_f32_16x16x32_bf16 v[34:37], v[154:157], v[236:239], v[34:37]
	v_mfma_f32_16x16x32_bf16 v[90:93], v[150:153], v[182:185], v[90:93]
	v_mfma_f32_16x16x32_bf16 v[82:85], v[158:161], v[182:185], v[82:85]
	v_mfma_f32_16x16x32_bf16 v[66:69], v[150:153], v[206:209], v[66:69]
	v_mfma_f32_16x16x32_bf16 v[58:61], v[158:161], v[206:209], v[58:61]
	v_mfma_f32_16x16x32_bf16 v[46:49], v[150:153], v[232:235], v[46:49]
	v_mfma_f32_16x16x32_bf16 v[42:45], v[158:161], v[232:235], v[42:45]
	v_mfma_f32_16x16x32_bf16 v[38:41], v[150:153], v[240:243], v[38:41]
	v_mfma_f32_16x16x32_bf16 v[34:37], v[158:161], v[240:243], v[34:37]
	s_setprio 0
	s_setprio 1
	v_mfma_f32_16x16x32_bf16 v[30:33], v[162:165], v[178:181], v[30:33]
	v_mfma_f32_16x16x32_bf16 v[26:29], v[170:173], v[178:181], v[26:29]
	v_mfma_f32_16x16x32_bf16 v[22:25], v[162:165], v[202:205], v[22:25]
	v_mfma_f32_16x16x32_bf16 v[18:21], v[170:173], v[202:205], v[18:21]
	v_mfma_f32_16x16x32_bf16 v[14:17], v[162:165], v[210:213], v[14:17]
	v_mfma_f32_16x16x32_bf16 v[10:13], v[170:173], v[210:213], v[10:13]
	v_mfma_f32_16x16x32_bf16 v[6:9], v[162:165], v[236:239], v[6:9]
	v_mfma_f32_16x16x32_bf16 v[2:5], v[170:173], v[236:239], v[2:5]
	v_mfma_f32_16x16x32_bf16 v[30:33], v[166:169], v[182:185], v[30:33]
	v_mfma_f32_16x16x32_bf16 v[26:29], v[174:177], v[182:185], v[26:29]
	v_mfma_f32_16x16x32_bf16 v[22:25], v[166:169], v[206:209], v[22:25]
	v_mfma_f32_16x16x32_bf16 v[18:21], v[174:177], v[206:209], v[18:21]
	v_mfma_f32_16x16x32_bf16 v[14:17], v[166:169], v[232:235], v[14:17]
	v_mfma_f32_16x16x32_bf16 v[10:13], v[174:177], v[232:235], v[10:13]
	v_mfma_f32_16x16x32_bf16 v[6:9], v[166:169], v[240:243], v[6:9]
	v_mfma_f32_16x16x32_bf16 v[2:5], v[174:177], v[240:243], v[2:5]
	s_setprio 0
	s_barrier
	s_add_i32 s34, 0, 0x18000
	v_add_u32_e32 v145, s34, v143
	s_add_i32 s35, 0, 0x1c000
	ds_read_b128 v[146:149], v145
	ds_read_b128 v[150:153], v145 offset:1024
	ds_read_b128 v[154:157], v145 offset:2048
	ds_read_b128 v[158:161], v145 offset:3072
	v_add_u32_e32 v145, s35, v143
	ds_read_b128 v[162:165], v145
	ds_read_b128 v[166:169], v145 offset:1024
	ds_read_b128 v[170:173], v145 offset:2048
	ds_read_b128 v[174:177], v145 offset:3072
	s_add_u32 s14, s14, 0x40000
	s_addc_u32 s15, s15, 0
	s_mov_b32 m0, s23
	ds_read_b128 v[178:181], v144 offset:32768
	ds_read_b128 v[182:185], v144 offset:33792
	ds_read_b128 v[202:205], v144 offset:34816
	ds_read_b128 v[206:209], v144 offset:35840
	ds_read_b128 v[210:213], v144 offset:36864
	ds_read_b128 v[232:235], v144 offset:37888
	ds_read_b128 v[236:239], v144 offset:38912
	ds_read_b128 v[240:243], v144 offset:39936
	global_load_lds_dwordx4 v136, s[14:15]
	s_mov_b32 m0, s24
	s_nop 0
	global_load_lds_dwordx4 v132, s[14:15]
	s_waitcnt vmcnt(8) lgkmcnt(0)
	s_barrier
	s_setprio 1
	v_mfma_f32_16x16x32_bf16 v[126:129], v[146:149], v[178:181], v[126:129]
	v_mfma_f32_16x16x32_bf16 v[122:125], v[154:157], v[178:181], v[122:125]
	v_mfma_f32_16x16x32_bf16 v[118:121], v[146:149], v[202:205], v[118:121]
	v_mfma_f32_16x16x32_bf16 v[114:117], v[154:157], v[202:205], v[114:117]
	v_mfma_f32_16x16x32_bf16 v[110:113], v[146:149], v[210:213], v[110:113]
	v_mfma_f32_16x16x32_bf16 v[106:109], v[154:157], v[210:213], v[106:109]
	v_mfma_f32_16x16x32_bf16 v[102:105], v[146:149], v[236:239], v[102:105]
	v_mfma_f32_16x16x32_bf16 v[98:101], v[154:157], v[236:239], v[98:101]
	v_mfma_f32_16x16x32_bf16 v[126:129], v[150:153], v[182:185], v[126:129]
	v_mfma_f32_16x16x32_bf16 v[122:125], v[158:161], v[182:185], v[122:125]
	v_mfma_f32_16x16x32_bf16 v[118:121], v[150:153], v[206:209], v[118:121]
	v_mfma_f32_16x16x32_bf16 v[114:117], v[158:161], v[206:209], v[114:117]
	v_mfma_f32_16x16x32_bf16 v[110:113], v[150:153], v[232:235], v[110:113]
	v_mfma_f32_16x16x32_bf16 v[106:109], v[158:161], v[232:235], v[106:109]
	v_mfma_f32_16x16x32_bf16 v[102:105], v[150:153], v[240:243], v[102:105]
	v_mfma_f32_16x16x32_bf16 v[98:101], v[158:161], v[240:243], v[98:101]
	s_setprio 0
	s_setprio 1
	v_mfma_f32_16x16x32_bf16 v[94:97], v[162:165], v[178:181], v[94:97]
	v_mfma_f32_16x16x32_bf16 v[86:89], v[170:173], v[178:181], v[86:89]
	v_mfma_f32_16x16x32_bf16 v[78:81], v[162:165], v[202:205], v[78:81]
	v_mfma_f32_16x16x32_bf16 v[74:77], v[170:173], v[202:205], v[74:77]
	v_mfma_f32_16x16x32_bf16 v[70:73], v[162:165], v[210:213], v[70:73]
	v_mfma_f32_16x16x32_bf16 v[62:65], v[170:173], v[210:213], v[62:65]
	v_mfma_f32_16x16x32_bf16 v[54:57], v[162:165], v[236:239], v[54:57]
	v_mfma_f32_16x16x32_bf16 v[50:53], v[170:173], v[236:239], v[50:53]
	v_mfma_f32_16x16x32_bf16 v[94:97], v[166:169], v[182:185], v[94:97]
	v_mfma_f32_16x16x32_bf16 v[86:89], v[174:177], v[182:185], v[86:89]
	v_mfma_f32_16x16x32_bf16 v[78:81], v[166:169], v[206:209], v[78:81]
	v_mfma_f32_16x16x32_bf16 v[74:77], v[174:177], v[206:209], v[74:77]
	v_mfma_f32_16x16x32_bf16 v[70:73], v[166:169], v[232:235], v[70:73]
	v_mfma_f32_16x16x32_bf16 v[62:65], v[174:177], v[232:235], v[62:65]
	v_mfma_f32_16x16x32_bf16 v[54:57], v[166:169], v[240:243], v[54:57]
	v_mfma_f32_16x16x32_bf16 v[50:53], v[174:177], v[240:243], v[50:53]
	s_setprio 0
	s_barrier
; #define PG8_STAGE(bufoff, gbase, voff) do { _Pragma("unroll") for (int _i = 0; _i < 2; ++_i) \
;         __builtin_amdgcn_global_load_lds((const unsigned*)((const char*)(gbase) + (voff)[_i]), (PG8_LAS unsigned*)(lds + (bufoff) + ldsw + _i * 8192), 16, 0, 0); } while (0)
; #define PG8_LDA(dst, b, h) do { _Pragma("unroll") for (int m = 0; m < 4; ++m) _Pragma("unroll") for (int k = 0; k < 2; ++k) dst[m][k] = *(const PG8_LAS bf16x8*)(lds + PG8_SA(b, h) + aoff + m * 2048 + k * 1024); } while (0)
; #define PG8_LDB(dst, b, h) do { _Pragma("unroll") for (int n = 0; n < 2; ++n) _Pragma("unroll") for (int k = 0; k < 2; ++k) dst[n][k] = *(const PG8_LAS bf16x8*)(lds + PG8_SB(b, h) + boff + n * 2048 + k * 1024); } while (0)
; #define PG8_MMA(ai, bj, At, Bt) do { __builtin_amdgcn_s_setprio(1); _Pragma("unroll") for (int m = 0; m < 4; ++m) _Pragma("unroll") for (int n = 0; n < 2; ++n) _Pragma("unroll") for (int k = 0; k < 2; ++k) \
;         acc[ai][bj][m][n] = __builtin_amdgcn_mfma_f32_16x16x32_bf16(Bt[n][k], At[m][k], acc[ai][bj][m][n], 0, 0, 0); __builtin_amdgcn_s_setprio(0); } while (0)
; template <class Epi, class Sched, bool ALIGN_EPI = false, bool SP2 = false>
; __device__ __forceinline__ void gemm_phase(PG8_LAS unsigned char* lds, const Gemm g, const Sched& S, const Epi& E) {
;     ...
;         for (int t = 0; t < nt; t += 2) {
;     ...
;             PG8_LDB(B0, 0, 0); PG8_LDB(B1, 0, 1); PG8_SCHED; PG8_LDA(At, 0, 0); PG8_STAGE(PG8_SA(1, 1), a1 + hstepA, voffA);
;             PG8_WAIT_V(8); PG8_WAIT_L(0); PG8_BAR; PG8_MMA(0, 0, At, B0); PG8_MMA(0, 1, At, B1); PG8_BAR; PG8_SCHED;
;             PG8_LDA(At, 0, 1); PG8_STAGE(PG8_SB(0, 0), b2, voffB); PG8_STAGE(PG8_SB(0, 1), b2 + hstepB, voffB); PG8_STAGE(PG8_SA(0, 0), a2, voffA);
;             PG8_WAIT_V(8); PG8_WAIT_L(0); PG8_BAR; PG8_MMA(1, 0, At, B0); PG8_MMA(1, 1, At, B1); PG8_BAR; PG8_SCHED;
;             PG8_LDB(B0, 1, 0); PG8_LDB(B1, 1, 1); PG8_SCHED; PG8_LDA(At, 1, 0); PG8_STAGE(PG8_SA(0, 1), a2 + hstepA, voffA);
;             PG8_WAIT_V(8); PG8_WAIT_L(0); PG8_BAR; PG8_MMA(0, 0, At, B0); PG8_MMA(0, 1, At, B1); PG8_BAR; PG8_SCHED;
;             PG8_LDA(At, 1, 1); PG8_STAGE(PG8_SB(1, 0), b3, voffB); PG8_STAGE(PG8_SB(1, 1), b3 + hstepB, voffB); PG8_STAGE(PG8_SA(1, 0), a3, voffA);
;             PG8_WAIT_V(8); PG8_WAIT_L(0); PG8_BAR; PG8_MMA(1, 0, At, B0); PG8_MMA(1, 1, At, B1); PG8_BAR; PG8_SCHED;
	s_add_i32 s14, s34, s20
	s_mov_b32 m0, s14
	ds_read_b128 v[178:181], v144 offset:49152
	ds_read_b128 v[182:185], v144 offset:50176
	ds_read_b128 v[202:205], v144 offset:51200
	ds_read_b128 v[206:209], v144 offset:52224
	ds_read_b128 v[210:213], v144 offset:53248
	ds_read_b128 v[232:235], v144 offset:54272
	ds_read_b128 v[236:239], v144 offset:55296
	ds_read_b128 v[240:243], v144 offset:56320
	global_load_lds_dwordx4 v134, s[60:61]
	s_add_i32 m0, s14, 0x2000
	s_add_u32 s12, s12, 0x80080
	s_addc_u32 s13, s13, 0
	s_add_i32 s14, s35, s20
	global_load_lds_dwordx4 v130, s[60:61]
	s_mov_b32 m0, s14
	s_nop 0
	global_load_lds_dwordx4 v134, s[12:13]
	s_add_i32 m0, s14, 0x2000
	s_nop 0
	global_load_lds_dwordx4 v130, s[12:13]
	s_mov_b32 m0, s26
	s_nop 0
	global_load_lds_dwordx4 v136, s[62:63]
	s_mov_b32 m0, s27
	s_nop 0
	global_load_lds_dwordx4 v132, s[62:63]
	s_waitcnt vmcnt(8) lgkmcnt(0)
	s_barrier
	s_setprio 1
	v_mfma_f32_16x16x32_bf16 v[90:93], v[146:149], v[178:181], v[90:93]
	v_mfma_f32_16x16x32_bf16 v[82:85], v[154:157], v[178:181], v[82:85]
	v_mfma_f32_16x16x32_bf16 v[66:69], v[146:149], v[202:205], v[66:69]
	v_mfma_f32_16x16x32_bf16 v[58:61], v[154:157], v[202:205], v[58:61]
	v_mfma_f32_16x16x32_bf16 v[46:49], v[146:149], v[210:213], v[46:49]
	v_mfma_f32_16x16x32_bf16 v[42:45], v[154:157], v[210:213], v[42:45]
	v_mfma_f32_16x16x32_bf16 v[38:41], v[146:149], v[236:239], v[38:41]
	v_mfma_f32_16x16x32_bf16 v[34:37], v[154:157], v[236:239], v[34:37]
	v_mfma_f32_16x16x32_bf16 v[90:93], v[150:153], v[182:185], v[90:93]
	v_mfma_f32_16x16x32_bf16 v[82:85], v[158:161], v[182:185], v[82:85]
	v_mfma_f32_16x16x32_bf16 v[66:69], v[150:153], v[206:209], v[66:69]
	v_mfma_f32_16x16x32_bf16 v[58:61], v[158:161], v[206:209], v[58:61]
	v_mfma_f32_16x16x32_bf16 v[46:49], v[150:153], v[232:235], v[46:49]
	v_mfma_f32_16x16x32_bf16 v[42:45], v[158:161], v[232:235], v[42:45]
	v_mfma_f32_16x16x32_bf16 v[38:41], v[150:153], v[240:243], v[38:41]
	v_mfma_f32_16x16x32_bf16 v[34:37], v[158:161], v[240:243], v[34:37]
	s_setprio 0
	s_setprio 1
	v_mfma_f32_16x16x32_bf16 v[30:33], v[162:165], v[178:181], v[30:33]
	v_mfma_f32_16x16x32_bf16 v[26:29], v[170:173], v[178:181], v[26:29]
	v_mfma_f32_16x16x32_bf16 v[22:25], v[162:165], v[202:205], v[22:25]
	v_mfma_f32_16x16x32_bf16 v[18:21], v[170:173], v[202:205], v[18:21]
	v_mfma_f32_16x16x32_bf16 v[14:17], v[162:165], v[210:213], v[14:17]
	v_mfma_f32_16x16x32_bf16 v[10:13], v[170:173], v[210:213], v[10:13]
	v_mfma_f32_16x16x32_bf16 v[6:9], v[162:165], v[236:239], v[6:9]
	v_mfma_f32_16x16x32_bf16 v[2:5], v[170:173], v[236:239], v[2:5]
	v_mfma_f32_16x16x32_bf16 v[30:33], v[166:169], v[182:185], v[30:33]
	v_mfma_f32_16x16x32_bf16 v[26:29], v[174:177], v[182:185], v[26:29]
	v_mfma_f32_16x16x32_bf16 v[22:25], v[166:169], v[206:209], v[22:25]
	v_mfma_f32_16x16x32_bf16 v[18:21], v[174:177], v[206:209], v[18:21]
	v_mfma_f32_16x16x32_bf16 v[14:17], v[166:169], v[232:235], v[14:17]
	v_mfma_f32_16x16x32_bf16 v[10:13], v[174:177], v[232:235], v[10:13]
	v_mfma_f32_16x16x32_bf16 v[6:9], v[166:169], v[240:243], v[6:9]
	v_mfma_f32_16x16x32_bf16 v[2:5], v[174:177], v[240:243], v[2:5]
	s_setprio 0
	s_barrier
	s_add_i32 s31, s31, 2
	s_add_u32 s8, s8, 0x100
	s_addc_u32 s9, s9, 0
	s_cmp_gt_u32 s31, 13
	s_cbranch_scc0 .LBB0_530
	s_cmpk_lt_u32 s19, 0x100
	s_cbranch_scc0 .LBB0_533
	s_barrier

; template <class Epi, class Sched, bool ALIGN_EPI = false, bool SP2 = false>
; __device__ __forceinline__ void gemm_phase(PG8_LAS unsigned char* lds, const Gemm g, const Sched& S, const Epi& E) {
;     ...
;         PG8_STAGE(PG8_SB(0, 0), cB, voffB); PG8_STAGE(PG8_SB(0, 1), cB + hstepB, voffB); PG8_STAGE(PG8_SA(0, 0), cA, voffA); PG8_STAGE(PG8_SA(0, 1), cA + hstepA, voffA);
;         if (wr == 1) PG8_BAR;
;         PG8_WAIT_V(2); PG8_BAR;
;         PG8_STAGE(PG8_SB(1, 0), cB + kstep, voffB); PG8_STAGE(PG8_SA(1, 0), cA + kstep, voffA); PG8_STAGE(PG8_SB(1, 1), cB + hstepB + kstep, voffB);
;         PG8_WAIT_V(6); PG8_BAR;
;     } else {
;         PG8_STAGE(PG8_SB(0, 0), cB, voffB); PG8_STAGE(PG8_SA(0, 0), cA, voffA); PG8_STAGE(PG8_SB(0, 1), cB + hstepB, voffB); PG8_STAGE(PG8_SA(0, 1), cA + hstepA, voffA);
;         if (wr == 1) PG8_BAR;
;         PG8_WAIT_V(4); PG8_BAR;
;         PG8_STAGE(PG8_SB(1, 0), cB + kstep, voffB); PG8_STAGE(PG8_SA(1, 0), cA + kstep, voffA); PG8_STAGE(PG8_SB(1, 1), cB + hstepB + kstep, voffB);
;         PG8_WAIT_V(6); PG8_BAR;
;     }
;     for (;;) {
;         const bool has_next = S.next(ui + 1, nxt);
;         const char* nA = has_next ? (const char*)g.A + (size_t)nxt.pm * tstepA : cA; const char* nB = has_next ? (const char*)g.Bt + (size_t)nxt.pn * tstepB : cB;
;         for (int t = 0; t < nt; t += 2) {
;             const bool last = (t == nt - 2);
;             const char* a1 = cA + (size_t)(t + 1) * kstep;
;             const char* a2 = last ? nA : cA + (size_t)(t + 2) * kstep; const char* b2 = last ? nB : cB + (size_t)(t + 2) * kstep;
;             const char* a3 = a2 + kstep; const char* b3 = b2 + kstep;
;             if (last && has_next) S.a_ready(nxt);
;             if constexpr (SP2) {
;             PG8_LDB(B0, 0, 0); PG8_LDB(B1, 0, 1); PG8_SCHED; PG8_LDA(At, 0, 0); PG8_STAGE(PG8_SA(1, 1), a1 + hstepA, voffA);
;             PG8_WAIT_V(8); PG8_WAIT_L(0); PG8_BAR; PG8_MMA(0, 0, At, B0); PG8_MMA(0, 1, At, B1); PG8_BAR; PG8_SCHED;
;             PG8_LDA(At, 0, 1); PG8_STAGE(PG8_SB(0, 0), b2, voffB); PG8_STAGE(PG8_SB(0, 1), b2 + hstepB, voffB); PG8_STAGE(PG8_SA(0, 0), a2, voffA);
;             PG8_WAIT_V(8); PG8_WAIT_L(0); PG8_BAR; PG8_MMA(1, 0, At, B0); PG8_MMA(1, 1, At, B1); PG8_BAR; PG8_SCHED;
;             PG8_LDB(B0, 1, 0); PG8_LDB(B1, 1, 1); PG8_SCHED; PG8_LDA(At, 1, 0); PG8_STAGE(PG8_SA(0, 1), a2 + hstepA, voffA);
.LBB0_592:
	s_add_i32 s44, 0, 0x18000
	s_add_i32 s36, s44, s14
	s_and_b32 s28, s15, 3
	v_lshl_add_u64 v[26:27], v[4:5], 0, s[96:97]
	s_mov_b32 m0, s36
	s_add_i32 s38, s36, 0x2000
	s_lshl_b32 s15, s26, 13
	s_lshl_b32 s43, s28, 12
	s_waitcnt vmcnt(2)
	s_barrier
	global_load_lds_dwordx4 v[26:27], off
	v_lshl_add_u64 v[28:29], v[6:7], 0, s[96:97]
	s_mov_b32 m0, s38
	s_add_i32 s37, s27, 0x8000
	s_add_i32 s39, s27, 0xa000
	global_load_lds_dwordx4 v[28:29], off
	v_lshl_add_u64 v[24:25], v[18:19], 0, s[96:97]
	s_mov_b32 m0, s37
	s_add_u32 s16, s8, 0x10080
	global_load_lds_dwordx4 v[24:25], off
	v_lshl_add_u64 v[30:31], v[22:23], 0, s[96:97]
	s_mov_b32 m0, s39
	s_addc_u32 s17, s9, 0
	s_add_i32 s40, s27, 0x1c000
	global_load_lds_dwordx4 v[30:31], off
	v_lshl_add_u64 v[68:69], s[16:17], 0, v[32:33]
	s_mov_b32 m0, s40
	s_add_i32 s41, s27, 0x1e000
	global_load_lds_dwordx4 v[68:69], off
	v_lshl_add_u64 v[70:71], s[16:17], 0, v[20:21]
	s_mov_b32 m0, s41
	v_lshrrev_b32_e32 v35, 1, v34
	global_load_lds_dwordx4 v[70:71], off
	v_and_b32_e32 v72, 24, v35
	v_and_b32_e32 v67, 15, v34
	v_lshlrev_b32_e32 v35, 1, v72
	v_lshlrev_b32_e32 v34, 2, v34
	v_lshl_or_b32 v35, v67, 6, v35
	v_and_b32_e32 v34, 32, v34
	v_bitop3_b32 v36, v35, s15, v34 bitop3:0xde
	s_add_i32 s15, 0, 0x10000
	v_bitop3_b32 v34, v35, s43, v34 bitop3:0xde
	s_add_u32 s48, s12, 0x10080
	v_add_u32_e32 v157, s44, v34
	s_addc_u32 s49, s13, 0
	s_add_i32 s44, s15, s14
	s_add_i32 s46, s27, 0xc000
	s_add_i32 s45, s27, 0xe000
	s_add_i32 s43, s44, 0x2000
	v_add_u32_e32 v73, s15, v34
	s_add_u32 s50, s8, 0x10100
	s_waitcnt vmcnt(6)
	s_barrier
	v_add_u32_e32 v156, 0, v36
	s_addc_u32 s51, s9, 0
	ds_read_b128 v[34:37], v73
	ds_read_b128 v[38:41], v73 offset:1024
	ds_read_b128 v[42:45], v73 offset:2048
	ds_read_b128 v[46:49], v73 offset:3072
	s_add_u32 s16, s12, 0x10100
	s_addc_u32 s17, s13, 0
	s_add_u32 s14, s8, 0x10180
	s_addc_u32 s15, s9, 0
	s_add_u32 s8, s12, 0x10180
	s_addc_u32 s9, s13, 0
	s_cmpk_gt_u32 s42, 0xff
	s_mov_b32 m0, s46
	v_lshl_add_u64 v[90:91], s[48:49], 0, v[14:15]
	ds_read_b128 v[50:53], v156
	ds_read_b128 v[54:57], v156 offset:1024
	ds_read_b128 v[58:61], v156 offset:2048
	ds_read_b128 v[62:65], v156 offset:3072
	ds_read_b128 v[74:77], v156 offset:4096
	ds_read_b128 v[78:81], v156 offset:5120
	ds_read_b128 v[82:85], v156 offset:6144
	ds_read_b128 v[86:89], v156 offset:7168
	global_load_lds_dwordx4 v[90:91], off
	v_lshl_add_u64 v[90:91], s[48:49], 0, v[2:3]
	s_mov_b32 m0, s45
	s_nop 0
	global_load_lds_dwordx4 v[90:91], off
	s_waitcnt vmcnt(8) lgkmcnt(0)
	s_barrier
	s_setprio 1
	v_mfma_f32_16x16x32_bf16 v[90:93], v[34:37], v[50:53], 0
	v_mfma_f32_16x16x32_bf16 v[50:53], v[42:45], v[50:53], 0
	v_mfma_f32_16x16x32_bf16 v[90:93], v[38:41], v[54:57], v[90:93]
	v_mfma_f32_16x16x32_bf16 v[50:53], v[46:49], v[54:57], v[50:53]
	v_mfma_f32_16x16x32_bf16 v[54:57], v[34:37], v[58:61], 0
	v_mfma_f32_16x16x32_bf16 v[58:61], v[42:45], v[58:61], 0
	v_mfma_f32_16x16x32_bf16 v[54:57], v[38:41], v[62:65], v[54:57]
	v_mfma_f32_16x16x32_bf16 v[58:61], v[46:49], v[62:65], v[58:61]
	v_mfma_f32_16x16x32_bf16 v[62:65], v[34:37], v[74:77], 0
	v_mfma_f32_16x16x32_bf16 v[74:77], v[42:45], v[74:77], 0
	v_mfma_f32_16x16x32_bf16 v[62:65], v[38:41], v[78:81], v[62:65]
	v_mfma_f32_16x16x32_bf16 v[74:77], v[46:49], v[78:81], v[74:77]
	v_mfma_f32_16x16x32_bf16 v[78:81], v[34:37], v[82:85], 0
	v_mfma_f32_16x16x32_bf16 v[82:85], v[42:45], v[82:85], 0
	v_mfma_f32_16x16x32_bf16 v[78:81], v[38:41], v[86:89], v[78:81]
	v_mfma_f32_16x16x32_bf16 v[82:85], v[46:49], v[86:89], v[82:85]
	s_setprio 0
	s_setprio 1
	s_setprio 0
	s_barrier
	s_mov_b64 s[12:13], 0x100
	s_mov_b32 m0, s44
	v_lshl_add_u64 v[122:123], v[4:5], 0, s[12:13]
	ds_read_b128 v[86:89], v156 offset:16384
	ds_read_b128 v[94:97], v156 offset:17408
	ds_read_b128 v[98:101], v156 offset:18432
	ds_read_b128 v[102:105], v156 offset:19456
	ds_read_b128 v[106:109], v156 offset:20480
	ds_read_b128 v[110:113], v156 offset:21504
	ds_read_b128 v[114:117], v156 offset:22528
	ds_read_b128 v[118:121], v156 offset:23552
	global_load_lds_dwordx4 v[122:123], off
	v_lshl_add_u64 v[122:123], v[6:7], 0, s[12:13]
	s_mov_b32 m0, s43
	s_nop 0
	global_load_lds_dwordx4 v[122:123], off
	v_lshl_add_u64 v[122:123], s[50:51], 0, v[32:33]
	s_mov_b32 m0, s29
	s_nop 0
	global_load_lds_dwordx4 v[122:123], off
	v_lshl_add_u64 v[122:123], s[50:51], 0, v[20:21]
	s_mov_b32 m0, s31
	s_nop 0
	global_load_lds_dwordx4 v[122:123], off
	v_lshl_add_u64 v[122:123], v[18:19], 0, s[12:13]
	s_mov_b32 m0, s27
	s_nop 0
	global_load_lds_dwordx4 v[122:123], off
	v_lshl_add_u64 v[122:123], v[22:23], 0, s[12:13]
	s_mov_b32 m0, s35
	s_nop 0
	global_load_lds_dwordx4 v[122:123], off
	s_waitcnt vmcnt(8) lgkmcnt(0)
	s_barrier
	s_setprio 1
	v_mfma_f32_16x16x32_bf16 v[122:125], v[34:37], v[86:89], 0
	v_mfma_f32_16x16x32_bf16 v[86:89], v[42:45], v[86:89], 0
	v_mfma_f32_16x16x32_bf16 v[122:125], v[38:41], v[94:97], v[122:125]
	v_mfma_f32_16x16x32_bf16 v[86:89], v[46:49], v[94:97], v[86:89]
	v_mfma_f32_16x16x32_bf16 v[94:97], v[34:37], v[98:101], 0
	v_mfma_f32_16x16x32_bf16 v[98:101], v[42:45], v[98:101], 0
	v_mfma_f32_16x16x32_bf16 v[94:97], v[38:41], v[102:105], v[94:97]
	v_mfma_f32_16x16x32_bf16 v[98:101], v[46:49], v[102:105], v[98:101]
	v_mfma_f32_16x16x32_bf16 v[102:105], v[34:37], v[106:109], 0
	v_mfma_f32_16x16x32_bf16 v[34:37], v[34:37], v[114:117], 0
	v_mfma_f32_16x16x32_bf16 v[102:105], v[38:41], v[110:113], v[102:105]
	v_mfma_f32_16x16x32_bf16 v[34:37], v[38:41], v[118:121], v[34:37]
	v_mfma_f32_16x16x32_bf16 v[38:41], v[42:45], v[114:117], 0
	v_mfma_f32_16x16x32_bf16 v[106:109], v[42:45], v[106:109], 0
	v_mfma_f32_16x16x32_bf16 v[38:41], v[46:49], v[118:121], v[38:41]
	v_mfma_f32_16x16x32_bf16 v[106:109], v[46:49], v[110:113], v[106:109]
	s_setprio 0
	s_setprio 1
	s_setprio 0
	s_barrier
; #define PG8_STAGE(bufoff, gbase, voff) do { _Pragma("unroll") for (int _i = 0; _i < 2; ++_i) \
;         __builtin_amdgcn_global_load_lds((const unsigned*)((const char*)(gbase) + (voff)[_i]), (PG8_LAS unsigned*)(lds + (bufoff) + ldsw + _i * 8192), 16, 0, 0); } while (0)
; #define PG8_LDA(dst, b, h) do { _Pragma("unroll") for (int m = 0; m < 4; ++m) _Pragma("unroll") for (int k = 0; k < 2; ++k) dst[m][k] = *(const PG8_LAS bf16x8*)(lds + PG8_SA(b, h) + aoff + m * 2048 + k * 1024); } while (0)
; #define PG8_LDB(dst, b, h) do { _Pragma("unroll") for (int n = 0; n < 2; ++n) _Pragma("unroll") for (int k = 0; k < 2; ++k) dst[n][k] = *(const PG8_LAS bf16x8*)(lds + PG8_SB(b, h) + boff + n * 2048 + k * 1024); } while (0)
; #define PG8_MMA(ai, bj, At, Bt) do { __builtin_amdgcn_s_setprio(1); _Pragma("unroll") for (int m = 0; m < 4; ++m) _Pragma("unroll") for (int n = 0; n < 2; ++n) _Pragma("unroll") for (int k = 0; k < 2; ++k) \
;         acc[ai][bj][m][n] = __builtin_amdgcn_mfma_f32_16x16x32_bf16(Bt[n][k], At[m][k], acc[ai][bj][m][n], 0, 0, 0); __builtin_amdgcn_s_setprio(0); } while (0)
; #define PG8_WAIT_V(n) asm volatile("s_waitcnt vmcnt(" #n ")" ::: "memory")
; template <class Epi, class Sched, bool ALIGN_EPI = false, bool SP2 = false>
; __device__ __forceinline__ void gemm_phase(PG8_LAS unsigned char* lds, const Gemm g, const Sched& S, const Epi& E) {
;     ...
;             PG8_LDB(B0, 0, 0); PG8_LDB(B1, 0, 1); PG8_SCHED; PG8_LDA(At, 0, 0); PG8_STAGE(PG8_SA(1, 1), a1 + hstepA, voffA);
;             PG8_WAIT_V(8); PG8_WAIT_L(0); PG8_BAR; PG8_MMA(0, 0, At, B0); PG8_MMA(0, 1, At, B1); PG8_BAR; PG8_SCHED;
;             PG8_LDA(At, 0, 1); PG8_STAGE(PG8_SB(0, 0), b2, voffB); PG8_STAGE(PG8_SB(0, 1), b2 + hstepB, voffB); PG8_STAGE(PG8_SA(0, 0), a2, voffA);
;             PG8_WAIT_V(8); PG8_WAIT_L(0); PG8_BAR; PG8_MMA(1, 0, At, B0); PG8_MMA(1, 1, At, B1); PG8_BAR; PG8_SCHED;
;             PG8_LDB(B0, 1, 0); PG8_LDB(B1, 1, 1); PG8_SCHED; PG8_LDA(At, 1, 0); PG8_STAGE(PG8_SA(0, 1), a2 + hstepA, voffA);
;             PG8_WAIT_V(8); PG8_WAIT_L(0); PG8_BAR; PG8_MMA(0, 0, At, B0); PG8_MMA(0, 1, At, B1); PG8_BAR; PG8_SCHED;
;             PG8_LDA(At, 1, 1); PG8_STAGE(PG8_SB(1, 0), b3, voffB); PG8_STAGE(PG8_SB(1, 1), b3 + hstepB, voffB); PG8_STAGE(PG8_SA(1, 0), a3, voffA);
;             PG8_WAIT_V(8); PG8_WAIT_L(0); PG8_BAR; PG8_MMA(1, 0, At, B0); PG8_MMA(1, 1, At, B1); PG8_BAR; PG8_SCHED;
	ds_read_b128 v[42:45], v157
	ds_read_b128 v[46:49], v157 offset:1024
	ds_read_b128 v[110:113], v157 offset:2048
	ds_read_b128 v[114:117], v157 offset:3072
	s_mov_b32 m0, s30
	v_lshl_add_u64 v[154:155], s[16:17], 0, v[14:15]
	ds_read_b128 v[118:121], v156 offset:32768
	ds_read_b128 v[126:129], v156 offset:33792
	ds_read_b128 v[130:133], v156 offset:34816
	ds_read_b128 v[134:137], v156 offset:35840
	ds_read_b128 v[138:141], v156 offset:36864
	ds_read_b128 v[142:145], v156 offset:37888
	ds_read_b128 v[146:149], v156 offset:38912
	ds_read_b128 v[150:153], v156 offset:39936
	global_load_lds_dwordx4 v[154:155], off
	v_lshl_add_u64 v[154:155], s[16:17], 0, v[2:3]
	s_mov_b32 m0, s34
	s_nop 0
	global_load_lds_dwordx4 v[154:155], off
	s_waitcnt vmcnt(8) lgkmcnt(0)
	s_barrier
	s_setprio 1
	v_mfma_f32_16x16x32_bf16 v[50:53], v[110:113], v[118:121], v[50:53]
	v_mfma_f32_16x16x32_bf16 v[54:57], v[42:45], v[130:133], v[54:57]
	v_mfma_f32_16x16x32_bf16 v[58:61], v[110:113], v[130:133], v[58:61]
	v_mfma_f32_16x16x32_bf16 v[62:65], v[42:45], v[138:141], v[62:65]
	v_mfma_f32_16x16x32_bf16 v[90:93], v[42:45], v[118:121], v[90:93]
	v_mfma_f32_16x16x32_bf16 v[50:53], v[114:117], v[126:129], v[50:53]
	v_mfma_f32_16x16x32_bf16 v[54:57], v[46:49], v[134:137], v[54:57]
	v_mfma_f32_16x16x32_bf16 v[58:61], v[114:117], v[134:137], v[58:61]
	v_mfma_f32_16x16x32_bf16 v[62:65], v[46:49], v[142:145], v[62:65]
	v_mfma_f32_16x16x32_bf16 v[74:77], v[110:113], v[138:141], v[74:77]
	v_mfma_f32_16x16x32_bf16 v[78:81], v[42:45], v[146:149], v[78:81]
	v_mfma_f32_16x16x32_bf16 v[82:85], v[110:113], v[146:149], v[82:85]
	v_mfma_f32_16x16x32_bf16 v[90:93], v[46:49], v[126:129], v[90:93]
	v_mfma_f32_16x16x32_bf16 v[74:77], v[114:117], v[142:145], v[74:77]
	v_mfma_f32_16x16x32_bf16 v[78:81], v[46:49], v[150:153], v[78:81]
	v_mfma_f32_16x16x32_bf16 v[82:85], v[114:117], v[150:153], v[82:85]
	s_setprio 0
	s_setprio 1
	s_setprio 0
	s_barrier
	s_mov_b64 s[12:13], 0x180
	s_mov_b32 m0, s36
	v_lshl_add_u64 v[154:155], v[4:5], 0, s[12:13]
	ds_read_b128 v[118:121], v156 offset:49152
	ds_read_b128 v[126:129], v156 offset:50176
	ds_read_b128 v[130:133], v156 offset:51200
	ds_read_b128 v[134:137], v156 offset:52224
	ds_read_b128 v[138:141], v156 offset:53248
	ds_read_b128 v[142:145], v156 offset:54272
	ds_read_b128 v[146:149], v156 offset:55296
	ds_read_b128 v[150:153], v156 offset:56320
	global_load_lds_dwordx4 v[154:155], off
	v_lshl_add_u64 v[154:155], v[6:7], 0, s[12:13]
	s_mov_b32 m0, s38
	v_lshl_add_u64 v[32:33], s[14:15], 0, v[32:33]
	global_load_lds_dwordx4 v[154:155], off
	s_mov_b32 m0, s40
	v_lshl_add_u64 v[20:21], s[14:15], 0, v[20:21]
	global_load_lds_dwordx4 v[32:33], off
	s_mov_b32 m0, s41
	s_nop 0
	global_load_lds_dwordx4 v[20:21], off
	v_lshl_add_u64 v[20:21], v[18:19], 0, s[12:13]
	s_mov_b32 m0, s37
	s_nop 0
	global_load_lds_dwordx4 v[20:21], off
	v_lshl_add_u64 v[20:21], v[22:23], 0, s[12:13]
	s_mov_b32 m0, s39
	s_nop 0
	global_load_lds_dwordx4 v[20:21], off
	s_waitcnt vmcnt(8) lgkmcnt(0)
	s_barrier
	s_setprio 1
	v_mfma_f32_16x16x32_bf16 v[32:35], v[42:45], v[146:149], v[34:37]
	v_mfma_f32_16x16x32_bf16 v[36:39], v[110:113], v[146:149], v[38:41]
	v_mfma_f32_16x16x32_bf16 v[122:125], v[42:45], v[118:121], v[122:125]
	v_mfma_f32_16x16x32_bf16 v[86:89], v[110:113], v[118:121], v[86:89]
	v_mfma_f32_16x16x32_bf16 v[94:97], v[42:45], v[130:133], v[94:97]
	v_mfma_f32_16x16x32_bf16 v[98:101], v[110:113], v[130:133], v[98:101]
	v_mfma_f32_16x16x32_bf16 v[102:105], v[42:45], v[138:141], v[102:105]
	v_mfma_f32_16x16x32_bf16 v[106:109], v[110:113], v[138:141], v[106:109]
	v_mfma_f32_16x16x32_bf16 v[32:35], v[46:49], v[150:153], v[32:35]
	v_mfma_f32_16x16x32_bf16 v[36:39], v[114:117], v[150:153], v[36:39]
	v_mfma_f32_16x16x32_bf16 v[122:125], v[46:49], v[126:129], v[122:125]
	v_mfma_f32_16x16x32_bf16 v[86:89], v[114:117], v[126:129], v[86:89]
	v_mfma_f32_16x16x32_bf16 v[94:97], v[46:49], v[134:137], v[94:97]
	v_mfma_f32_16x16x32_bf16 v[98:101], v[114:117], v[134:137], v[98:101]
	v_mfma_f32_16x16x32_bf16 v[102:105], v[46:49], v[142:145], v[102:105]
	v_mfma_f32_16x16x32_bf16 v[106:109], v[114:117], v[142:145], v[106:109]
	s_setprio 0
	s_setprio 1
	s_setprio 0
	s_barrier
	ds_read_b128 v[40:43], v73
	ds_read_b128 v[44:47], v73 offset:1024
	ds_read_b128 v[110:113], v73 offset:2048
	ds_read_b128 v[114:117], v73 offset:3072
	s_mov_b32 m0, s46
	v_lshl_add_u64 v[14:15], s[8:9], 0, v[14:15]
	ds_read_b128 v[118:121], v156
	ds_read_b128 v[126:129], v156 offset:1024
	ds_read_b128 v[130:133], v156 offset:2048
	ds_read_b128 v[134:137], v156 offset:3072
	ds_read_b128 v[138:141], v156 offset:4096
	ds_read_b128 v[142:145], v156 offset:5120
	ds_read_b128 v[146:149], v156 offset:6144
	ds_read_b128 v[150:153], v156 offset:7168
	global_load_lds_dwordx4 v[14:15], off
	v_lshl_add_u64 v[2:3], s[8:9], 0, v[2:3]
	s_mov_b32 m0, s45
	s_nop 0
	global_load_lds_dwordx4 v[2:3], off
	s_waitcnt vmcnt(8) lgkmcnt(0)
	s_barrier
	s_setprio 1
	v_mfma_f32_16x16x32_bf16 v[48:51], v[110:113], v[118:121], v[50:53]
	v_mfma_f32_16x16x32_bf16 v[52:55], v[40:43], v[130:133], v[54:57]
	v_mfma_f32_16x16x32_bf16 v[56:59], v[110:113], v[130:133], v[58:61]
	v_mfma_f32_16x16x32_bf16 v[90:93], v[40:43], v[118:121], v[90:93]
	v_mfma_f32_16x16x32_bf16 v[118:121], v[114:117], v[134:137], v[56:59]
	v_mfma_f32_16x16x32_bf16 v[56:59], v[40:43], v[138:141], v[62:65]
	v_mfma_f32_16x16x32_bf16 v[90:93], v[44:47], v[126:129], v[90:93]
	v_mfma_f32_16x16x32_bf16 v[48:51], v[114:117], v[126:129], v[48:51]
	v_mfma_f32_16x16x32_bf16 v[126:129], v[44:47], v[142:145], v[56:59]
	v_mfma_f32_16x16x32_bf16 v[56:59], v[110:113], v[138:141], v[74:77]
	v_mfma_f32_16x16x32_bf16 v[74:77], v[114:117], v[142:145], v[56:59]
	v_mfma_f32_16x16x32_bf16 v[56:59], v[40:43], v[146:149], v[78:81]
	v_mfma_f32_16x16x32_bf16 v[52:55], v[44:47], v[134:137], v[52:55]
	v_mfma_f32_16x16x32_bf16 v[78:81], v[44:47], v[150:153], v[56:59]
	v_mfma_f32_16x16x32_bf16 v[56:59], v[110:113], v[146:149], v[82:85]
	v_mfma_f32_16x16x32_bf16 v[82:85], v[114:117], v[150:153], v[56:59]
	s_setprio 0
	s_setprio 1
	s_setprio 0
	s_barrier
; #define PG8_STAGE(bufoff, gbase, voff) do { _Pragma("unroll") for (int _i = 0; _i < 2; ++_i) \
;         __builtin_amdgcn_global_load_lds((const unsigned*)((const char*)(gbase) + (voff)[_i]), (PG8_LAS unsigned*)(lds + (bufoff) + ldsw + _i * 8192), 16, 0, 0); } while (0)
; #define PG8_LDA(dst, b, h) do { _Pragma("unroll") for (int m = 0; m < 4; ++m) _Pragma("unroll") for (int k = 0; k < 2; ++k) dst[m][k] = *(const PG8_LAS bf16x8*)(lds + PG8_SA(b, h) + aoff + m * 2048 + k * 1024); } while (0)
; #define PG8_LDB(dst, b, h) do { _Pragma("unroll") for (int n = 0; n < 2; ++n) _Pragma("unroll") for (int k = 0; k < 2; ++k) dst[n][k] = *(const PG8_LAS bf16x8*)(lds + PG8_SB(b, h) + boff + n * 2048 + k * 1024); } while (0)
; #define PG8_MMA(ai, bj, At, Bt) do { __builtin_amdgcn_s_setprio(1); _Pragma("unroll") for (int m = 0; m < 4; ++m) _Pragma("unroll") for (int n = 0; n < 2; ++n) _Pragma("unroll") for (int k = 0; k < 2; ++k) \
;         acc[ai][bj][m][n] = __builtin_amdgcn_mfma_f32_16x16x32_bf16(Bt[n][k], At[m][k], acc[ai][bj][m][n], 0, 0, 0); __builtin_amdgcn_s_setprio(0); } while (0)
; template <class Epi, class Sched, bool ALIGN_EPI = false, bool SP2 = false>
; __device__ __forceinline__ void gemm_phase(PG8_LAS unsigned char* lds, const Gemm g, const Sched& S, const Epi& E) {
;     ...
;             PG8_LDB(B0, 0, 0); PG8_LDB(B1, 0, 1); PG8_SCHED; PG8_LDA(At, 0, 0); PG8_STAGE(PG8_SA(1, 1), a1 + hstepA, voffA);
;             PG8_WAIT_V(8); PG8_WAIT_L(0); PG8_BAR; PG8_MMA(0, 0, At, B0); PG8_MMA(0, 1, At, B1); PG8_BAR; PG8_SCHED;
;             PG8_LDA(At, 0, 1); PG8_STAGE(PG8_SB(0, 0), b2, voffB); PG8_STAGE(PG8_SB(0, 1), b2 + hstepB, voffB); PG8_STAGE(PG8_SA(0, 0), a2, voffA);
;             PG8_WAIT_V(8); PG8_WAIT_L(0); PG8_BAR; PG8_MMA(1, 0, At, B0); PG8_MMA(1, 1, At, B1); PG8_BAR; PG8_SCHED;
;             PG8_LDB(B0, 1, 0); PG8_LDB(B1, 1, 1); PG8_SCHED; PG8_LDA(At, 1, 0); PG8_STAGE(PG8_SA(0, 1), a2 + hstepA, voffA);
;             PG8_WAIT_V(8); PG8_WAIT_L(0); PG8_BAR; PG8_MMA(0, 0, At, B0); PG8_MMA(0, 1, At, B1); PG8_BAR; PG8_SCHED;
;             PG8_LDA(At, 1, 1); PG8_STAGE(PG8_SB(1, 0), b3, voffB); PG8_STAGE(PG8_SB(1, 1), b3 + hstepB, voffB); PG8_STAGE(PG8_SA(1, 0), a3, voffA);
;             PG8_WAIT_V(8); PG8_WAIT_L(0); PG8_BAR; PG8_MMA(1, 0, At, B0); PG8_MMA(1, 1, At, B1); PG8_BAR; PG8_SCHED;
;     ...
;         if constexpr (ALIGN_EPI) { if (wr == 0) PG8_BAR; }
	s_mov_b32 m0, s44
	s_nop 1
	ds_read_b128 v[56:59], v156 offset:16384
	ds_read_b128 v[60:63], v156 offset:17408
	ds_read_b128 v[130:133], v156 offset:18432
	ds_read_b128 v[134:137], v156 offset:19456
	ds_read_b128 v[138:141], v156 offset:20480
	ds_read_b128 v[142:145], v156 offset:21504
	ds_read_b128 v[146:149], v156 offset:22528
	ds_read_b128 v[150:153], v156 offset:23552
	global_load_lds_dwordx4 v[4:5], off
	s_mov_b32 m0, s43
	s_nop 0
	global_load_lds_dwordx4 v[6:7], off
	s_mov_b32 m0, s29
	s_nop 0
	global_load_lds_dwordx4 v[8:9], off
	s_mov_b32 m0, s31
	s_nop 0
	global_load_lds_dwordx4 v[10:11], off
	s_mov_b32 m0, s27
	s_nop 0
	global_load_lds_dwordx4 v[18:19], off
	s_mov_b32 m0, s35
	s_nop 0
	global_load_lds_dwordx4 v[22:23], off
	s_waitcnt vmcnt(8) lgkmcnt(0)
	s_barrier
	s_setprio 1
	v_mfma_f32_16x16x32_bf16 v[2:5], v[40:43], v[56:59], v[122:125]
	v_mfma_f32_16x16x32_bf16 v[6:9], v[110:113], v[56:59], v[86:89]
	v_mfma_f32_16x16x32_bf16 v[56:59], v[110:113], v[130:133], v[98:101]
	v_mfma_f32_16x16x32_bf16 v[18:21], v[40:43], v[130:133], v[94:97]
	v_mfma_f32_16x16x32_bf16 v[86:89], v[114:117], v[134:137], v[56:59]
	v_mfma_f32_16x16x32_bf16 v[56:59], v[40:43], v[138:141], v[102:105]
	v_mfma_f32_16x16x32_bf16 v[32:35], v[40:43], v[146:149], v[32:35]
	v_mfma_f32_16x16x32_bf16 v[2:5], v[44:47], v[60:63], v[2:5]
	v_mfma_f32_16x16x32_bf16 v[6:9], v[114:117], v[60:63], v[6:9]
	v_mfma_f32_16x16x32_bf16 v[18:21], v[44:47], v[134:137], v[18:21]
	v_mfma_f32_16x16x32_bf16 v[94:97], v[44:47], v[142:145], v[56:59]
	v_mfma_f32_16x16x32_bf16 v[56:59], v[110:113], v[138:141], v[106:109]
	v_mfma_f32_16x16x32_bf16 v[102:105], v[44:47], v[150:153], v[32:35]
	v_mfma_f32_16x16x32_bf16 v[32:35], v[110:113], v[146:149], v[36:39]
	v_mfma_f32_16x16x32_bf16 v[98:101], v[114:117], v[142:145], v[56:59]
	v_mfma_f32_16x16x32_bf16 v[106:109], v[114:117], v[150:153], v[32:35]
	s_setprio 0
	s_setprio 1
	s_setprio 0
	s_barrier
	ds_read_b128 v[110:113], v157
	ds_read_b128 v[114:117], v157 offset:1024
	ds_read_b128 v[122:125], v157 offset:2048
	ds_read_b128 v[130:133], v157 offset:3072
	s_mov_b32 m0, s30
	ds_read_b128 v[32:35], v156 offset:32768
	ds_read_b128 v[36:39], v156 offset:33792
	ds_read_b128 v[40:43], v156 offset:34816
	ds_read_b128 v[44:47], v156 offset:35840
	ds_read_b128 v[134:137], v156 offset:36864
	ds_read_b128 v[138:141], v156 offset:37888
	ds_read_b128 v[142:145], v156 offset:38912
	ds_read_b128 v[146:149], v156 offset:39936
	global_load_lds_dwordx4 v[12:13], off
	s_mov_b32 m0, s34
	s_nop 0
	global_load_lds_dwordx4 v[16:17], off
	s_waitcnt vmcnt(8) lgkmcnt(0)
	s_barrier
	s_setprio 1
	v_mfma_f32_16x16x32_bf16 v[10:13], v[110:113], v[32:35], v[90:93]
	v_mfma_f32_16x16x32_bf16 v[58:61], v[114:117], v[36:39], v[10:13]
	v_mfma_f32_16x16x32_bf16 v[10:13], v[122:125], v[32:35], v[48:51]
	v_mfma_f32_16x16x32_bf16 v[62:65], v[130:133], v[36:39], v[10:13]
	v_mfma_f32_16x16x32_bf16 v[10:13], v[110:113], v[40:43], v[52:55]
	v_mfma_f32_16x16x32_bf16 v[50:53], v[114:117], v[44:47], v[10:13]
	v_mfma_f32_16x16x32_bf16 v[10:13], v[122:125], v[40:43], v[118:121]
	v_mfma_f32_16x16x32_bf16 v[54:57], v[130:133], v[44:47], v[10:13]
	v_mfma_f32_16x16x32_bf16 v[10:13], v[110:113], v[134:137], v[126:129]
	v_mfma_f32_16x16x32_bf16 v[42:45], v[114:117], v[138:141], v[10:13]
	v_mfma_f32_16x16x32_bf16 v[10:13], v[122:125], v[134:137], v[74:77]
	v_mfma_f32_16x16x32_bf16 v[46:49], v[130:133], v[138:141], v[10:13]
	v_mfma_f32_16x16x32_bf16 v[10:13], v[110:113], v[142:145], v[78:81]
	v_mfma_f32_16x16x32_bf16 v[34:37], v[114:117], v[146:149], v[10:13]
	v_mfma_f32_16x16x32_bf16 v[10:13], v[122:125], v[142:145], v[82:85]
	v_mfma_f32_16x16x32_bf16 v[38:41], v[130:133], v[146:149], v[10:13]
	s_setprio 0
	s_setprio 1
	s_setprio 0
	s_barrier
	s_mov_b32 m0, s36
	s_nop 1
	ds_read_b128 v[10:13], v156 offset:49152
	ds_read_b128 v[14:17], v156 offset:50176
	ds_read_b128 v[74:77], v156 offset:51200
	ds_read_b128 v[78:81], v156 offset:52224
	ds_read_b128 v[82:85], v156 offset:53248
	ds_read_b128 v[90:93], v156 offset:54272
	ds_read_b128 v[118:121], v156 offset:55296
	ds_read_b128 v[126:129], v156 offset:56320
	global_load_lds_dwordx4 v[26:27], off
	s_mov_b32 m0, s38
	s_nop 0
	global_load_lds_dwordx4 v[28:29], off
	s_mov_b32 m0, s40
	s_nop 0
	global_load_lds_dwordx4 v[68:69], off
	s_mov_b32 m0, s41
	s_nop 0
	global_load_lds_dwordx4 v[70:71], off
	s_mov_b32 m0, s37
	s_nop 0
	global_load_lds_dwordx4 v[24:25], off
	s_mov_b32 m0, s39
	s_nop 0
	global_load_lds_dwordx4 v[30:31], off
	s_waitcnt vmcnt(8) lgkmcnt(0)
	s_barrier
	s_setprio 1
	v_mfma_f32_16x16x32_bf16 v[2:5], v[110:113], v[10:13], v[2:5]
	v_mfma_f32_16x16x32_bf16 v[26:29], v[114:117], v[14:17], v[2:5]
	v_mfma_f32_16x16x32_bf16 v[2:5], v[122:125], v[10:13], v[6:9]
	v_mfma_f32_16x16x32_bf16 v[30:33], v[130:133], v[14:17], v[2:5]
	v_mfma_f32_16x16x32_bf16 v[2:5], v[110:113], v[74:77], v[18:21]
	v_mfma_f32_16x16x32_bf16 v[18:21], v[114:117], v[78:81], v[2:5]
	v_mfma_f32_16x16x32_bf16 v[2:5], v[122:125], v[74:77], v[86:89]
	v_mfma_f32_16x16x32_bf16 v[22:25], v[130:133], v[78:81], v[2:5]
	v_mfma_f32_16x16x32_bf16 v[2:5], v[110:113], v[82:85], v[94:97]
	v_mfma_f32_16x16x32_bf16 v[10:13], v[114:117], v[90:93], v[2:5]
	v_mfma_f32_16x16x32_bf16 v[2:5], v[122:125], v[82:85], v[98:101]
	v_mfma_f32_16x16x32_bf16 v[14:17], v[130:133], v[90:93], v[2:5]
	v_mfma_f32_16x16x32_bf16 v[2:5], v[110:113], v[118:121], v[102:105]
	v_mfma_f32_16x16x32_bf16 v[6:9], v[122:125], v[118:121], v[106:109]
	v_mfma_f32_16x16x32_bf16 v[2:5], v[114:117], v[126:129], v[2:5]
	v_mfma_f32_16x16x32_bf16 v[6:9], v[130:133], v[126:129], v[6:9]
	s_setprio 0
	s_setprio 1
	s_setprio 0
	s_barrier
	s_cbranch_scc1 .LBB0_594
	s_barrier

; #define PG8_STAGE(bufoff, gbase, voff) do { _Pragma("unroll") for (int _i = 0; _i < 2; ++_i) \
;         __builtin_amdgcn_global_load_lds((const unsigned*)((const char*)(gbase) + (voff)[_i]), (PG8_LAS unsigned*)(lds + (bufoff) + ldsw + _i * 8192), 16, 0, 0); } while (0)
; #define PG8_LDA(dst, b, h) do { _Pragma("unroll") for (int m = 0; m < 4; ++m) _Pragma("unroll") for (int k = 0; k < 2; ++k) dst[m][k] = *(const PG8_LAS bf16x8*)(lds + PG8_SA(b, h) + aoff + m * 2048 + k * 1024); } while (0)
; #define PG8_LDB(dst, b, h) do { _Pragma("unroll") for (int n = 0; n < 2; ++n) _Pragma("unroll") for (int k = 0; k < 2; ++k) dst[n][k] = *(const PG8_LAS bf16x8*)(lds + PG8_SB(b, h) + boff + n * 2048 + k * 1024); } while (0)
; #define PG8_BAR __builtin_amdgcn_s_barrier()
; template <class Epi, class Sched, bool ALIGN_EPI = false, bool SP2 = false>
; __device__ __forceinline__ void gemm_phase(PG8_LAS unsigned char* lds, const Gemm g, const Sched& S, const Epi& E) {
;     ...
;             const bool last = (t == nt - 2);
;             const char* a1 = cA + (size_t)(t + 1) * kstep;
;             const char* a2 = last ? nA : cA + (size_t)(t + 2) * kstep; const char* b2 = last ? nB : cB + (size_t)(t + 2) * kstep;
;             const char* a3 = a2 + kstep; const char* b3 = b2 + kstep;
;             if (last && has_next) S.a_ready(nxt);
;             if constexpr (SP2) {
;             PG8_LDB(B0, 0, 0); PG8_LDB(B1, 0, 1); PG8_SCHED; PG8_LDA(At, 0, 0); PG8_STAGE(PG8_SA(1, 1), a1 + hstepA, voffA);
;             PG8_WAIT_V(8); PG8_WAIT_L(0); PG8_BAR; PG8_MMA(0, 0, At, B0); PG8_MMA(0, 1, At, B1); PG8_BAR; PG8_SCHED;
;             PG8_LDA(At, 0, 1); PG8_STAGE(PG8_SB(0, 0), b2, voffB); PG8_STAGE(PG8_SB(0, 1), b2 + hstepB, voffB); PG8_STAGE(PG8_SA(0, 0), a2, voffA);
;             PG8_WAIT_V(8); PG8_WAIT_L(0); PG8_BAR; PG8_MMA(1, 0, At, B0); PG8_MMA(1, 1, At, B1); PG8_BAR; PG8_SCHED;
;             PG8_LDB(B0, 1, 0); PG8_LDB(B1, 1, 1); PG8_SCHED; PG8_LDA(At, 1, 0); PG8_STAGE(PG8_SA(0, 1), a2 + hstepA, voffA);
;             PG8_WAIT_V(8); PG8_WAIT_L(0); PG8_BAR; PG8_MMA(0, 0, At, B0); PG8_MMA(0, 1, At, B1); PG8_BAR; PG8_SCHED;
;             PG8_LDA(At, 1, 1); PG8_STAGE(PG8_SB(1, 0), b3, voffB); PG8_STAGE(PG8_SB(1, 1), b3 + hstepB, voffB); PG8_STAGE(PG8_SA(1, 0), a3, voffA);
;             PG8_WAIT_V(8); PG8_WAIT_L(0); PG8_BAR; PG8_MMA(1, 0, At, B0); PG8_MMA(1, 1, At, B1); PG8_BAR; PG8_SCHED;
.LBB0_1160:
	s_add_u32 s24, s22, 0x100
	s_addc_u32 s25, s23, 0
	s_add_i32 s57, 0, 0x10000
	s_cmp_eq_u32 s56, 4
	s_cselect_b32 s29, s17, s25
	s_cselect_b32 s28, s16, s24
	v_add_u32_e32 v145, s57, v142
	s_cselect_b32 s27, s52, s55
	s_cselect_b32 s26, s53, s54
	s_add_i32 s58, 0, 0x14000
	ds_read_b128 v[146:149], v145
	ds_read_b128 v[150:153], v145 offset:1024
	ds_read_b128 v[154:157], v145 offset:2048
	ds_read_b128 v[158:161], v145 offset:3072
	v_add_u32_e32 v145, s58, v142
	ds_read_b128 v[162:165], v145
	ds_read_b128 v[166:169], v145 offset:1024
	ds_read_b128 v[170:173], v145 offset:2048
	ds_read_b128 v[174:177], v145 offset:3072
	s_add_i32 m0, s39, 0xc000
	ds_read_b128 v[178:181], v143
	ds_read_b128 v[182:185], v143 offset:1024
	ds_read_b128 v[202:205], v143 offset:2048
	ds_read_b128 v[206:209], v143 offset:3072
	ds_read_b128 v[210:213], v143 offset:4096
	ds_read_b128 v[232:235], v143 offset:5120
	ds_read_b128 v[236:239], v143 offset:6144
	ds_read_b128 v[240:243], v143 offset:7168
	global_load_lds_dwordx4 v138, s[22:23]
	s_add_i32 m0, s39, 0xe000
	s_nop 0
	global_load_lds_dwordx4 v140, s[22:23]
	s_waitcnt vmcnt(8) lgkmcnt(0)
	s_barrier
	s_setprio 1
	v_mfma_f32_16x16x32_bf16 v[126:129], v[146:149], v[178:181], v[126:129]
	v_mfma_f32_16x16x32_bf16 v[122:125], v[154:157], v[178:181], v[122:125]
	v_mfma_f32_16x16x32_bf16 v[118:121], v[146:149], v[202:205], v[118:121]
	v_mfma_f32_16x16x32_bf16 v[114:117], v[154:157], v[202:205], v[114:117]
	v_mfma_f32_16x16x32_bf16 v[110:113], v[146:149], v[210:213], v[110:113]
	v_mfma_f32_16x16x32_bf16 v[106:109], v[154:157], v[210:213], v[106:109]
	v_mfma_f32_16x16x32_bf16 v[102:105], v[146:149], v[236:239], v[102:105]
	v_mfma_f32_16x16x32_bf16 v[98:101], v[154:157], v[236:239], v[98:101]
	v_mfma_f32_16x16x32_bf16 v[126:129], v[150:153], v[182:185], v[126:129]
	v_mfma_f32_16x16x32_bf16 v[122:125], v[158:161], v[182:185], v[122:125]
	v_mfma_f32_16x16x32_bf16 v[118:121], v[150:153], v[206:209], v[118:121]
	v_mfma_f32_16x16x32_bf16 v[114:117], v[158:161], v[206:209], v[114:117]
	v_mfma_f32_16x16x32_bf16 v[110:113], v[150:153], v[232:235], v[110:113]
	v_mfma_f32_16x16x32_bf16 v[106:109], v[158:161], v[232:235], v[106:109]
	v_mfma_f32_16x16x32_bf16 v[102:105], v[150:153], v[240:243], v[102:105]
	v_mfma_f32_16x16x32_bf16 v[98:101], v[158:161], v[240:243], v[98:101]
	s_setprio 0
	s_setprio 1
	v_mfma_f32_16x16x32_bf16 v[78:81], v[162:165], v[178:181], v[78:81]
	v_mfma_f32_16x16x32_bf16 v[70:73], v[170:173], v[178:181], v[70:73]
	v_mfma_f32_16x16x32_bf16 v[62:65], v[162:165], v[202:205], v[62:65]
	v_mfma_f32_16x16x32_bf16 v[54:57], v[170:173], v[202:205], v[54:57]
	v_mfma_f32_16x16x32_bf16 v[46:49], v[162:165], v[210:213], v[46:49]
	v_mfma_f32_16x16x32_bf16 v[42:45], v[170:173], v[210:213], v[42:45]
	v_mfma_f32_16x16x32_bf16 v[38:41], v[162:165], v[236:239], v[38:41]
	v_mfma_f32_16x16x32_bf16 v[34:37], v[170:173], v[236:239], v[34:37]
	v_mfma_f32_16x16x32_bf16 v[78:81], v[166:169], v[182:185], v[78:81]
	v_mfma_f32_16x16x32_bf16 v[70:73], v[174:177], v[182:185], v[70:73]
	v_mfma_f32_16x16x32_bf16 v[62:65], v[166:169], v[206:209], v[62:65]
	v_mfma_f32_16x16x32_bf16 v[54:57], v[174:177], v[206:209], v[54:57]
	v_mfma_f32_16x16x32_bf16 v[46:49], v[166:169], v[232:235], v[46:49]
	v_mfma_f32_16x16x32_bf16 v[42:45], v[174:177], v[232:235], v[42:45]
	v_mfma_f32_16x16x32_bf16 v[38:41], v[166:169], v[240:243], v[38:41]
	v_mfma_f32_16x16x32_bf16 v[34:37], v[174:177], v[240:243], v[34:37]
	s_setprio 0
	s_barrier
	s_add_i32 s22, s57, s38
	s_mov_b32 m0, s22
	ds_read_b128 v[178:181], v143 offset:16384
	ds_read_b128 v[182:185], v143 offset:17408
	ds_read_b128 v[202:205], v143 offset:18432
	ds_read_b128 v[206:209], v143 offset:19456
	ds_read_b128 v[210:213], v143 offset:20480
	ds_read_b128 v[232:235], v143 offset:21504
	ds_read_b128 v[236:239], v143 offset:22528
	ds_read_b128 v[240:243], v143 offset:23552
	s_add_u32 s60, s26, 0x80
	s_addc_u32 s61, s27, 0
	s_add_u32 s62, s28, 0x80
	s_addc_u32 s63, s29, 0
	global_load_lds_dwordx4 v134, s[26:27]
	s_add_i32 m0, s22, 0x2000
	s_add_u32 s22, s26, 0x20000
	s_addc_u32 s23, s27, 0
	s_add_i32 s57, s58, s38
	global_load_lds_dwordx4 v130, s[26:27]
	s_mov_b32 m0, s57
	s_nop 0
	global_load_lds_dwordx4 v134, s[22:23]
	s_add_i32 m0, s57, 0x2000
	s_nop 0
	global_load_lds_dwordx4 v130, s[22:23]
	s_mov_b32 m0, s39
	s_nop 0
	global_load_lds_dwordx4 v136, s[28:29]
	s_mov_b32 m0, s40
	s_nop 0
	global_load_lds_dwordx4 v132, s[28:29]
	s_waitcnt vmcnt(8) lgkmcnt(0)
	s_barrier
	s_setprio 1
	v_mfma_f32_16x16x32_bf16 v[94:97], v[146:149], v[178:181], v[94:97]
	v_mfma_f32_16x16x32_bf16 v[90:93], v[154:157], v[178:181], v[90:93]
	v_mfma_f32_16x16x32_bf16 v[86:89], v[146:149], v[202:205], v[86:89]
	v_mfma_f32_16x16x32_bf16 v[82:85], v[154:157], v[202:205], v[82:85]
	v_mfma_f32_16x16x32_bf16 v[74:77], v[146:149], v[210:213], v[74:77]
	v_mfma_f32_16x16x32_bf16 v[66:69], v[154:157], v[210:213], v[66:69]
	v_mfma_f32_16x16x32_bf16 v[58:61], v[146:149], v[236:239], v[58:61]
	v_mfma_f32_16x16x32_bf16 v[50:53], v[154:157], v[236:239], v[50:53]
	v_mfma_f32_16x16x32_bf16 v[94:97], v[150:153], v[182:185], v[94:97]
	v_mfma_f32_16x16x32_bf16 v[90:93], v[158:161], v[182:185], v[90:93]
	v_mfma_f32_16x16x32_bf16 v[86:89], v[150:153], v[206:209], v[86:89]
	v_mfma_f32_16x16x32_bf16 v[82:85], v[158:161], v[206:209], v[82:85]
	v_mfma_f32_16x16x32_bf16 v[74:77], v[150:153], v[232:235], v[74:77]
	v_mfma_f32_16x16x32_bf16 v[66:69], v[158:161], v[232:235], v[66:69]
	v_mfma_f32_16x16x32_bf16 v[58:61], v[150:153], v[240:243], v[58:61]
	v_mfma_f32_16x16x32_bf16 v[50:53], v[158:161], v[240:243], v[50:53]
	s_setprio 0
	s_setprio 1
	v_mfma_f32_16x16x32_bf16 v[30:33], v[162:165], v[178:181], v[30:33]
	v_mfma_f32_16x16x32_bf16 v[26:29], v[170:173], v[178:181], v[26:29]
	v_mfma_f32_16x16x32_bf16 v[22:25], v[162:165], v[202:205], v[22:25]
	v_mfma_f32_16x16x32_bf16 v[18:21], v[170:173], v[202:205], v[18:21]
	v_mfma_f32_16x16x32_bf16 v[14:17], v[162:165], v[210:213], v[14:17]
	v_mfma_f32_16x16x32_bf16 v[10:13], v[170:173], v[210:213], v[10:13]
	v_mfma_f32_16x16x32_bf16 v[6:9], v[162:165], v[236:239], v[6:9]
	v_mfma_f32_16x16x32_bf16 v[2:5], v[170:173], v[236:239], v[2:5]
	v_mfma_f32_16x16x32_bf16 v[30:33], v[166:169], v[182:185], v[30:33]
	v_mfma_f32_16x16x32_bf16 v[26:29], v[174:177], v[182:185], v[26:29]
	v_mfma_f32_16x16x32_bf16 v[22:25], v[166:169], v[206:209], v[22:25]
	v_mfma_f32_16x16x32_bf16 v[18:21], v[174:177], v[206:209], v[18:21]
	v_mfma_f32_16x16x32_bf16 v[14:17], v[166:169], v[232:235], v[14:17]
	v_mfma_f32_16x16x32_bf16 v[10:13], v[174:177], v[232:235], v[10:13]
	v_mfma_f32_16x16x32_bf16 v[6:9], v[166:169], v[240:243], v[6:9]
	v_mfma_f32_16x16x32_bf16 v[2:5], v[174:177], v[240:243], v[2:5]
	s_setprio 0
	s_barrier
; #define PG8_STAGE(bufoff, gbase, voff) do { _Pragma("unroll") for (int _i = 0; _i < 2; ++_i) \
;         __builtin_amdgcn_global_load_lds((const unsigned*)((const char*)(gbase) + (voff)[_i]), (PG8_LAS unsigned*)(lds + (bufoff) + ldsw + _i * 8192), 16, 0, 0); } while (0)
; #define PG8_LDA(dst, b, h) do { _Pragma("unroll") for (int m = 0; m < 4; ++m) _Pragma("unroll") for (int k = 0; k < 2; ++k) dst[m][k] = *(const PG8_LAS bf16x8*)(lds + PG8_SA(b, h) + aoff + m * 2048 + k * 1024); } while (0)
; #define PG8_LDB(dst, b, h) do { _Pragma("unroll") for (int n = 0; n < 2; ++n) _Pragma("unroll") for (int k = 0; k < 2; ++k) dst[n][k] = *(const PG8_LAS bf16x8*)(lds + PG8_SB(b, h) + boff + n * 2048 + k * 1024); } while (0)
; #define PG8_MMA(ai, bj, At, Bt) do { __builtin_amdgcn_s_setprio(1); _Pragma("unroll") for (int m = 0; m < 4; ++m) _Pragma("unroll") for (int n = 0; n < 2; ++n) _Pragma("unroll") for (int k = 0; k < 2; ++k) \
;         acc[ai][bj][m][n] = __builtin_amdgcn_mfma_f32_16x16x32_bf16(Bt[n][k], At[m][k], acc[ai][bj][m][n], 0, 0, 0); __builtin_amdgcn_s_setprio(0); } while (0)
; template <class Epi, class Sched, bool ALIGN_EPI = false, bool SP2 = false>
; __device__ __forceinline__ void gemm_phase(PG8_LAS unsigned char* lds, const Gemm g, const Sched& S, const Epi& E) {
;     ...
;         for (int t = 0; t < nt; t += 2) {
;     ...
;             PG8_LDB(B0, 0, 0); PG8_LDB(B1, 0, 1); PG8_SCHED; PG8_LDA(At, 0, 0); PG8_STAGE(PG8_SA(1, 1), a1 + hstepA, voffA);
;             PG8_WAIT_V(8); PG8_WAIT_L(0); PG8_BAR; PG8_MMA(0, 0, At, B0); PG8_MMA(0, 1, At, B1); PG8_BAR; PG8_SCHED;
;             PG8_LDA(At, 0, 1); PG8_STAGE(PG8_SB(0, 0), b2, voffB); PG8_STAGE(PG8_SB(0, 1), b2 + hstepB, voffB); PG8_STAGE(PG8_SA(0, 0), a2, voffA);
;             PG8_WAIT_V(8); PG8_WAIT_L(0); PG8_BAR; PG8_MMA(1, 0, At, B0); PG8_MMA(1, 1, At, B1); PG8_BAR; PG8_SCHED;
;             PG8_LDB(B0, 1, 0); PG8_LDB(B1, 1, 1); PG8_SCHED; PG8_LDA(At, 1, 0); PG8_STAGE(PG8_SA(0, 1), a2 + hstepA, voffA);
;             PG8_WAIT_V(8); PG8_WAIT_L(0); PG8_BAR; PG8_MMA(0, 0, At, B0); PG8_MMA(0, 1, At, B1); PG8_BAR; PG8_SCHED;
;             PG8_LDA(At, 1, 1); PG8_STAGE(PG8_SB(1, 0), b3, voffB); PG8_STAGE(PG8_SB(1, 1), b3 + hstepB, voffB); PG8_STAGE(PG8_SA(1, 0), a3, voffA);
;             PG8_WAIT_V(8); PG8_WAIT_L(0); PG8_BAR; PG8_MMA(1, 0, At, B0); PG8_MMA(1, 1, At, B1); PG8_BAR; PG8_SCHED;
	s_add_i32 s57, 0, 0x18000
	v_add_u32_e32 v145, s57, v142
	s_add_i32 s58, 0, 0x1c000
	ds_read_b128 v[146:149], v145
	ds_read_b128 v[150:153], v145 offset:1024
	ds_read_b128 v[154:157], v145 offset:2048
	ds_read_b128 v[158:161], v145 offset:3072
	v_add_u32_e32 v145, s58, v142
	ds_read_b128 v[162:165], v145
	ds_read_b128 v[166:169], v145 offset:1024
	ds_read_b128 v[170:173], v145 offset:2048
	ds_read_b128 v[174:177], v145 offset:3072
	s_add_u32 s22, s28, 0x30000
	s_addc_u32 s23, s29, 0
	s_mov_b32 m0, s41
	ds_read_b128 v[178:181], v143 offset:32768
	ds_read_b128 v[182:185], v143 offset:33792
	ds_read_b128 v[202:205], v143 offset:34816
	ds_read_b128 v[206:209], v143 offset:35840
	ds_read_b128 v[210:213], v143 offset:36864
	ds_read_b128 v[232:235], v143 offset:37888
	ds_read_b128 v[236:239], v143 offset:38912
	ds_read_b128 v[240:243], v143 offset:39936
	global_load_lds_dwordx4 v136, s[22:23]
	s_mov_b32 m0, s42
	s_nop 0
	global_load_lds_dwordx4 v132, s[22:23]
	s_waitcnt vmcnt(8) lgkmcnt(0)
	s_barrier
	s_setprio 1
	v_mfma_f32_16x16x32_bf16 v[126:129], v[146:149], v[178:181], v[126:129]
	v_mfma_f32_16x16x32_bf16 v[122:125], v[154:157], v[178:181], v[122:125]
	v_mfma_f32_16x16x32_bf16 v[118:121], v[146:149], v[202:205], v[118:121]
	v_mfma_f32_16x16x32_bf16 v[114:117], v[154:157], v[202:205], v[114:117]
	v_mfma_f32_16x16x32_bf16 v[110:113], v[146:149], v[210:213], v[110:113]
	v_mfma_f32_16x16x32_bf16 v[106:109], v[154:157], v[210:213], v[106:109]
	v_mfma_f32_16x16x32_bf16 v[102:105], v[146:149], v[236:239], v[102:105]
	v_mfma_f32_16x16x32_bf16 v[98:101], v[154:157], v[236:239], v[98:101]
	v_mfma_f32_16x16x32_bf16 v[126:129], v[150:153], v[182:185], v[126:129]
	v_mfma_f32_16x16x32_bf16 v[122:125], v[158:161], v[182:185], v[122:125]
	v_mfma_f32_16x16x32_bf16 v[118:121], v[150:153], v[206:209], v[118:121]
	v_mfma_f32_16x16x32_bf16 v[114:117], v[158:161], v[206:209], v[114:117]
	v_mfma_f32_16x16x32_bf16 v[110:113], v[150:153], v[232:235], v[110:113]
	v_mfma_f32_16x16x32_bf16 v[106:109], v[158:161], v[232:235], v[106:109]
	v_mfma_f32_16x16x32_bf16 v[102:105], v[150:153], v[240:243], v[102:105]
	v_mfma_f32_16x16x32_bf16 v[98:101], v[158:161], v[240:243], v[98:101]
	s_setprio 0
	s_setprio 1
	v_mfma_f32_16x16x32_bf16 v[78:81], v[162:165], v[178:181], v[78:81]
	v_mfma_f32_16x16x32_bf16 v[70:73], v[170:173], v[178:181], v[70:73]
	v_mfma_f32_16x16x32_bf16 v[62:65], v[162:165], v[202:205], v[62:65]
	v_mfma_f32_16x16x32_bf16 v[54:57], v[170:173], v[202:205], v[54:57]
	v_mfma_f32_16x16x32_bf16 v[46:49], v[162:165], v[210:213], v[46:49]
	v_mfma_f32_16x16x32_bf16 v[42:45], v[170:173], v[210:213], v[42:45]
	v_mfma_f32_16x16x32_bf16 v[38:41], v[162:165], v[236:239], v[38:41]
	v_mfma_f32_16x16x32_bf16 v[34:37], v[170:173], v[236:239], v[34:37]
	v_mfma_f32_16x16x32_bf16 v[78:81], v[166:169], v[182:185], v[78:81]
	v_mfma_f32_16x16x32_bf16 v[70:73], v[174:177], v[182:185], v[70:73]
	v_mfma_f32_16x16x32_bf16 v[62:65], v[166:169], v[206:209], v[62:65]
	v_mfma_f32_16x16x32_bf16 v[54:57], v[174:177], v[206:209], v[54:57]
	v_mfma_f32_16x16x32_bf16 v[46:49], v[166:169], v[232:235], v[46:49]
	v_mfma_f32_16x16x32_bf16 v[42:45], v[174:177], v[232:235], v[42:45]
	v_mfma_f32_16x16x32_bf16 v[38:41], v[166:169], v[240:243], v[38:41]
	v_mfma_f32_16x16x32_bf16 v[34:37], v[174:177], v[240:243], v[34:37]
	s_setprio 0
	s_barrier
	s_add_i32 s22, s57, s38
	s_mov_b32 m0, s22
	ds_read_b128 v[178:181], v143 offset:49152
	ds_read_b128 v[182:185], v143 offset:50176
	ds_read_b128 v[202:205], v143 offset:51200
	ds_read_b128 v[206:209], v143 offset:52224
	ds_read_b128 v[210:213], v143 offset:53248
	ds_read_b128 v[232:235], v143 offset:54272
	ds_read_b128 v[236:239], v143 offset:55296
	ds_read_b128 v[240:243], v143 offset:56320
	global_load_lds_dwordx4 v134, s[60:61]
	s_add_i32 m0, s22, 0x2000
	s_add_u32 s22, s26, 0x20080
	s_addc_u32 s23, s27, 0
	s_add_i32 s26, s58, s38
	global_load_lds_dwordx4 v130, s[60:61]
	s_mov_b32 m0, s26
	s_nop 0
	global_load_lds_dwordx4 v134, s[22:23]
	s_add_i32 m0, s26, 0x2000
	s_nop 0
	global_load_lds_dwordx4 v130, s[22:23]
	s_mov_b32 m0, s43
	s_nop 0
	global_load_lds_dwordx4 v136, s[62:63]
	s_mov_b32 m0, s46
	s_nop 0
	global_load_lds_dwordx4 v132, s[62:63]
	s_waitcnt vmcnt(8) lgkmcnt(0)
	s_barrier
	s_setprio 1
	v_mfma_f32_16x16x32_bf16 v[94:97], v[146:149], v[178:181], v[94:97]
	v_mfma_f32_16x16x32_bf16 v[90:93], v[154:157], v[178:181], v[90:93]
	v_mfma_f32_16x16x32_bf16 v[86:89], v[146:149], v[202:205], v[86:89]
	v_mfma_f32_16x16x32_bf16 v[82:85], v[154:157], v[202:205], v[82:85]
	v_mfma_f32_16x16x32_bf16 v[74:77], v[146:149], v[210:213], v[74:77]
	v_mfma_f32_16x16x32_bf16 v[66:69], v[154:157], v[210:213], v[66:69]
	v_mfma_f32_16x16x32_bf16 v[58:61], v[146:149], v[236:239], v[58:61]
	v_mfma_f32_16x16x32_bf16 v[50:53], v[154:157], v[236:239], v[50:53]
	v_mfma_f32_16x16x32_bf16 v[94:97], v[150:153], v[182:185], v[94:97]
	v_mfma_f32_16x16x32_bf16 v[90:93], v[158:161], v[182:185], v[90:93]
	v_mfma_f32_16x16x32_bf16 v[86:89], v[150:153], v[206:209], v[86:89]
	v_mfma_f32_16x16x32_bf16 v[82:85], v[158:161], v[206:209], v[82:85]
	v_mfma_f32_16x16x32_bf16 v[74:77], v[150:153], v[232:235], v[74:77]
	v_mfma_f32_16x16x32_bf16 v[66:69], v[158:161], v[232:235], v[66:69]
	v_mfma_f32_16x16x32_bf16 v[58:61], v[150:153], v[240:243], v[58:61]
	v_mfma_f32_16x16x32_bf16 v[50:53], v[158:161], v[240:243], v[50:53]
	s_setprio 0
	s_setprio 1
	v_mfma_f32_16x16x32_bf16 v[30:33], v[162:165], v[178:181], v[30:33]
	v_mfma_f32_16x16x32_bf16 v[26:29], v[170:173], v[178:181], v[26:29]
	v_mfma_f32_16x16x32_bf16 v[22:25], v[162:165], v[202:205], v[22:25]
	v_mfma_f32_16x16x32_bf16 v[18:21], v[170:173], v[202:205], v[18:21]
	v_mfma_f32_16x16x32_bf16 v[14:17], v[162:165], v[210:213], v[14:17]
	v_mfma_f32_16x16x32_bf16 v[10:13], v[170:173], v[210:213], v[10:13]
	v_mfma_f32_16x16x32_bf16 v[6:9], v[162:165], v[236:239], v[6:9]
	v_mfma_f32_16x16x32_bf16 v[2:5], v[170:173], v[236:239], v[2:5]
	v_mfma_f32_16x16x32_bf16 v[30:33], v[166:169], v[182:185], v[30:33]
	v_mfma_f32_16x16x32_bf16 v[26:29], v[174:177], v[182:185], v[26:29]
	v_mfma_f32_16x16x32_bf16 v[22:25], v[166:169], v[206:209], v[22:25]
	v_mfma_f32_16x16x32_bf16 v[18:21], v[174:177], v[206:209], v[18:21]
	v_mfma_f32_16x16x32_bf16 v[14:17], v[166:169], v[232:235], v[14:17]
	v_mfma_f32_16x16x32_bf16 v[10:13], v[174:177], v[232:235], v[10:13]
	v_mfma_f32_16x16x32_bf16 v[6:9], v[166:169], v[240:243], v[6:9]
	v_mfma_f32_16x16x32_bf16 v[2:5], v[174:177], v[240:243], v[2:5]
	s_setprio 0
	s_barrier
	s_add_i32 s56, s56, 2
	s_add_u32 s54, s54, 0x100
	s_addc_u32 s55, s55, 0
	s_cmp_gt_u32 s56, 5
	s_mov_b64 s[22:23], s[24:25]
	s_cbranch_scc0 .LBB0_1160
	s_and_b64 vcc, exec, s[8:9]
	s_cbranch_vccz .LBB0_1163
	s_barrier

; #define PG8_STAGE(bufoff, gbase, voff) do { _Pragma("unroll") for (int _i = 0; _i < 2; ++_i) \
;         __builtin_amdgcn_global_load_lds((const unsigned*)((const char*)(gbase) + (voff)[_i]), (PG8_LAS unsigned*)(lds + (bufoff) + ldsw + _i * 8192), 16, 0, 0); } while (0)
; #define PG8_LDA(dst, b, h) do { _Pragma("unroll") for (int m = 0; m < 4; ++m) _Pragma("unroll") for (int k = 0; k < 2; ++k) dst[m][k] = *(const PG8_LAS bf16x8*)(lds + PG8_SA(b, h) + aoff + m * 2048 + k * 1024); } while (0)
; #define PG8_LDB(dst, b, h) do { _Pragma("unroll") for (int n = 0; n < 2; ++n) _Pragma("unroll") for (int k = 0; k < 2; ++k) dst[n][k] = *(const PG8_LAS bf16x8*)(lds + PG8_SB(b, h) + boff + n * 2048 + k * 1024); } while (0)
; template <class Epi, class Sched, bool ALIGN_EPI = false, bool SP2 = false>
; __device__ __forceinline__ void gemm_phase(PG8_LAS unsigned char* lds, const Gemm g, const Sched& S, const Epi& E) {
;     ...
;         for (int t = 0; t < nt; t += 2) {
;             const bool last = (t == nt - 2);
;             const char* a1 = cA + (size_t)(t + 1) * kstep;
;             const char* a2 = last ? nA : cA + (size_t)(t + 2) * kstep; const char* b2 = last ? nB : cB + (size_t)(t + 2) * kstep;
;             const char* a3 = a2 + kstep; const char* b3 = b2 + kstep;
;             if (last && has_next) S.a_ready(nxt);
;             if constexpr (SP2) {
;             PG8_LDB(B0, 0, 0); PG8_LDB(B1, 0, 1); PG8_SCHED; PG8_LDA(At, 0, 0); PG8_STAGE(PG8_SA(1, 1), a1 + hstepA, voffA);
;             PG8_WAIT_V(8); PG8_WAIT_L(0); PG8_BAR; PG8_MMA(0, 0, At, B0); PG8_MMA(0, 1, At, B1); PG8_BAR; PG8_SCHED;
;             PG8_LDA(At, 0, 1); PG8_STAGE(PG8_SB(0, 0), b2, voffB); PG8_STAGE(PG8_SB(0, 1), b2 + hstepB, voffB); PG8_STAGE(PG8_SA(0, 0), a2, voffA);
;             PG8_WAIT_V(8); PG8_WAIT_L(0); PG8_BAR; PG8_MMA(1, 0, At, B0); PG8_MMA(1, 1, At, B1); PG8_BAR; PG8_SCHED;
;             PG8_LDB(B0, 1, 0); PG8_LDB(B1, 1, 1); PG8_SCHED; PG8_LDA(At, 1, 0); PG8_STAGE(PG8_SA(0, 1), a2 + hstepA, voffA);
;             PG8_WAIT_V(8); PG8_WAIT_L(0); PG8_BAR; PG8_MMA(0, 0, At, B0); PG8_MMA(0, 1, At, B1); PG8_BAR; PG8_SCHED;
;             PG8_LDA(At, 1, 1); PG8_STAGE(PG8_SB(1, 0), b3, voffB); PG8_STAGE(PG8_SB(1, 1), b3 + hstepB, voffB); PG8_STAGE(PG8_SA(1, 0), a3, voffA);
;             PG8_WAIT_V(8); PG8_WAIT_L(0); PG8_BAR; PG8_MMA(1, 0, At, B0); PG8_MMA(1, 1, At, B1); PG8_BAR; PG8_SCHED;
.LBB0_1176:
	s_add_u32 s35, s26, s34
	s_addc_u32 s40, s27, 0
	s_add_u32 s38, s35, 0x100
	s_addc_u32 s39, s40, 0
	s_and_b64 s[36:37], s[30:31], exec
	s_cselect_b32 s37, s19, s39
	s_cselect_b32 s36, s18, s38
	s_add_u32 s34, s24, s34
	s_addc_u32 s38, s25, 0
	s_add_u32 s34, s34, 0x100
	s_addc_u32 s38, s38, 0
	s_add_i32 s72, 0, 0x10000
	s_and_b64 s[30:31], s[30:31], exec
	s_cselect_b32 s39, s61, s38
	s_cselect_b32 s38, s62, s34
	s_add_i32 s31, 0, 0x14000
	s_add_u32 s42, s35, 0x30080
	s_addc_u32 s43, s40, 0
	s_add_i32 s71, s72, s50
	s_add_i32 m0, s51, 0xc000
	s_add_i32 s74, s51, 0xe000
	s_add_i32 s67, s71, 0x2000
	v_add_u32_e32 v141, s72, v138
	s_add_u32 s40, s38, 0x10000
	ds_read_b128 v[142:145], v141
	ds_read_b128 v[146:149], v141 offset:1024
	ds_read_b128 v[150:153], v141 offset:2048
	ds_read_b128 v[154:157], v141 offset:3072
	v_add_u32_e32 v141, s31, v138
	s_addc_u32 s41, s39, 0
	s_add_i32 s69, s31, s50
	ds_read_b128 v[158:161], v141
	ds_read_b128 v[162:165], v141 offset:1024
	ds_read_b128 v[166:169], v141 offset:2048
	ds_read_b128 v[170:173], v141 offset:3072
	s_add_i32 s68, s69, 0x2000
	s_add_i32 s66, 0, 0x18000
	s_add_i32 s65, 0, 0x1c000
	s_add_u32 s34, s36, 0x30000
	s_addc_u32 s35, s37, 0
	s_add_i32 s64, s66, s50
	s_add_i32 s63, s64, 0x2000
	s_add_u32 s30, s38, 0x10080
	s_addc_u32 s31, s39, 0
	s_add_i32 s73, s65, s50
	s_add_i32 s72, s73, 0x2000
	v_lshl_add_u64 v[186:187], s[42:43], 0, v[136:137]
	ds_read_b128 v[174:177], v140
	ds_read_b128 v[178:181], v140 offset:1024
	ds_read_b128 v[182:185], v140 offset:2048
	ds_read_b128 v[202:205], v140 offset:3072
	ds_read_b128 v[206:209], v140 offset:4096
	ds_read_b128 v[210:213], v140 offset:5120
	ds_read_b128 v[232:235], v140 offset:6144
	ds_read_b128 v[236:239], v140 offset:7168
	global_load_lds_dwordx4 v[186:187], off
	v_lshl_add_u64 v[186:187], s[42:43], 0, v[132:133]
	s_mov_b32 m0, s74
	s_nop 0
	global_load_lds_dwordx4 v[186:187], off
	s_waitcnt vmcnt(8) lgkmcnt(0)
	s_barrier
	s_setprio 1
	v_mfma_f32_16x16x32_bf16 v[126:129], v[142:145], v[174:177], v[126:129]
	v_mfma_f32_16x16x32_bf16 v[122:125], v[150:153], v[174:177], v[122:125]
	v_mfma_f32_16x16x32_bf16 v[118:121], v[142:145], v[182:185], v[118:121]
	v_mfma_f32_16x16x32_bf16 v[114:117], v[150:153], v[182:185], v[114:117]
	v_mfma_f32_16x16x32_bf16 v[110:113], v[142:145], v[206:209], v[110:113]
	v_mfma_f32_16x16x32_bf16 v[106:109], v[150:153], v[206:209], v[106:109]
	v_mfma_f32_16x16x32_bf16 v[102:105], v[142:145], v[232:235], v[102:105]
	v_mfma_f32_16x16x32_bf16 v[98:101], v[150:153], v[232:235], v[98:101]
	v_mfma_f32_16x16x32_bf16 v[126:129], v[146:149], v[178:181], v[126:129]
	v_mfma_f32_16x16x32_bf16 v[122:125], v[154:157], v[178:181], v[122:125]
	v_mfma_f32_16x16x32_bf16 v[118:121], v[146:149], v[202:205], v[118:121]
	v_mfma_f32_16x16x32_bf16 v[114:117], v[154:157], v[202:205], v[114:117]
	v_mfma_f32_16x16x32_bf16 v[110:113], v[146:149], v[210:213], v[110:113]
	v_mfma_f32_16x16x32_bf16 v[106:109], v[154:157], v[210:213], v[106:109]
	v_mfma_f32_16x16x32_bf16 v[102:105], v[146:149], v[236:239], v[102:105]
	v_mfma_f32_16x16x32_bf16 v[98:101], v[154:157], v[236:239], v[98:101]
	s_setprio 0
	s_setprio 1
	v_mfma_f32_16x16x32_bf16 v[78:81], v[158:161], v[174:177], v[78:81]
	v_mfma_f32_16x16x32_bf16 v[70:73], v[166:169], v[174:177], v[70:73]
	v_mfma_f32_16x16x32_bf16 v[62:65], v[158:161], v[182:185], v[62:65]
	v_mfma_f32_16x16x32_bf16 v[54:57], v[166:169], v[182:185], v[54:57]
	v_mfma_f32_16x16x32_bf16 v[46:49], v[158:161], v[206:209], v[46:49]
	v_mfma_f32_16x16x32_bf16 v[42:45], v[166:169], v[206:209], v[42:45]
	v_mfma_f32_16x16x32_bf16 v[38:41], v[158:161], v[232:235], v[38:41]
	v_mfma_f32_16x16x32_bf16 v[34:37], v[166:169], v[232:235], v[34:37]
	v_mfma_f32_16x16x32_bf16 v[78:81], v[162:165], v[178:181], v[78:81]
	v_mfma_f32_16x16x32_bf16 v[70:73], v[170:173], v[178:181], v[70:73]
	v_mfma_f32_16x16x32_bf16 v[62:65], v[162:165], v[202:205], v[62:65]
	v_mfma_f32_16x16x32_bf16 v[54:57], v[170:173], v[202:205], v[54:57]
	v_mfma_f32_16x16x32_bf16 v[46:49], v[162:165], v[210:213], v[46:49]
	v_mfma_f32_16x16x32_bf16 v[42:45], v[170:173], v[210:213], v[42:45]
	v_mfma_f32_16x16x32_bf16 v[38:41], v[162:165], v[236:239], v[38:41]
	v_mfma_f32_16x16x32_bf16 v[34:37], v[170:173], v[236:239], v[34:37]
	s_setprio 0
	s_barrier
	s_mov_b32 m0, s71
	v_lshl_add_u64 v[186:187], s[38:39], 0, v[134:135]
	ds_read_b128 v[174:177], v140 offset:16384
	ds_read_b128 v[178:181], v140 offset:17408
	ds_read_b128 v[182:185], v140 offset:18432
	ds_read_b128 v[202:205], v140 offset:19456
	ds_read_b128 v[206:209], v140 offset:20480
	ds_read_b128 v[210:213], v140 offset:21504
	ds_read_b128 v[232:235], v140 offset:22528
	ds_read_b128 v[236:239], v140 offset:23552
	global_load_lds_dwordx4 v[186:187], off
	v_lshl_add_u64 v[214:215], s[38:39], 0, v[130:131]
	s_mov_b32 m0, s67
	v_lshl_add_u64 v[240:241], s[40:41], 0, v[134:135]
	global_load_lds_dwordx4 v[214:215], off
	s_mov_b32 m0, s69
	v_lshl_add_u64 v[242:243], s[36:37], 0, v[132:133]
	global_load_lds_dwordx4 v[240:241], off
	v_lshl_add_u64 v[240:241], s[40:41], 0, v[130:131]
	s_mov_b32 m0, s68
	s_nop 0
	global_load_lds_dwordx4 v[240:241], off
	v_lshl_add_u64 v[240:241], s[36:37], 0, v[136:137]
	s_mov_b32 m0, s51
	s_nop 0
	global_load_lds_dwordx4 v[240:241], off
	s_mov_b32 m0, s52
	s_nop 0
	global_load_lds_dwordx4 v[242:243], off
	s_waitcnt vmcnt(8) lgkmcnt(0)
	s_barrier
; #define PG8_STAGE(bufoff, gbase, voff) do { _Pragma("unroll") for (int _i = 0; _i < 2; ++_i) \
;         __builtin_amdgcn_global_load_lds((const unsigned*)((const char*)(gbase) + (voff)[_i]), (PG8_LAS unsigned*)(lds + (bufoff) + ldsw + _i * 8192), 16, 0, 0); } while (0)
; #define PG8_LDA(dst, b, h) do { _Pragma("unroll") for (int m = 0; m < 4; ++m) _Pragma("unroll") for (int k = 0; k < 2; ++k) dst[m][k] = *(const PG8_LAS bf16x8*)(lds + PG8_SA(b, h) + aoff + m * 2048 + k * 1024); } while (0)
; #define PG8_LDB(dst, b, h) do { _Pragma("unroll") for (int n = 0; n < 2; ++n) _Pragma("unroll") for (int k = 0; k < 2; ++k) dst[n][k] = *(const PG8_LAS bf16x8*)(lds + PG8_SB(b, h) + boff + n * 2048 + k * 1024); } while (0)
; #define PG8_MMA(ai, bj, At, Bt) do { __builtin_amdgcn_s_setprio(1); _Pragma("unroll") for (int m = 0; m < 4; ++m) _Pragma("unroll") for (int n = 0; n < 2; ++n) _Pragma("unroll") for (int k = 0; k < 2; ++k) \
;         acc[ai][bj][m][n] = __builtin_amdgcn_mfma_f32_16x16x32_bf16(Bt[n][k], At[m][k], acc[ai][bj][m][n], 0, 0, 0); __builtin_amdgcn_s_setprio(0); } while (0)
; #define PG8_WAIT_V(n) asm volatile("s_waitcnt vmcnt(" #n ")" ::: "memory")
; template <class Epi, class Sched, bool ALIGN_EPI = false, bool SP2 = false>
; __device__ __forceinline__ void gemm_phase(PG8_LAS unsigned char* lds, const Gemm g, const Sched& S, const Epi& E) {
;     ...
;             PG8_LDB(B0, 0, 0); PG8_LDB(B1, 0, 1); PG8_SCHED; PG8_LDA(At, 0, 0); PG8_STAGE(PG8_SA(1, 1), a1 + hstepA, voffA);
;             PG8_WAIT_V(8); PG8_WAIT_L(0); PG8_BAR; PG8_MMA(0, 0, At, B0); PG8_MMA(0, 1, At, B1); PG8_BAR; PG8_SCHED;
;             PG8_LDA(At, 0, 1); PG8_STAGE(PG8_SB(0, 0), b2, voffB); PG8_STAGE(PG8_SB(0, 1), b2 + hstepB, voffB); PG8_STAGE(PG8_SA(0, 0), a2, voffA);
;             PG8_WAIT_V(8); PG8_WAIT_L(0); PG8_BAR; PG8_MMA(1, 0, At, B0); PG8_MMA(1, 1, At, B1); PG8_BAR; PG8_SCHED;
;             PG8_LDB(B0, 1, 0); PG8_LDB(B1, 1, 1); PG8_SCHED; PG8_LDA(At, 1, 0); PG8_STAGE(PG8_SA(0, 1), a2 + hstepA, voffA);
;             PG8_WAIT_V(8); PG8_WAIT_L(0); PG8_BAR; PG8_MMA(0, 0, At, B0); PG8_MMA(0, 1, At, B1); PG8_BAR; PG8_SCHED;
;             PG8_LDA(At, 1, 1); PG8_STAGE(PG8_SB(1, 0), b3, voffB); PG8_STAGE(PG8_SB(1, 1), b3 + hstepB, voffB); PG8_STAGE(PG8_SA(1, 0), a3, voffA);
;             PG8_WAIT_V(8); PG8_WAIT_L(0); PG8_BAR; PG8_MMA(1, 0, At, B0); PG8_MMA(1, 1, At, B1); PG8_BAR; PG8_SCHED;
	s_setprio 1
	v_mfma_f32_16x16x32_bf16 v[94:97], v[142:145], v[174:177], v[94:97]
	v_mfma_f32_16x16x32_bf16 v[90:93], v[150:153], v[174:177], v[90:93]
	v_mfma_f32_16x16x32_bf16 v[86:89], v[142:145], v[182:185], v[86:89]
	v_mfma_f32_16x16x32_bf16 v[82:85], v[150:153], v[182:185], v[82:85]
	v_mfma_f32_16x16x32_bf16 v[74:77], v[142:145], v[206:209], v[74:77]
	v_mfma_f32_16x16x32_bf16 v[66:69], v[150:153], v[206:209], v[66:69]
	v_mfma_f32_16x16x32_bf16 v[58:61], v[142:145], v[232:235], v[58:61]
	v_mfma_f32_16x16x32_bf16 v[50:53], v[150:153], v[232:235], v[50:53]
	v_mfma_f32_16x16x32_bf16 v[94:97], v[146:149], v[178:181], v[94:97]
	v_mfma_f32_16x16x32_bf16 v[90:93], v[154:157], v[178:181], v[90:93]
	v_mfma_f32_16x16x32_bf16 v[86:89], v[146:149], v[202:205], v[86:89]
	v_mfma_f32_16x16x32_bf16 v[82:85], v[154:157], v[202:205], v[82:85]
	v_mfma_f32_16x16x32_bf16 v[74:77], v[146:149], v[210:213], v[74:77]
	v_mfma_f32_16x16x32_bf16 v[66:69], v[154:157], v[210:213], v[66:69]
	v_mfma_f32_16x16x32_bf16 v[58:61], v[146:149], v[236:239], v[58:61]
	v_mfma_f32_16x16x32_bf16 v[50:53], v[154:157], v[236:239], v[50:53]
	s_setprio 0
	s_setprio 1
	v_mfma_f32_16x16x32_bf16 v[30:33], v[158:161], v[174:177], v[30:33]
	v_mfma_f32_16x16x32_bf16 v[26:29], v[166:169], v[174:177], v[26:29]
	v_mfma_f32_16x16x32_bf16 v[22:25], v[158:161], v[182:185], v[22:25]
	v_mfma_f32_16x16x32_bf16 v[18:21], v[166:169], v[182:185], v[18:21]
	v_mfma_f32_16x16x32_bf16 v[14:17], v[158:161], v[206:209], v[14:17]
	v_mfma_f32_16x16x32_bf16 v[10:13], v[166:169], v[206:209], v[10:13]
	v_mfma_f32_16x16x32_bf16 v[6:9], v[158:161], v[232:235], v[6:9]
	v_mfma_f32_16x16x32_bf16 v[2:5], v[166:169], v[232:235], v[2:5]
	v_mfma_f32_16x16x32_bf16 v[30:33], v[162:165], v[178:181], v[30:33]
	v_mfma_f32_16x16x32_bf16 v[26:29], v[170:173], v[178:181], v[26:29]
	v_mfma_f32_16x16x32_bf16 v[22:25], v[162:165], v[202:205], v[22:25]
	v_mfma_f32_16x16x32_bf16 v[18:21], v[170:173], v[202:205], v[18:21]
	v_mfma_f32_16x16x32_bf16 v[14:17], v[162:165], v[210:213], v[14:17]
	v_mfma_f32_16x16x32_bf16 v[10:13], v[170:173], v[210:213], v[10:13]
	v_mfma_f32_16x16x32_bf16 v[6:9], v[162:165], v[236:239], v[6:9]
	v_mfma_f32_16x16x32_bf16 v[2:5], v[170:173], v[236:239], v[2:5]
	s_setprio 0
	s_barrier
	v_add_u32_e32 v141, s66, v138
	ds_read_b128 v[142:145], v141
	ds_read_b128 v[146:149], v141 offset:1024
	ds_read_b128 v[150:153], v141 offset:2048
	ds_read_b128 v[154:157], v141 offset:3072
	v_add_u32_e32 v141, s65, v138
	ds_read_b128 v[158:161], v141
	ds_read_b128 v[162:165], v141 offset:1024
	ds_read_b128 v[166:169], v141 offset:2048
	ds_read_b128 v[170:173], v141 offset:3072
	s_mov_b32 m0, s53
	v_lshl_add_u64 v[244:245], s[34:35], 0, v[136:137]
	ds_read_b128 v[174:177], v140 offset:32768
	ds_read_b128 v[178:181], v140 offset:33792
	ds_read_b128 v[182:185], v140 offset:34816
	ds_read_b128 v[202:205], v140 offset:35840
	ds_read_b128 v[206:209], v140 offset:36864
	ds_read_b128 v[210:213], v140 offset:37888
	ds_read_b128 v[232:235], v140 offset:38912
	ds_read_b128 v[236:239], v140 offset:39936
	global_load_lds_dwordx4 v[244:245], off
	v_lshl_add_u64 v[244:245], s[34:35], 0, v[132:133]
	s_mov_b32 m0, s54
	s_nop 0
	global_load_lds_dwordx4 v[244:245], off
	s_waitcnt vmcnt(8) lgkmcnt(0)
	s_barrier
	s_setprio 1
	v_mfma_f32_16x16x32_bf16 v[126:129], v[142:145], v[174:177], v[126:129]
	v_mfma_f32_16x16x32_bf16 v[122:125], v[150:153], v[174:177], v[122:125]
	v_mfma_f32_16x16x32_bf16 v[118:121], v[142:145], v[182:185], v[118:121]
	v_mfma_f32_16x16x32_bf16 v[114:117], v[150:153], v[182:185], v[114:117]
	v_mfma_f32_16x16x32_bf16 v[110:113], v[142:145], v[206:209], v[110:113]
	v_mfma_f32_16x16x32_bf16 v[106:109], v[150:153], v[206:209], v[106:109]
	v_mfma_f32_16x16x32_bf16 v[102:105], v[142:145], v[232:235], v[102:105]
	v_mfma_f32_16x16x32_bf16 v[98:101], v[150:153], v[232:235], v[98:101]
	v_mfma_f32_16x16x32_bf16 v[126:129], v[146:149], v[178:181], v[126:129]
	v_mfma_f32_16x16x32_bf16 v[122:125], v[154:157], v[178:181], v[122:125]
	v_mfma_f32_16x16x32_bf16 v[118:121], v[146:149], v[202:205], v[118:121]
	v_mfma_f32_16x16x32_bf16 v[114:117], v[154:157], v[202:205], v[114:117]
	v_mfma_f32_16x16x32_bf16 v[110:113], v[146:149], v[210:213], v[110:113]
	v_mfma_f32_16x16x32_bf16 v[106:109], v[154:157], v[210:213], v[106:109]
	v_mfma_f32_16x16x32_bf16 v[102:105], v[146:149], v[236:239], v[102:105]
	v_mfma_f32_16x16x32_bf16 v[98:101], v[154:157], v[236:239], v[98:101]
	s_setprio 0
	s_setprio 1
	v_mfma_f32_16x16x32_bf16 v[78:81], v[158:161], v[174:177], v[78:81]
	v_mfma_f32_16x16x32_bf16 v[70:73], v[166:169], v[174:177], v[70:73]
	v_mfma_f32_16x16x32_bf16 v[62:65], v[158:161], v[182:185], v[62:65]
	v_mfma_f32_16x16x32_bf16 v[54:57], v[166:169], v[182:185], v[54:57]
	v_mfma_f32_16x16x32_bf16 v[46:49], v[158:161], v[206:209], v[46:49]
	v_mfma_f32_16x16x32_bf16 v[42:45], v[166:169], v[206:209], v[42:45]
	v_mfma_f32_16x16x32_bf16 v[38:41], v[158:161], v[232:235], v[38:41]
	v_mfma_f32_16x16x32_bf16 v[34:37], v[166:169], v[232:235], v[34:37]
	v_mfma_f32_16x16x32_bf16 v[78:81], v[162:165], v[178:181], v[78:81]
	v_mfma_f32_16x16x32_bf16 v[70:73], v[170:173], v[178:181], v[70:73]
	v_mfma_f32_16x16x32_bf16 v[62:65], v[162:165], v[202:205], v[62:65]
	v_mfma_f32_16x16x32_bf16 v[54:57], v[170:173], v[202:205], v[54:57]
	v_mfma_f32_16x16x32_bf16 v[46:49], v[162:165], v[210:213], v[46:49]
	v_mfma_f32_16x16x32_bf16 v[42:45], v[170:173], v[210:213], v[42:45]
	v_mfma_f32_16x16x32_bf16 v[38:41], v[162:165], v[236:239], v[38:41]
	v_mfma_f32_16x16x32_bf16 v[34:37], v[170:173], v[236:239], v[34:37]
	s_setprio 0
	s_barrier
; #define PG8_STAGE(bufoff, gbase, voff) do { _Pragma("unroll") for (int _i = 0; _i < 2; ++_i) \
;         __builtin_amdgcn_global_load_lds((const unsigned*)((const char*)(gbase) + (voff)[_i]), (PG8_LAS unsigned*)(lds + (bufoff) + ldsw + _i * 8192), 16, 0, 0); } while (0)
; #define PG8_LDA(dst, b, h) do { _Pragma("unroll") for (int m = 0; m < 4; ++m) _Pragma("unroll") for (int k = 0; k < 2; ++k) dst[m][k] = *(const PG8_LAS bf16x8*)(lds + PG8_SA(b, h) + aoff + m * 2048 + k * 1024); } while (0)
; #define PG8_LDB(dst, b, h) do { _Pragma("unroll") for (int n = 0; n < 2; ++n) _Pragma("unroll") for (int k = 0; k < 2; ++k) dst[n][k] = *(const PG8_LAS bf16x8*)(lds + PG8_SB(b, h) + boff + n * 2048 + k * 1024); } while (0)
; #define PG8_MMA(ai, bj, At, Bt) do { __builtin_amdgcn_s_setprio(1); _Pragma("unroll") for (int m = 0; m < 4; ++m) _Pragma("unroll") for (int n = 0; n < 2; ++n) _Pragma("unroll") for (int k = 0; k < 2; ++k) \
;         acc[ai][bj][m][n] = __builtin_amdgcn_mfma_f32_16x16x32_bf16(Bt[n][k], At[m][k], acc[ai][bj][m][n], 0, 0, 0); __builtin_amdgcn_s_setprio(0); } while (0)
; template <class Epi, class Sched, bool ALIGN_EPI = false, bool SP2 = false>
; __device__ __forceinline__ void gemm_phase(PG8_LAS unsigned char* lds, const Gemm g, const Sched& S, const Epi& E) {
;     ...
;         for (int t = 0; t < nt; t += 2) {
;     ...
;             PG8_LDB(B0, 0, 0); PG8_LDB(B1, 0, 1); PG8_SCHED; PG8_LDA(At, 0, 0); PG8_STAGE(PG8_SA(1, 1), a1 + hstepA, voffA);
;             PG8_WAIT_V(8); PG8_WAIT_L(0); PG8_BAR; PG8_MMA(0, 0, At, B0); PG8_MMA(0, 1, At, B1); PG8_BAR; PG8_SCHED;
;             PG8_LDA(At, 0, 1); PG8_STAGE(PG8_SB(0, 0), b2, voffB); PG8_STAGE(PG8_SB(0, 1), b2 + hstepB, voffB); PG8_STAGE(PG8_SA(0, 0), a2, voffA);
;             PG8_WAIT_V(8); PG8_WAIT_L(0); PG8_BAR; PG8_MMA(1, 0, At, B0); PG8_MMA(1, 1, At, B1); PG8_BAR; PG8_SCHED;
;             PG8_LDB(B0, 1, 0); PG8_LDB(B1, 1, 1); PG8_SCHED; PG8_LDA(At, 1, 0); PG8_STAGE(PG8_SA(0, 1), a2 + hstepA, voffA);
;             PG8_WAIT_V(8); PG8_WAIT_L(0); PG8_BAR; PG8_MMA(0, 0, At, B0); PG8_MMA(0, 1, At, B1); PG8_BAR; PG8_SCHED;
;             PG8_LDA(At, 1, 1); PG8_STAGE(PG8_SB(1, 0), b3, voffB); PG8_STAGE(PG8_SB(1, 1), b3 + hstepB, voffB); PG8_STAGE(PG8_SA(1, 0), a3, voffA);
;             PG8_WAIT_V(8); PG8_WAIT_L(0); PG8_BAR; PG8_MMA(1, 0, At, B0); PG8_MMA(1, 1, At, B1); PG8_BAR; PG8_SCHED;
	s_mov_b32 m0, s64
	v_lshl_add_u64 v[186:187], v[186:187], 0, s[96:97]
	ds_read_b128 v[174:177], v140 offset:49152
	ds_read_b128 v[178:181], v140 offset:50176
	ds_read_b128 v[182:185], v140 offset:51200
	ds_read_b128 v[202:205], v140 offset:52224
	ds_read_b128 v[206:209], v140 offset:53248
	ds_read_b128 v[210:213], v140 offset:54272
	ds_read_b128 v[232:235], v140 offset:55296
	ds_read_b128 v[236:239], v140 offset:56320
	global_load_lds_dwordx4 v[186:187], off
	v_lshl_add_u64 v[186:187], v[214:215], 0, s[96:97]
	s_mov_b32 m0, s63
	s_nop 0
	global_load_lds_dwordx4 v[186:187], off
	v_lshl_add_u64 v[186:187], s[30:31], 0, v[134:135]
	s_mov_b32 m0, s73
	s_nop 0
	global_load_lds_dwordx4 v[186:187], off
	v_lshl_add_u64 v[186:187], s[30:31], 0, v[130:131]
	s_mov_b32 m0, s72
	s_nop 0
	global_load_lds_dwordx4 v[186:187], off
	v_lshl_add_u64 v[186:187], v[240:241], 0, s[96:97]
	s_mov_b32 m0, s55
	s_nop 0
	global_load_lds_dwordx4 v[186:187], off
	v_lshl_add_u64 v[186:187], v[242:243], 0, s[96:97]
	s_mov_b32 m0, s56
	s_nop 0
	global_load_lds_dwordx4 v[186:187], off
	s_waitcnt vmcnt(8) lgkmcnt(0)
	s_barrier
	s_setprio 1
	v_mfma_f32_16x16x32_bf16 v[94:97], v[142:145], v[174:177], v[94:97]
	v_mfma_f32_16x16x32_bf16 v[90:93], v[150:153], v[174:177], v[90:93]
	v_mfma_f32_16x16x32_bf16 v[86:89], v[142:145], v[182:185], v[86:89]
	v_mfma_f32_16x16x32_bf16 v[82:85], v[150:153], v[182:185], v[82:85]
	v_mfma_f32_16x16x32_bf16 v[74:77], v[142:145], v[206:209], v[74:77]
	v_mfma_f32_16x16x32_bf16 v[66:69], v[150:153], v[206:209], v[66:69]
	v_mfma_f32_16x16x32_bf16 v[58:61], v[142:145], v[232:235], v[58:61]
	v_mfma_f32_16x16x32_bf16 v[50:53], v[150:153], v[232:235], v[50:53]
	v_mfma_f32_16x16x32_bf16 v[94:97], v[146:149], v[178:181], v[94:97]
	v_mfma_f32_16x16x32_bf16 v[90:93], v[154:157], v[178:181], v[90:93]
	v_mfma_f32_16x16x32_bf16 v[86:89], v[146:149], v[202:205], v[86:89]
	v_mfma_f32_16x16x32_bf16 v[82:85], v[154:157], v[202:205], v[82:85]
	v_mfma_f32_16x16x32_bf16 v[74:77], v[146:149], v[210:213], v[74:77]
	v_mfma_f32_16x16x32_bf16 v[66:69], v[154:157], v[210:213], v[66:69]
	v_mfma_f32_16x16x32_bf16 v[58:61], v[146:149], v[236:239], v[58:61]
	v_mfma_f32_16x16x32_bf16 v[50:53], v[154:157], v[236:239], v[50:53]
	s_setprio 0
	s_setprio 1
	v_mfma_f32_16x16x32_bf16 v[30:33], v[158:161], v[174:177], v[30:33]
	v_mfma_f32_16x16x32_bf16 v[26:29], v[166:169], v[174:177], v[26:29]
	v_mfma_f32_16x16x32_bf16 v[22:25], v[158:161], v[182:185], v[22:25]
	v_mfma_f32_16x16x32_bf16 v[18:21], v[166:169], v[182:185], v[18:21]
	v_mfma_f32_16x16x32_bf16 v[14:17], v[158:161], v[206:209], v[14:17]
	v_mfma_f32_16x16x32_bf16 v[10:13], v[166:169], v[206:209], v[10:13]
	v_mfma_f32_16x16x32_bf16 v[6:9], v[158:161], v[232:235], v[6:9]
	v_mfma_f32_16x16x32_bf16 v[2:5], v[166:169], v[232:235], v[2:5]
	v_mfma_f32_16x16x32_bf16 v[30:33], v[162:165], v[178:181], v[30:33]
	v_mfma_f32_16x16x32_bf16 v[26:29], v[170:173], v[178:181], v[26:29]
	v_mfma_f32_16x16x32_bf16 v[22:25], v[162:165], v[202:205], v[22:25]
	v_mfma_f32_16x16x32_bf16 v[18:21], v[170:173], v[202:205], v[18:21]
	v_mfma_f32_16x16x32_bf16 v[14:17], v[162:165], v[210:213], v[14:17]
	v_mfma_f32_16x16x32_bf16 v[10:13], v[170:173], v[210:213], v[10:13]
	v_mfma_f32_16x16x32_bf16 v[6:9], v[162:165], v[236:239], v[6:9]
	v_mfma_f32_16x16x32_bf16 v[2:5], v[170:173], v[236:239], v[2:5]
	s_setprio 0
	s_barrier
	s_movk_i32 s34, 0x100
	s_andn2_b64 vcc, exec, s[28:29]
	s_mov_b64 s[30:31], -1
	s_mov_b64 s[28:29], 0
	s_cbranch_vccz .LBB0_1176
	s_and_b64 vcc, exec, s[16:17]
	s_cbranch_vccz .LBB0_1179
	s_barrier

; #define PG8_STAGE(bufoff, gbase, voff) do { _Pragma("unroll") for (int _i = 0; _i < 2; ++_i) \
;         __builtin_amdgcn_global_load_lds((const unsigned*)((const char*)(gbase) + (voff)[_i]), (PG8_LAS unsigned*)(lds + (bufoff) + ldsw + _i * 8192), 16, 0, 0); } while (0)
; #define PG8_LDA(dst, b, h) do { _Pragma("unroll") for (int m = 0; m < 4; ++m) _Pragma("unroll") for (int k = 0; k < 2; ++k) dst[m][k] = *(const PG8_LAS bf16x8*)(lds + PG8_SA(b, h) + aoff + m * 2048 + k * 1024); } while (0)
; #define PG8_LDB(dst, b, h) do { _Pragma("unroll") for (int n = 0; n < 2; ++n) _Pragma("unroll") for (int k = 0; k < 2; ++k) dst[n][k] = *(const PG8_LAS bf16x8*)(lds + PG8_SB(b, h) + boff + n * 2048 + k * 1024); } while (0)
; #define PG8_BAR __builtin_amdgcn_s_barrier()
; template <class Epi, class Sched, bool ALIGN_EPI = false, bool SP2 = false>
; __device__ __forceinline__ void gemm_phase(PG8_LAS unsigned char* lds, const Gemm g, const Sched& S, const Epi& E) {
;     ...
;             const bool last = (t == nt - 2);
;             const char* a1 = cA + (size_t)(t + 1) * kstep;
;             const char* a2 = last ? nA : cA + (size_t)(t + 2) * kstep; const char* b2 = last ? nB : cB + (size_t)(t + 2) * kstep;
;             const char* a3 = a2 + kstep; const char* b3 = b2 + kstep;
;             if (last && has_next) S.a_ready(nxt);
;             if constexpr (SP2) {
;             PG8_LDB(B0, 0, 0); PG8_LDB(B1, 0, 1); PG8_SCHED; PG8_LDA(At, 0, 0); PG8_STAGE(PG8_SA(1, 1), a1 + hstepA, voffA);
;             PG8_WAIT_V(8); PG8_WAIT_L(0); PG8_BAR; PG8_MMA(0, 0, At, B0); PG8_MMA(0, 1, At, B1); PG8_BAR; PG8_SCHED;
;             PG8_LDA(At, 0, 1); PG8_STAGE(PG8_SB(0, 0), b2, voffB); PG8_STAGE(PG8_SB(0, 1), b2 + hstepB, voffB); PG8_STAGE(PG8_SA(0, 0), a2, voffA);
;             PG8_WAIT_V(8); PG8_WAIT_L(0); PG8_BAR; PG8_MMA(1, 0, At, B0); PG8_MMA(1, 1, At, B1); PG8_BAR; PG8_SCHED;
;             PG8_LDB(B0, 1, 0); PG8_LDB(B1, 1, 1); PG8_SCHED; PG8_LDA(At, 1, 0); PG8_STAGE(PG8_SA(0, 1), a2 + hstepA, voffA);
;             PG8_WAIT_V(8); PG8_WAIT_L(0); PG8_BAR; PG8_MMA(0, 0, At, B0); PG8_MMA(0, 1, At, B1); PG8_BAR; PG8_SCHED;
;             PG8_LDA(At, 1, 1); PG8_STAGE(PG8_SB(1, 0), b3, voffB); PG8_STAGE(PG8_SB(1, 1), b3 + hstepB, voffB); PG8_STAGE(PG8_SA(1, 0), a3, voffA);
;             PG8_WAIT_V(8); PG8_WAIT_L(0); PG8_BAR; PG8_MMA(1, 0, At, B0); PG8_MMA(1, 1, At, B1); PG8_BAR; PG8_SCHED;
.LBB0_1190:
	s_add_u32 s24, s22, 0xfffc0080
	s_addc_u32 s25, s23, -1
	s_add_i32 s51, 0, 0x10000
	s_cmp_eq_u32 s50, 12
	s_cselect_b32 s27, s44, s25
	s_cselect_b32 s26, s45, s24
	s_cselect_b32 s25, s46, s49
	s_cselect_b32 s24, s47, s48
	s_add_i32 s54, 0, 0x14000
	v_add_u32_e32 v142, s51, v168
	v_add_u32_e32 v166, s54, v168
	ds_read_b128 v[130:133], v142
	ds_read_b128 v[134:137], v142 offset:1024
	ds_read_b128 v[138:141], v142 offset:2048
	ds_read_b128 v[142:145], v142 offset:3072
	ds_read_b128 v[158:161], v166
	ds_read_b128 v[162:165], v166 offset:1024
	ds_read_b128 v[172:175], v166 offset:2048
	ds_read_b128 v[176:179], v166 offset:3072
	s_add_i32 m0, s7, 0xc000
	ds_read_b128 v[180:183], v171
	ds_read_b128 v[184:187], v171 offset:1024
	ds_read_b128 v[202:205], v171 offset:2048
	ds_read_b128 v[206:209], v171 offset:3072
	ds_read_b128 v[210:213], v171 offset:4096
	ds_read_b128 v[232:235], v171 offset:5120
	ds_read_b128 v[236:239], v171 offset:6144
	ds_read_b128 v[240:243], v171 offset:7168
	global_load_lds_dwordx4 v154, s[22:23]
	s_add_i32 m0, s7, 0xe000
	s_nop 0
	global_load_lds_dwordx4 v156, s[22:23]
	s_waitcnt vmcnt(8) lgkmcnt(0)
	s_barrier
	s_setprio 1
	v_mfma_f32_16x16x32_bf16 v[126:129], v[130:133], v[180:183], v[126:129]
	v_mfma_f32_16x16x32_bf16 v[118:121], v[138:141], v[180:183], v[118:121]
	v_mfma_f32_16x16x32_bf16 v[110:113], v[130:133], v[202:205], v[110:113]
	v_mfma_f32_16x16x32_bf16 v[102:105], v[138:141], v[202:205], v[102:105]
	v_mfma_f32_16x16x32_bf16 v[94:97], v[130:133], v[210:213], v[94:97]
	v_mfma_f32_16x16x32_bf16 v[86:89], v[138:141], v[210:213], v[86:89]
	v_mfma_f32_16x16x32_bf16 v[78:81], v[130:133], v[236:239], v[78:81]
	v_mfma_f32_16x16x32_bf16 v[70:73], v[138:141], v[236:239], v[70:73]
	v_mfma_f32_16x16x32_bf16 v[126:129], v[134:137], v[184:187], v[126:129]
	v_mfma_f32_16x16x32_bf16 v[118:121], v[142:145], v[184:187], v[118:121]
	v_mfma_f32_16x16x32_bf16 v[110:113], v[134:137], v[206:209], v[110:113]
	v_mfma_f32_16x16x32_bf16 v[102:105], v[142:145], v[206:209], v[102:105]
	v_mfma_f32_16x16x32_bf16 v[94:97], v[134:137], v[232:235], v[94:97]
	v_mfma_f32_16x16x32_bf16 v[86:89], v[142:145], v[232:235], v[86:89]
	v_mfma_f32_16x16x32_bf16 v[78:81], v[134:137], v[240:243], v[78:81]
	v_mfma_f32_16x16x32_bf16 v[70:73], v[142:145], v[240:243], v[70:73]
	s_setprio 0
	s_setprio 1
	v_mfma_f32_16x16x32_bf16 v[122:125], v[158:161], v[180:183], v[122:125]
	v_mfma_f32_16x16x32_bf16 v[114:117], v[172:175], v[180:183], v[114:117]
	v_mfma_f32_16x16x32_bf16 v[106:109], v[158:161], v[202:205], v[106:109]
	v_mfma_f32_16x16x32_bf16 v[98:101], v[172:175], v[202:205], v[98:101]
	v_mfma_f32_16x16x32_bf16 v[90:93], v[158:161], v[210:213], v[90:93]
	v_mfma_f32_16x16x32_bf16 v[82:85], v[172:175], v[210:213], v[82:85]
	v_mfma_f32_16x16x32_bf16 v[74:77], v[158:161], v[236:239], v[74:77]
	v_mfma_f32_16x16x32_bf16 v[66:69], v[172:175], v[236:239], v[66:69]
	v_mfma_f32_16x16x32_bf16 v[122:125], v[162:165], v[184:187], v[122:125]
	v_mfma_f32_16x16x32_bf16 v[114:117], v[176:179], v[184:187], v[114:117]
	v_mfma_f32_16x16x32_bf16 v[106:109], v[162:165], v[206:209], v[106:109]
	v_mfma_f32_16x16x32_bf16 v[98:101], v[176:179], v[206:209], v[98:101]
	v_mfma_f32_16x16x32_bf16 v[90:93], v[162:165], v[232:235], v[90:93]
	v_mfma_f32_16x16x32_bf16 v[82:85], v[176:179], v[232:235], v[82:85]
	v_mfma_f32_16x16x32_bf16 v[74:77], v[162:165], v[240:243], v[74:77]
	v_mfma_f32_16x16x32_bf16 v[66:69], v[176:179], v[240:243], v[66:69]
	s_setprio 0
	s_barrier
	s_add_i32 s51, s51, s30
	s_mov_b32 m0, s51
	ds_read_b128 v[180:183], v171 offset:16384
	ds_read_b128 v[184:187], v171 offset:17408
	ds_read_b128 v[202:205], v171 offset:18432
	ds_read_b128 v[206:209], v171 offset:19456
	ds_read_b128 v[210:213], v171 offset:20480
	ds_read_b128 v[232:235], v171 offset:21504
	ds_read_b128 v[236:239], v171 offset:22528
	ds_read_b128 v[240:243], v171 offset:23552
	s_add_u32 s60, s24, 0x80
	s_addc_u32 s61, s25, 0
	s_add_u32 s62, s26, 0x80
	s_addc_u32 s63, s27, 0
	global_load_lds_dwordx4 v150, s[24:25]
	s_add_i32 m0, s51, 0x2000
	s_add_u32 s52, s24, 0x40000
	s_addc_u32 s53, s25, 0
	s_add_i32 s51, s54, s30
	global_load_lds_dwordx4 v146, s[24:25]
	s_mov_b32 m0, s51
	s_nop 0
	global_load_lds_dwordx4 v150, s[52:53]
	s_add_i32 m0, s51, 0x2000
	s_nop 0
	global_load_lds_dwordx4 v146, s[52:53]
	s_mov_b32 m0, s7
	s_nop 0
	global_load_lds_dwordx4 v152, s[26:27]
	s_mov_b32 m0, s36
	s_nop 0
	global_load_lds_dwordx4 v148, s[26:27]
	s_waitcnt vmcnt(8) lgkmcnt(0)
	s_barrier
	s_setprio 1
	v_mfma_f32_16x16x32_bf16 v[62:65], v[130:133], v[180:183], v[62:65]
	v_mfma_f32_16x16x32_bf16 v[54:57], v[138:141], v[180:183], v[54:57]
	v_mfma_f32_16x16x32_bf16 v[46:49], v[130:133], v[202:205], v[46:49]
	v_mfma_f32_16x16x32_bf16 v[38:41], v[138:141], v[202:205], v[38:41]
	v_mfma_f32_16x16x32_bf16 v[30:33], v[130:133], v[210:213], v[30:33]
	v_mfma_f32_16x16x32_bf16 v[22:25], v[138:141], v[210:213], v[22:25]
	v_mfma_f32_16x16x32_bf16 v[14:17], v[130:133], v[236:239], v[14:17]
	v_mfma_f32_16x16x32_bf16 v[6:9], v[138:141], v[236:239], v[6:9]
	v_mfma_f32_16x16x32_bf16 v[62:65], v[134:137], v[184:187], v[62:65]
	v_mfma_f32_16x16x32_bf16 v[54:57], v[142:145], v[184:187], v[54:57]
	v_mfma_f32_16x16x32_bf16 v[46:49], v[134:137], v[206:209], v[46:49]
	v_mfma_f32_16x16x32_bf16 v[38:41], v[142:145], v[206:209], v[38:41]
	v_mfma_f32_16x16x32_bf16 v[30:33], v[134:137], v[232:235], v[30:33]
	v_mfma_f32_16x16x32_bf16 v[22:25], v[142:145], v[232:235], v[22:25]
	v_mfma_f32_16x16x32_bf16 v[14:17], v[134:137], v[240:243], v[14:17]
	v_mfma_f32_16x16x32_bf16 v[6:9], v[142:145], v[240:243], v[6:9]
	s_setprio 0
	s_setprio 1
	v_mfma_f32_16x16x32_bf16 v[58:61], v[158:161], v[180:183], v[58:61]
	v_mfma_f32_16x16x32_bf16 v[50:53], v[172:175], v[180:183], v[50:53]
	v_mfma_f32_16x16x32_bf16 v[42:45], v[158:161], v[202:205], v[42:45]
	v_mfma_f32_16x16x32_bf16 v[34:37], v[172:175], v[202:205], v[34:37]
	v_mfma_f32_16x16x32_bf16 v[26:29], v[158:161], v[210:213], v[26:29]
	v_mfma_f32_16x16x32_bf16 v[18:21], v[172:175], v[210:213], v[18:21]
	v_mfma_f32_16x16x32_bf16 v[10:13], v[158:161], v[236:239], v[10:13]
	v_mfma_f32_16x16x32_bf16 v[2:5], v[172:175], v[236:239], v[2:5]
	v_mfma_f32_16x16x32_bf16 v[58:61], v[162:165], v[184:187], v[58:61]
	v_mfma_f32_16x16x32_bf16 v[50:53], v[176:179], v[184:187], v[50:53]
	v_mfma_f32_16x16x32_bf16 v[42:45], v[162:165], v[206:209], v[42:45]
	v_mfma_f32_16x16x32_bf16 v[34:37], v[176:179], v[206:209], v[34:37]
	v_mfma_f32_16x16x32_bf16 v[26:29], v[162:165], v[232:235], v[26:29]
	v_mfma_f32_16x16x32_bf16 v[18:21], v[176:179], v[232:235], v[18:21]
	v_mfma_f32_16x16x32_bf16 v[10:13], v[162:165], v[240:243], v[10:13]
	v_mfma_f32_16x16x32_bf16 v[2:5], v[176:179], v[240:243], v[2:5]
	s_setprio 0
	s_barrier
; #define PG8_STAGE(bufoff, gbase, voff) do { _Pragma("unroll") for (int _i = 0; _i < 2; ++_i) \
;         __builtin_amdgcn_global_load_lds((const unsigned*)((const char*)(gbase) + (voff)[_i]), (PG8_LAS unsigned*)(lds + (bufoff) + ldsw + _i * 8192), 16, 0, 0); } while (0)
; #define PG8_LDA(dst, b, h) do { _Pragma("unroll") for (int m = 0; m < 4; ++m) _Pragma("unroll") for (int k = 0; k < 2; ++k) dst[m][k] = *(const PG8_LAS bf16x8*)(lds + PG8_SA(b, h) + aoff + m * 2048 + k * 1024); } while (0)
; #define PG8_LDB(dst, b, h) do { _Pragma("unroll") for (int n = 0; n < 2; ++n) _Pragma("unroll") for (int k = 0; k < 2; ++k) dst[n][k] = *(const PG8_LAS bf16x8*)(lds + PG8_SB(b, h) + boff + n * 2048 + k * 1024); } while (0)
; #define PG8_MMA(ai, bj, At, Bt) do { __builtin_amdgcn_s_setprio(1); _Pragma("unroll") for (int m = 0; m < 4; ++m) _Pragma("unroll") for (int n = 0; n < 2; ++n) _Pragma("unroll") for (int k = 0; k < 2; ++k) \
;         acc[ai][bj][m][n] = __builtin_amdgcn_mfma_f32_16x16x32_bf16(Bt[n][k], At[m][k], acc[ai][bj][m][n], 0, 0, 0); __builtin_amdgcn_s_setprio(0); } while (0)
; template <class Epi, class Sched, bool ALIGN_EPI = false, bool SP2 = false>
; __device__ __forceinline__ void gemm_phase(PG8_LAS unsigned char* lds, const Gemm g, const Sched& S, const Epi& E) {
;     ...
;         for (int t = 0; t < nt; t += 2) {
;     ...
;             PG8_LDB(B0, 0, 0); PG8_LDB(B1, 0, 1); PG8_SCHED; PG8_LDA(At, 0, 0); PG8_STAGE(PG8_SA(1, 1), a1 + hstepA, voffA);
;             PG8_WAIT_V(8); PG8_WAIT_L(0); PG8_BAR; PG8_MMA(0, 0, At, B0); PG8_MMA(0, 1, At, B1); PG8_BAR; PG8_SCHED;
;             PG8_LDA(At, 0, 1); PG8_STAGE(PG8_SB(0, 0), b2, voffB); PG8_STAGE(PG8_SB(0, 1), b2 + hstepB, voffB); PG8_STAGE(PG8_SA(0, 0), a2, voffA);
;             PG8_WAIT_V(8); PG8_WAIT_L(0); PG8_BAR; PG8_MMA(1, 0, At, B0); PG8_MMA(1, 1, At, B1); PG8_BAR; PG8_SCHED;
;             PG8_LDB(B0, 1, 0); PG8_LDB(B1, 1, 1); PG8_SCHED; PG8_LDA(At, 1, 0); PG8_STAGE(PG8_SA(0, 1), a2 + hstepA, voffA);
;             PG8_WAIT_V(8); PG8_WAIT_L(0); PG8_BAR; PG8_MMA(0, 0, At, B0); PG8_MMA(0, 1, At, B1); PG8_BAR; PG8_SCHED;
;             PG8_LDA(At, 1, 1); PG8_STAGE(PG8_SB(1, 0), b3, voffB); PG8_STAGE(PG8_SB(1, 1), b3 + hstepB, voffB); PG8_STAGE(PG8_SA(1, 0), a3, voffA);
;             PG8_WAIT_V(8); PG8_WAIT_L(0); PG8_BAR; PG8_MMA(1, 0, At, B0); PG8_MMA(1, 1, At, B1); PG8_BAR; PG8_SCHED;
	s_add_i32 s51, 0, 0x18000
	s_add_i32 s52, 0, 0x1c000
	v_add_u32_e32 v142, s51, v168
	v_add_u32_e32 v176, s52, v168
	ds_read_b128 v[130:133], v142
	ds_read_b128 v[134:137], v142 offset:1024
	ds_read_b128 v[138:141], v142 offset:2048
	ds_read_b128 v[142:145], v142 offset:3072
	ds_read_b128 v[158:161], v176
	ds_read_b128 v[162:165], v176 offset:1024
	ds_read_b128 v[172:175], v176 offset:2048
	ds_read_b128 v[176:179], v176 offset:3072
	s_add_u32 s26, s26, 0x40000
	s_addc_u32 s27, s27, 0
	s_mov_b32 m0, s37
	ds_read_b128 v[180:183], v171 offset:32768
	ds_read_b128 v[184:187], v171 offset:33792
	ds_read_b128 v[202:205], v171 offset:34816
	ds_read_b128 v[206:209], v171 offset:35840
	ds_read_b128 v[210:213], v171 offset:36864
	ds_read_b128 v[232:235], v171 offset:37888
	ds_read_b128 v[236:239], v171 offset:38912
	ds_read_b128 v[240:243], v171 offset:39936
	global_load_lds_dwordx4 v152, s[26:27]
	s_mov_b32 m0, s38
	s_nop 0
	global_load_lds_dwordx4 v148, s[26:27]
	s_waitcnt vmcnt(8) lgkmcnt(0)
	s_barrier
	s_setprio 1
	v_mfma_f32_16x16x32_bf16 v[126:129], v[130:133], v[180:183], v[126:129]
	v_mfma_f32_16x16x32_bf16 v[118:121], v[138:141], v[180:183], v[118:121]
	v_mfma_f32_16x16x32_bf16 v[110:113], v[130:133], v[202:205], v[110:113]
	v_mfma_f32_16x16x32_bf16 v[102:105], v[138:141], v[202:205], v[102:105]
	v_mfma_f32_16x16x32_bf16 v[94:97], v[130:133], v[210:213], v[94:97]
	v_mfma_f32_16x16x32_bf16 v[86:89], v[138:141], v[210:213], v[86:89]
	v_mfma_f32_16x16x32_bf16 v[78:81], v[130:133], v[236:239], v[78:81]
	v_mfma_f32_16x16x32_bf16 v[70:73], v[138:141], v[236:239], v[70:73]
	v_mfma_f32_16x16x32_bf16 v[126:129], v[134:137], v[184:187], v[126:129]
	v_mfma_f32_16x16x32_bf16 v[118:121], v[142:145], v[184:187], v[118:121]
	v_mfma_f32_16x16x32_bf16 v[110:113], v[134:137], v[206:209], v[110:113]
	v_mfma_f32_16x16x32_bf16 v[102:105], v[142:145], v[206:209], v[102:105]
	v_mfma_f32_16x16x32_bf16 v[94:97], v[134:137], v[232:235], v[94:97]
	v_mfma_f32_16x16x32_bf16 v[86:89], v[142:145], v[232:235], v[86:89]
	v_mfma_f32_16x16x32_bf16 v[78:81], v[134:137], v[240:243], v[78:81]
	v_mfma_f32_16x16x32_bf16 v[70:73], v[142:145], v[240:243], v[70:73]
	s_setprio 0
	s_setprio 1
	v_mfma_f32_16x16x32_bf16 v[122:125], v[158:161], v[180:183], v[122:125]
	v_mfma_f32_16x16x32_bf16 v[114:117], v[172:175], v[180:183], v[114:117]
	v_mfma_f32_16x16x32_bf16 v[106:109], v[158:161], v[202:205], v[106:109]
	v_mfma_f32_16x16x32_bf16 v[98:101], v[172:175], v[202:205], v[98:101]
	v_mfma_f32_16x16x32_bf16 v[90:93], v[158:161], v[210:213], v[90:93]
	v_mfma_f32_16x16x32_bf16 v[82:85], v[172:175], v[210:213], v[82:85]
	v_mfma_f32_16x16x32_bf16 v[74:77], v[158:161], v[236:239], v[74:77]
	v_mfma_f32_16x16x32_bf16 v[66:69], v[172:175], v[236:239], v[66:69]
	v_mfma_f32_16x16x32_bf16 v[122:125], v[162:165], v[184:187], v[122:125]
	v_mfma_f32_16x16x32_bf16 v[114:117], v[176:179], v[184:187], v[114:117]
	v_mfma_f32_16x16x32_bf16 v[106:109], v[162:165], v[206:209], v[106:109]
	v_mfma_f32_16x16x32_bf16 v[98:101], v[176:179], v[206:209], v[98:101]
	v_mfma_f32_16x16x32_bf16 v[90:93], v[162:165], v[232:235], v[90:93]
	v_mfma_f32_16x16x32_bf16 v[82:85], v[176:179], v[232:235], v[82:85]
	v_mfma_f32_16x16x32_bf16 v[74:77], v[162:165], v[240:243], v[74:77]
	v_mfma_f32_16x16x32_bf16 v[66:69], v[176:179], v[240:243], v[66:69]
	s_setprio 0
	s_barrier
	s_add_i32 s26, s51, s30
	s_mov_b32 m0, s26
	ds_read_b128 v[180:183], v171 offset:49152
	ds_read_b128 v[184:187], v171 offset:50176
	ds_read_b128 v[202:205], v171 offset:51200
	ds_read_b128 v[206:209], v171 offset:52224
	ds_read_b128 v[210:213], v171 offset:53248
	ds_read_b128 v[232:235], v171 offset:54272
	ds_read_b128 v[236:239], v171 offset:55296
	ds_read_b128 v[240:243], v171 offset:56320
	global_load_lds_dwordx4 v150, s[60:61]
	s_add_i32 m0, s26, 0x2000
	s_add_u32 s24, s24, 0x40080
	s_addc_u32 s25, s25, 0
	s_add_i32 s26, s52, s30
	global_load_lds_dwordx4 v146, s[60:61]
	s_mov_b32 m0, s26
	s_nop 0
	global_load_lds_dwordx4 v150, s[24:25]
	s_add_i32 m0, s26, 0x2000
	s_nop 0
	global_load_lds_dwordx4 v146, s[24:25]
	s_mov_b32 m0, s39
	s_nop 0
	global_load_lds_dwordx4 v152, s[62:63]
	s_mov_b32 m0, s40
	s_nop 0
	global_load_lds_dwordx4 v148, s[62:63]
	s_waitcnt vmcnt(8) lgkmcnt(0)
	s_barrier
	s_setprio 1
	v_mfma_f32_16x16x32_bf16 v[62:65], v[130:133], v[180:183], v[62:65]
	v_mfma_f32_16x16x32_bf16 v[54:57], v[138:141], v[180:183], v[54:57]
	v_mfma_f32_16x16x32_bf16 v[46:49], v[130:133], v[202:205], v[46:49]
	v_mfma_f32_16x16x32_bf16 v[38:41], v[138:141], v[202:205], v[38:41]
	v_mfma_f32_16x16x32_bf16 v[30:33], v[130:133], v[210:213], v[30:33]
	v_mfma_f32_16x16x32_bf16 v[22:25], v[138:141], v[210:213], v[22:25]
	v_mfma_f32_16x16x32_bf16 v[14:17], v[130:133], v[236:239], v[14:17]
	v_mfma_f32_16x16x32_bf16 v[6:9], v[138:141], v[236:239], v[6:9]
	v_mfma_f32_16x16x32_bf16 v[62:65], v[134:137], v[184:187], v[62:65]
	v_mfma_f32_16x16x32_bf16 v[54:57], v[142:145], v[184:187], v[54:57]
	v_mfma_f32_16x16x32_bf16 v[46:49], v[134:137], v[206:209], v[46:49]
	v_mfma_f32_16x16x32_bf16 v[38:41], v[142:145], v[206:209], v[38:41]
	v_mfma_f32_16x16x32_bf16 v[30:33], v[134:137], v[232:235], v[30:33]
	v_mfma_f32_16x16x32_bf16 v[22:25], v[142:145], v[232:235], v[22:25]
	v_mfma_f32_16x16x32_bf16 v[14:17], v[134:137], v[240:243], v[14:17]
	v_mfma_f32_16x16x32_bf16 v[6:9], v[142:145], v[240:243], v[6:9]
	s_setprio 0
	s_setprio 1
	v_mfma_f32_16x16x32_bf16 v[58:61], v[158:161], v[180:183], v[58:61]
	v_mfma_f32_16x16x32_bf16 v[50:53], v[172:175], v[180:183], v[50:53]
	v_mfma_f32_16x16x32_bf16 v[42:45], v[158:161], v[202:205], v[42:45]
	v_mfma_f32_16x16x32_bf16 v[34:37], v[172:175], v[202:205], v[34:37]
	v_mfma_f32_16x16x32_bf16 v[26:29], v[158:161], v[210:213], v[26:29]
	v_mfma_f32_16x16x32_bf16 v[18:21], v[172:175], v[210:213], v[18:21]
	v_mfma_f32_16x16x32_bf16 v[10:13], v[158:161], v[236:239], v[10:13]
	v_mfma_f32_16x16x32_bf16 v[2:5], v[172:175], v[236:239], v[2:5]
	v_mfma_f32_16x16x32_bf16 v[58:61], v[162:165], v[184:187], v[58:61]
	v_mfma_f32_16x16x32_bf16 v[50:53], v[176:179], v[184:187], v[50:53]
	v_mfma_f32_16x16x32_bf16 v[42:45], v[162:165], v[206:209], v[42:45]
	v_mfma_f32_16x16x32_bf16 v[34:37], v[176:179], v[206:209], v[34:37]
	v_mfma_f32_16x16x32_bf16 v[26:29], v[162:165], v[232:235], v[26:29]
	v_mfma_f32_16x16x32_bf16 v[18:21], v[176:179], v[232:235], v[18:21]
	v_mfma_f32_16x16x32_bf16 v[10:13], v[162:165], v[240:243], v[10:13]
	v_mfma_f32_16x16x32_bf16 v[2:5], v[176:179], v[240:243], v[2:5]
	s_setprio 0
	s_barrier
	s_add_i32 s50, s50, 2
	s_add_u32 s22, s22, 0x100
	s_addc_u32 s23, s23, 0
	s_add_u32 s48, s48, 0x100
	s_addc_u32 s49, s49, 0
	s_cmp_gt_u32 s50, 13
	s_cbranch_scc0 .LBB0_1190
	s_and_b64 vcc, exec, s[18:19]
	s_cbranch_vccz .LBB0_1193
	s_barrier

; #define PG8_STAGE(bufoff, gbase, voff) do { _Pragma("unroll") for (int _i = 0; _i < 2; ++_i) \
;         __builtin_amdgcn_global_load_lds((const unsigned*)((const char*)(gbase) + (voff)[_i]), (PG8_LAS unsigned*)(lds + (bufoff) + ldsw + _i * 8192), 16, 0, 0); } while (0)
; #define PG8_LDA(dst, b, h) do { _Pragma("unroll") for (int m = 0; m < 4; ++m) _Pragma("unroll") for (int k = 0; k < 2; ++k) dst[m][k] = *(const PG8_LAS bf16x8*)(lds + PG8_SA(b, h) + aoff + m * 2048 + k * 1024); } while (0)
; #define PG8_LDB(dst, b, h) do { _Pragma("unroll") for (int n = 0; n < 2; ++n) _Pragma("unroll") for (int k = 0; k < 2; ++k) dst[n][k] = *(const PG8_LAS bf16x8*)(lds + PG8_SB(b, h) + boff + n * 2048 + k * 1024); } while (0)
; #define PG8_MMA(ai, bj, At, Bt) do { __builtin_amdgcn_s_setprio(1); _Pragma("unroll") for (int m = 0; m < 4; ++m) _Pragma("unroll") for (int n = 0; n < 2; ++n) _Pragma("unroll") for (int k = 0; k < 2; ++k) \
;         acc[ai][bj][m][n] = __builtin_amdgcn_mfma_f32_16x16x32_bf16(Bt[n][k], At[m][k], acc[ai][bj][m][n], 0, 0, 0); __builtin_amdgcn_s_setprio(0); } while (0)
; #define PG8_WAIT_V(n) asm volatile("s_waitcnt vmcnt(" #n ")" ::: "memory")
; #define PG8_BAR __builtin_amdgcn_s_barrier()
; template <class Epi, class Sched, bool ALIGN_EPI = false, bool SP2 = false>
; __device__ __forceinline__ void gemm_phase(PG8_LAS unsigned char* lds, const Gemm g, const Sched& S, const Epi& E) {
;     ...
;         for (int t = 0; t < nt; t += 2) {
;             const bool last = (t == nt - 2);
;             const char* a1 = cA + (size_t)(t + 1) * kstep;
;             const char* a2 = last ? nA : cA + (size_t)(t + 2) * kstep; const char* b2 = last ? nB : cB + (size_t)(t + 2) * kstep;
;             const char* a3 = a2 + kstep; const char* b3 = b2 + kstep;
;             if (last && has_next) S.a_ready(nxt);
;             if constexpr (SP2) {
;             PG8_LDB(B0, 0, 0); PG8_LDB(B1, 0, 1); PG8_SCHED; PG8_LDA(At, 0, 0); PG8_STAGE(PG8_SA(1, 1), a1 + hstepA, voffA);
;             PG8_WAIT_V(8); PG8_WAIT_L(0); PG8_BAR; PG8_MMA(0, 0, At, B0); PG8_MMA(0, 1, At, B1); PG8_BAR; PG8_SCHED;
;             PG8_LDA(At, 0, 1); PG8_STAGE(PG8_SB(0, 0), b2, voffB); PG8_STAGE(PG8_SB(0, 1), b2 + hstepB, voffB); PG8_STAGE(PG8_SA(0, 0), a2, voffA);
;             PG8_WAIT_V(8); PG8_WAIT_L(0); PG8_BAR; PG8_MMA(1, 0, At, B0); PG8_MMA(1, 1, At, B1); PG8_BAR; PG8_SCHED;
.LBB0_1270:
	s_add_u32 s28, s26, 0xfffc0080
	s_addc_u32 s29, s27, -1
	s_add_i32 s52, 0, 0x10000
	s_cmp_eq_u32 s51, 12
	s_cselect_b32 s31, s17, s29
	s_cselect_b32 s30, s23, s28
	s_cselect_b32 s29, s15, s50
	s_cselect_b32 s28, s25, s49
	s_add_i32 s54, 0, 0x14000
	v_add_u32_e32 v142, s52, v186
	v_add_u32_e32 v172, s54, v186
	ds_read_b128 v[130:133], v142
	ds_read_b128 v[134:137], v142 offset:1024
	ds_read_b128 v[138:141], v142 offset:2048
	ds_read_b128 v[142:145], v142 offset:3072
	ds_read_b128 v[146:149], v172
	ds_read_b128 v[150:153], v172 offset:1024
	ds_read_b128 v[168:171], v172 offset:2048
	ds_read_b128 v[172:175], v172 offset:3072
	s_add_i32 m0, s39, 0xc000
	ds_read_b128 v[176:179], v200
	ds_read_b128 v[180:183], v200 offset:1024
	ds_read_b128 v[202:205], v200 offset:2048
	ds_read_b128 v[206:209], v200 offset:3072
	ds_read_b128 v[210:213], v200 offset:4096
	ds_read_b128 v[232:235], v200 offset:5120
	ds_read_b128 v[236:239], v200 offset:6144
	ds_read_b128 v[240:243], v200 offset:7168
	global_load_lds_dwordx4 v164, s[26:27]
	s_add_i32 m0, s39, 0xe000
	s_nop 0
	global_load_lds_dwordx4 v166, s[26:27]
	s_waitcnt vmcnt(8) lgkmcnt(0)
	s_barrier
	s_setprio 1
	v_mfma_f32_16x16x32_bf16 v[126:129], v[130:133], v[176:179], v[126:129]
	v_mfma_f32_16x16x32_bf16 v[122:125], v[138:141], v[176:179], v[122:125]
	v_mfma_f32_16x16x32_bf16 v[110:113], v[130:133], v[202:205], v[110:113]
	v_mfma_f32_16x16x32_bf16 v[106:109], v[138:141], v[202:205], v[106:109]
	v_mfma_f32_16x16x32_bf16 v[94:97], v[130:133], v[210:213], v[94:97]
	v_mfma_f32_16x16x32_bf16 v[90:93], v[138:141], v[210:213], v[90:93]
	v_mfma_f32_16x16x32_bf16 v[78:81], v[130:133], v[236:239], v[78:81]
	v_mfma_f32_16x16x32_bf16 v[74:77], v[138:141], v[236:239], v[74:77]
	v_mfma_f32_16x16x32_bf16 v[126:129], v[134:137], v[180:183], v[126:129]
	v_mfma_f32_16x16x32_bf16 v[122:125], v[142:145], v[180:183], v[122:125]
	v_mfma_f32_16x16x32_bf16 v[110:113], v[134:137], v[206:209], v[110:113]
	v_mfma_f32_16x16x32_bf16 v[106:109], v[142:145], v[206:209], v[106:109]
	v_mfma_f32_16x16x32_bf16 v[94:97], v[134:137], v[232:235], v[94:97]
	v_mfma_f32_16x16x32_bf16 v[90:93], v[142:145], v[232:235], v[90:93]
	v_mfma_f32_16x16x32_bf16 v[78:81], v[134:137], v[240:243], v[78:81]
	v_mfma_f32_16x16x32_bf16 v[74:77], v[142:145], v[240:243], v[74:77]
	s_setprio 0
	s_setprio 1
	v_mfma_f32_16x16x32_bf16 v[118:121], v[146:149], v[176:179], v[118:121]
	v_mfma_f32_16x16x32_bf16 v[114:117], v[168:171], v[176:179], v[114:117]
	v_mfma_f32_16x16x32_bf16 v[102:105], v[146:149], v[202:205], v[102:105]
	v_mfma_f32_16x16x32_bf16 v[98:101], v[168:171], v[202:205], v[98:101]
	v_mfma_f32_16x16x32_bf16 v[86:89], v[146:149], v[210:213], v[86:89]
	v_mfma_f32_16x16x32_bf16 v[82:85], v[168:171], v[210:213], v[82:85]
	v_mfma_f32_16x16x32_bf16 v[70:73], v[146:149], v[236:239], v[70:73]
	v_mfma_f32_16x16x32_bf16 v[66:69], v[168:171], v[236:239], v[66:69]
	v_mfma_f32_16x16x32_bf16 v[118:121], v[150:153], v[180:183], v[118:121]
	v_mfma_f32_16x16x32_bf16 v[114:117], v[172:175], v[180:183], v[114:117]
	v_mfma_f32_16x16x32_bf16 v[102:105], v[150:153], v[206:209], v[102:105]
	v_mfma_f32_16x16x32_bf16 v[98:101], v[172:175], v[206:209], v[98:101]
	v_mfma_f32_16x16x32_bf16 v[86:89], v[150:153], v[232:235], v[86:89]
	v_mfma_f32_16x16x32_bf16 v[82:85], v[172:175], v[232:235], v[82:85]
	v_mfma_f32_16x16x32_bf16 v[70:73], v[150:153], v[240:243], v[70:73]
	v_mfma_f32_16x16x32_bf16 v[66:69], v[172:175], v[240:243], v[66:69]
	s_setprio 0
	s_barrier
	s_add_i32 s52, s52, s38
	s_mov_b32 m0, s52
	ds_read_b128 v[176:179], v200 offset:16384
	ds_read_b128 v[180:183], v200 offset:17408
	ds_read_b128 v[202:205], v200 offset:18432
	ds_read_b128 v[206:209], v200 offset:19456
	ds_read_b128 v[210:213], v200 offset:20480
	ds_read_b128 v[232:235], v200 offset:21504
	ds_read_b128 v[236:239], v200 offset:22528
	ds_read_b128 v[240:243], v200 offset:23552
	s_add_u32 s60, s28, 0x80
	s_addc_u32 s61, s29, 0
	s_add_u32 s62, s30, 0x80
	s_addc_u32 s63, s31, 0
	global_load_lds_dwordx4 v156, s[28:29]
	s_add_i32 m0, s52, 0x2000
	s_add_u32 s52, s28, 0x40000
	s_addc_u32 s53, s29, 0
	s_add_i32 s54, s54, s38
	global_load_lds_dwordx4 v160, s[28:29]
	s_mov_b32 m0, s54
	s_nop 0
	global_load_lds_dwordx4 v156, s[52:53]
	s_add_i32 m0, s54, 0x2000
	s_nop 0
	global_load_lds_dwordx4 v160, s[52:53]
	s_mov_b32 m0, s39
	s_nop 0
	global_load_lds_dwordx4 v154, s[30:31]
	s_mov_b32 m0, s40
	s_nop 0
	global_load_lds_dwordx4 v158, s[30:31]
	s_waitcnt vmcnt(8) lgkmcnt(0)
	s_barrier
	s_setprio 1
	v_mfma_f32_16x16x32_bf16 v[62:65], v[130:133], v[176:179], v[62:65]
	v_mfma_f32_16x16x32_bf16 v[58:61], v[138:141], v[176:179], v[58:61]
	v_mfma_f32_16x16x32_bf16 v[46:49], v[130:133], v[202:205], v[46:49]
	v_mfma_f32_16x16x32_bf16 v[42:45], v[138:141], v[202:205], v[42:45]
	v_mfma_f32_16x16x32_bf16 v[30:33], v[130:133], v[210:213], v[30:33]
	v_mfma_f32_16x16x32_bf16 v[26:29], v[138:141], v[210:213], v[26:29]
	v_mfma_f32_16x16x32_bf16 v[14:17], v[130:133], v[236:239], v[14:17]
	v_mfma_f32_16x16x32_bf16 v[10:13], v[138:141], v[236:239], v[10:13]
	v_mfma_f32_16x16x32_bf16 v[62:65], v[134:137], v[180:183], v[62:65]
	v_mfma_f32_16x16x32_bf16 v[58:61], v[142:145], v[180:183], v[58:61]
	v_mfma_f32_16x16x32_bf16 v[46:49], v[134:137], v[206:209], v[46:49]
	v_mfma_f32_16x16x32_bf16 v[42:45], v[142:145], v[206:209], v[42:45]
	v_mfma_f32_16x16x32_bf16 v[30:33], v[134:137], v[232:235], v[30:33]
	v_mfma_f32_16x16x32_bf16 v[26:29], v[142:145], v[232:235], v[26:29]
	v_mfma_f32_16x16x32_bf16 v[14:17], v[134:137], v[240:243], v[14:17]
	v_mfma_f32_16x16x32_bf16 v[10:13], v[142:145], v[240:243], v[10:13]
	s_setprio 0
	s_setprio 1
	v_mfma_f32_16x16x32_bf16 v[54:57], v[146:149], v[176:179], v[54:57]
	v_mfma_f32_16x16x32_bf16 v[50:53], v[168:171], v[176:179], v[50:53]
	v_mfma_f32_16x16x32_bf16 v[38:41], v[146:149], v[202:205], v[38:41]
	v_mfma_f32_16x16x32_bf16 v[34:37], v[168:171], v[202:205], v[34:37]
	v_mfma_f32_16x16x32_bf16 v[22:25], v[146:149], v[210:213], v[22:25]
	v_mfma_f32_16x16x32_bf16 v[18:21], v[168:171], v[210:213], v[18:21]
	v_mfma_f32_16x16x32_bf16 v[6:9], v[146:149], v[236:239], v[6:9]
	v_mfma_f32_16x16x32_bf16 v[2:5], v[168:171], v[236:239], v[2:5]
	v_mfma_f32_16x16x32_bf16 v[54:57], v[150:153], v[180:183], v[54:57]
	v_mfma_f32_16x16x32_bf16 v[50:53], v[172:175], v[180:183], v[50:53]
	v_mfma_f32_16x16x32_bf16 v[38:41], v[150:153], v[206:209], v[38:41]
	v_mfma_f32_16x16x32_bf16 v[34:37], v[172:175], v[206:209], v[34:37]
	v_mfma_f32_16x16x32_bf16 v[22:25], v[150:153], v[232:235], v[22:25]
	v_mfma_f32_16x16x32_bf16 v[18:21], v[172:175], v[232:235], v[18:21]
	v_mfma_f32_16x16x32_bf16 v[6:9], v[150:153], v[240:243], v[6:9]
	v_mfma_f32_16x16x32_bf16 v[2:5], v[172:175], v[240:243], v[2:5]
	s_setprio 0
	s_barrier
; #define PG8_STAGE(bufoff, gbase, voff) do { _Pragma("unroll") for (int _i = 0; _i < 2; ++_i) \
;         __builtin_amdgcn_global_load_lds((const unsigned*)((const char*)(gbase) + (voff)[_i]), (PG8_LAS unsigned*)(lds + (bufoff) + ldsw + _i * 8192), 16, 0, 0); } while (0)
; #define PG8_LDA(dst, b, h) do { _Pragma("unroll") for (int m = 0; m < 4; ++m) _Pragma("unroll") for (int k = 0; k < 2; ++k) dst[m][k] = *(const PG8_LAS bf16x8*)(lds + PG8_SA(b, h) + aoff + m * 2048 + k * 1024); } while (0)
; #define PG8_LDB(dst, b, h) do { _Pragma("unroll") for (int n = 0; n < 2; ++n) _Pragma("unroll") for (int k = 0; k < 2; ++k) dst[n][k] = *(const PG8_LAS bf16x8*)(lds + PG8_SB(b, h) + boff + n * 2048 + k * 1024); } while (0)
; #define PG8_MMA(ai, bj, At, Bt) do { __builtin_amdgcn_s_setprio(1); _Pragma("unroll") for (int m = 0; m < 4; ++m) _Pragma("unroll") for (int n = 0; n < 2; ++n) _Pragma("unroll") for (int k = 0; k < 2; ++k) \
;         acc[ai][bj][m][n] = __builtin_amdgcn_mfma_f32_16x16x32_bf16(Bt[n][k], At[m][k], acc[ai][bj][m][n], 0, 0, 0); __builtin_amdgcn_s_setprio(0); } while (0)
; #define PG8_WAIT_V(n) asm volatile("s_waitcnt vmcnt(" #n ")" ::: "memory")
; #define PG8_WAIT_L(n) asm volatile("s_waitcnt lgkmcnt(" #n ")" ::: "memory")
; #define PG8_BAR __builtin_amdgcn_s_barrier()
; #define PG8_SCHED __builtin_amdgcn_sched_barrier(0)
; template <class Epi, class Sched, bool ALIGN_EPI = false, bool SP2 = false>
; __device__ __forceinline__ void gemm_phase(PG8_LAS unsigned char* lds, const Gemm g, const Sched& S, const Epi& E) {
;     ...
;             PG8_LDB(B0, 1, 0); PG8_LDB(B1, 1, 1); PG8_SCHED; PG8_LDA(At, 1, 0); PG8_STAGE(PG8_SA(0, 1), a2 + hstepA, voffA);
;             PG8_WAIT_V(8); PG8_WAIT_L(0); PG8_BAR; PG8_MMA(0, 0, At, B0); PG8_MMA(0, 1, At, B1); PG8_BAR; PG8_SCHED;
;             PG8_LDA(At, 1, 1); PG8_STAGE(PG8_SB(1, 0), b3, voffB); PG8_STAGE(PG8_SB(1, 1), b3 + hstepB, voffB); PG8_STAGE(PG8_SA(1, 0), a3, voffA);
;             PG8_WAIT_V(8); PG8_WAIT_L(0); PG8_BAR; PG8_MMA(1, 0, At, B0); PG8_MMA(1, 1, At, B1); PG8_BAR; PG8_SCHED;
;     ...
;         }
;         if constexpr (ALIGN_EPI) { if (wr == 0) PG8_BAR; }
	s_add_i32 s52, 0, 0x18000
	s_add_i32 s53, 0, 0x1c000
	v_add_u32_e32 v142, s52, v186
	v_add_u32_e32 v172, s53, v186
	ds_read_b128 v[130:133], v142
	ds_read_b128 v[134:137], v142 offset:1024
	ds_read_b128 v[138:141], v142 offset:2048
	ds_read_b128 v[142:145], v142 offset:3072
	ds_read_b128 v[146:149], v172
	ds_read_b128 v[150:153], v172 offset:1024
	ds_read_b128 v[168:171], v172 offset:2048
	ds_read_b128 v[172:175], v172 offset:3072
	s_add_u32 s30, s30, 0x40000
	s_addc_u32 s31, s31, 0
	s_mov_b32 m0, s41
	ds_read_b128 v[176:179], v200 offset:32768
	ds_read_b128 v[180:183], v200 offset:33792
	ds_read_b128 v[202:205], v200 offset:34816
	ds_read_b128 v[206:209], v200 offset:35840
	ds_read_b128 v[210:213], v200 offset:36864
	ds_read_b128 v[232:235], v200 offset:37888
	ds_read_b128 v[236:239], v200 offset:38912
	ds_read_b128 v[240:243], v200 offset:39936
	global_load_lds_dwordx4 v154, s[30:31]
	s_mov_b32 m0, s42
	s_nop 0
	global_load_lds_dwordx4 v158, s[30:31]
	s_waitcnt vmcnt(8) lgkmcnt(0)
	s_barrier
	s_setprio 1
	v_mfma_f32_16x16x32_bf16 v[126:129], v[130:133], v[176:179], v[126:129]
	v_mfma_f32_16x16x32_bf16 v[122:125], v[138:141], v[176:179], v[122:125]
	v_mfma_f32_16x16x32_bf16 v[110:113], v[130:133], v[202:205], v[110:113]
	v_mfma_f32_16x16x32_bf16 v[106:109], v[138:141], v[202:205], v[106:109]
	v_mfma_f32_16x16x32_bf16 v[94:97], v[130:133], v[210:213], v[94:97]
	v_mfma_f32_16x16x32_bf16 v[90:93], v[138:141], v[210:213], v[90:93]
	v_mfma_f32_16x16x32_bf16 v[78:81], v[130:133], v[236:239], v[78:81]
	v_mfma_f32_16x16x32_bf16 v[74:77], v[138:141], v[236:239], v[74:77]
	v_mfma_f32_16x16x32_bf16 v[126:129], v[134:137], v[180:183], v[126:129]
	v_mfma_f32_16x16x32_bf16 v[122:125], v[142:145], v[180:183], v[122:125]
	v_mfma_f32_16x16x32_bf16 v[110:113], v[134:137], v[206:209], v[110:113]
	v_mfma_f32_16x16x32_bf16 v[106:109], v[142:145], v[206:209], v[106:109]
	v_mfma_f32_16x16x32_bf16 v[94:97], v[134:137], v[232:235], v[94:97]
	v_mfma_f32_16x16x32_bf16 v[90:93], v[142:145], v[232:235], v[90:93]
	v_mfma_f32_16x16x32_bf16 v[78:81], v[134:137], v[240:243], v[78:81]
	v_mfma_f32_16x16x32_bf16 v[74:77], v[142:145], v[240:243], v[74:77]
	s_setprio 0
	s_setprio 1
	v_mfma_f32_16x16x32_bf16 v[118:121], v[146:149], v[176:179], v[118:121]
	v_mfma_f32_16x16x32_bf16 v[114:117], v[168:171], v[176:179], v[114:117]
	v_mfma_f32_16x16x32_bf16 v[102:105], v[146:149], v[202:205], v[102:105]
	v_mfma_f32_16x16x32_bf16 v[98:101], v[168:171], v[202:205], v[98:101]
	v_mfma_f32_16x16x32_bf16 v[86:89], v[146:149], v[210:213], v[86:89]
	v_mfma_f32_16x16x32_bf16 v[82:85], v[168:171], v[210:213], v[82:85]
	v_mfma_f32_16x16x32_bf16 v[70:73], v[146:149], v[236:239], v[70:73]
	v_mfma_f32_16x16x32_bf16 v[66:69], v[168:171], v[236:239], v[66:69]
	v_mfma_f32_16x16x32_bf16 v[118:121], v[150:153], v[180:183], v[118:121]
	v_mfma_f32_16x16x32_bf16 v[114:117], v[172:175], v[180:183], v[114:117]
	v_mfma_f32_16x16x32_bf16 v[102:105], v[150:153], v[206:209], v[102:105]
	v_mfma_f32_16x16x32_bf16 v[98:101], v[172:175], v[206:209], v[98:101]
	v_mfma_f32_16x16x32_bf16 v[86:89], v[150:153], v[232:235], v[86:89]
	v_mfma_f32_16x16x32_bf16 v[82:85], v[172:175], v[232:235], v[82:85]
	v_mfma_f32_16x16x32_bf16 v[70:73], v[150:153], v[240:243], v[70:73]
	v_mfma_f32_16x16x32_bf16 v[66:69], v[172:175], v[240:243], v[66:69]
	s_setprio 0
	s_barrier
	s_add_i32 s30, s52, s38
	s_mov_b32 m0, s30
	ds_read_b128 v[176:179], v200 offset:49152
	ds_read_b128 v[180:183], v200 offset:50176
	ds_read_b128 v[202:205], v200 offset:51200
	ds_read_b128 v[206:209], v200 offset:52224
	ds_read_b128 v[210:213], v200 offset:53248
	ds_read_b128 v[232:235], v200 offset:54272
	ds_read_b128 v[236:239], v200 offset:55296
	ds_read_b128 v[240:243], v200 offset:56320
	global_load_lds_dwordx4 v156, s[60:61]
	s_add_i32 m0, s30, 0x2000
	s_add_u32 s28, s28, 0x40080
	s_addc_u32 s29, s29, 0
	s_add_i32 s30, s53, s38
	global_load_lds_dwordx4 v160, s[60:61]
	s_mov_b32 m0, s30
	s_nop 0
	global_load_lds_dwordx4 v156, s[28:29]
	s_add_i32 m0, s30, 0x2000
	s_nop 0
	global_load_lds_dwordx4 v160, s[28:29]
	s_mov_b32 m0, s44
	s_nop 0
	global_load_lds_dwordx4 v154, s[62:63]
	s_mov_b32 m0, s45
	s_nop 0
	global_load_lds_dwordx4 v158, s[62:63]
	s_waitcnt vmcnt(8) lgkmcnt(0)
	s_barrier
	s_setprio 1
	v_mfma_f32_16x16x32_bf16 v[62:65], v[130:133], v[176:179], v[62:65]
	v_mfma_f32_16x16x32_bf16 v[58:61], v[138:141], v[176:179], v[58:61]
	v_mfma_f32_16x16x32_bf16 v[46:49], v[130:133], v[202:205], v[46:49]
	v_mfma_f32_16x16x32_bf16 v[42:45], v[138:141], v[202:205], v[42:45]
	v_mfma_f32_16x16x32_bf16 v[30:33], v[130:133], v[210:213], v[30:33]
	v_mfma_f32_16x16x32_bf16 v[26:29], v[138:141], v[210:213], v[26:29]
	v_mfma_f32_16x16x32_bf16 v[14:17], v[130:133], v[236:239], v[14:17]
	v_mfma_f32_16x16x32_bf16 v[10:13], v[138:141], v[236:239], v[10:13]
	v_mfma_f32_16x16x32_bf16 v[62:65], v[134:137], v[180:183], v[62:65]
	v_mfma_f32_16x16x32_bf16 v[58:61], v[142:145], v[180:183], v[58:61]
	v_mfma_f32_16x16x32_bf16 v[46:49], v[134:137], v[206:209], v[46:49]
	v_mfma_f32_16x16x32_bf16 v[42:45], v[142:145], v[206:209], v[42:45]
	v_mfma_f32_16x16x32_bf16 v[30:33], v[134:137], v[232:235], v[30:33]
	v_mfma_f32_16x16x32_bf16 v[26:29], v[142:145], v[232:235], v[26:29]
	v_mfma_f32_16x16x32_bf16 v[14:17], v[134:137], v[240:243], v[14:17]
	v_mfma_f32_16x16x32_bf16 v[10:13], v[142:145], v[240:243], v[10:13]
	s_setprio 0
	s_setprio 1
	v_mfma_f32_16x16x32_bf16 v[54:57], v[146:149], v[176:179], v[54:57]
	v_mfma_f32_16x16x32_bf16 v[50:53], v[168:171], v[176:179], v[50:53]
	v_mfma_f32_16x16x32_bf16 v[38:41], v[146:149], v[202:205], v[38:41]
	v_mfma_f32_16x16x32_bf16 v[34:37], v[168:171], v[202:205], v[34:37]
	v_mfma_f32_16x16x32_bf16 v[22:25], v[146:149], v[210:213], v[22:25]
	v_mfma_f32_16x16x32_bf16 v[18:21], v[168:171], v[210:213], v[18:21]
	v_mfma_f32_16x16x32_bf16 v[6:9], v[146:149], v[236:239], v[6:9]
	v_mfma_f32_16x16x32_bf16 v[2:5], v[168:171], v[236:239], v[2:5]
	v_mfma_f32_16x16x32_bf16 v[54:57], v[150:153], v[180:183], v[54:57]
	v_mfma_f32_16x16x32_bf16 v[50:53], v[172:175], v[180:183], v[50:53]
	v_mfma_f32_16x16x32_bf16 v[38:41], v[150:153], v[206:209], v[38:41]
	v_mfma_f32_16x16x32_bf16 v[34:37], v[172:175], v[206:209], v[34:37]
	v_mfma_f32_16x16x32_bf16 v[22:25], v[150:153], v[232:235], v[22:25]
	v_mfma_f32_16x16x32_bf16 v[18:21], v[172:175], v[232:235], v[18:21]
	v_mfma_f32_16x16x32_bf16 v[6:9], v[150:153], v[240:243], v[6:9]
	v_mfma_f32_16x16x32_bf16 v[2:5], v[172:175], v[240:243], v[2:5]
	s_setprio 0
	s_barrier
	s_add_i32 s51, s51, 2
	s_add_u32 s26, s26, 0x100
	s_addc_u32 s27, s27, 0
	s_add_u32 s49, s49, 0x100
	s_addc_u32 s50, s50, 0
	s_cmp_gt_u32 s51, 13
	s_cbranch_scc0 .LBB0_1270
	s_and_b64 vcc, exec, s[12:13]
	s_cbranch_vccz .LBB0_1273
	s_barrier

; #define PG8_STAGE(bufoff, gbase, voff) do { _Pragma("unroll") for (int _i = 0; _i < 2; ++_i) \
;         __builtin_amdgcn_global_load_lds((const unsigned*)((const char*)(gbase) + (voff)[_i]), (PG8_LAS unsigned*)(lds + (bufoff) + ldsw + _i * 8192), 16, 0, 0); } while (0)
; #define PG8_LDA(dst, b, h) do { _Pragma("unroll") for (int m = 0; m < 4; ++m) _Pragma("unroll") for (int k = 0; k < 2; ++k) dst[m][k] = *(const PG8_LAS bf16x8*)(lds + PG8_SA(b, h) + aoff + m * 2048 + k * 1024); } while (0)
; #define PG8_LDB(dst, b, h) do { _Pragma("unroll") for (int n = 0; n < 2; ++n) _Pragma("unroll") for (int k = 0; k < 2; ++k) dst[n][k] = *(const PG8_LAS bf16x8*)(lds + PG8_SB(b, h) + boff + n * 2048 + k * 1024); } while (0)
; #define PG8_MMA(ai, bj, At, Bt) do { __builtin_amdgcn_s_setprio(1); _Pragma("unroll") for (int m = 0; m < 4; ++m) _Pragma("unroll") for (int n = 0; n < 2; ++n) _Pragma("unroll") for (int k = 0; k < 2; ++k) \
;         acc[ai][bj][m][n] = __builtin_amdgcn_mfma_f32_16x16x32_bf16(Bt[n][k], At[m][k], acc[ai][bj][m][n], 0, 0, 0); __builtin_amdgcn_s_setprio(0); } while (0)
; #define PG8_WAIT_V(n) asm volatile("s_waitcnt vmcnt(" #n ")" ::: "memory")
; #define PG8_BAR __builtin_amdgcn_s_barrier()
; template <class Epi, class Sched, bool ALIGN_EPI = false, bool SP2 = false>
; __device__ __forceinline__ void gemm_phase(PG8_LAS unsigned char* lds, const Gemm g, const Sched& S, const Epi& E) {
;     ...
;         for (int t = 0; t < nt; t += 2) {
;             const bool last = (t == nt - 2);
;             const char* a1 = cA + (size_t)(t + 1) * kstep;
;             const char* a2 = last ? nA : cA + (size_t)(t + 2) * kstep; const char* b2 = last ? nB : cB + (size_t)(t + 2) * kstep;
;             const char* a3 = a2 + kstep; const char* b3 = b2 + kstep;
;             if (last && has_next) S.a_ready(nxt);
;             if constexpr (SP2) {
;             PG8_LDB(B0, 0, 0); PG8_LDB(B1, 0, 1); PG8_SCHED; PG8_LDA(At, 0, 0); PG8_STAGE(PG8_SA(1, 1), a1 + hstepA, voffA);
;             PG8_WAIT_V(8); PG8_WAIT_L(0); PG8_BAR; PG8_MMA(0, 0, At, B0); PG8_MMA(0, 1, At, B1); PG8_BAR; PG8_SCHED;
;             PG8_LDA(At, 0, 1); PG8_STAGE(PG8_SB(0, 0), b2, voffB); PG8_STAGE(PG8_SB(0, 1), b2 + hstepB, voffB); PG8_STAGE(PG8_SA(0, 0), a2, voffA);
;             PG8_WAIT_V(8); PG8_WAIT_L(0); PG8_BAR; PG8_MMA(1, 0, At, B0); PG8_MMA(1, 1, At, B1); PG8_BAR; PG8_SCHED;
.LBB0_1354:
	s_add_u32 s24, s22, 0xfffc0080
	s_addc_u32 s25, s23, -1
	s_add_i32 s49, 0, 0x10000
	s_cmp_eq_u32 s48, 12
	s_cselect_b32 s27, s15, s25
	s_cselect_b32 s26, s21, s24
	v_add_u32_e32 v142, s49, v145
	s_cselect_b32 s25, s13, s47
	s_cselect_b32 s24, s45, s46
	s_add_i32 s52, 0, 0x14000
	ds_read_b128 v[150:153], v142
	ds_read_b128 v[154:157], v142 offset:1024
	ds_read_b128 v[158:161], v142 offset:2048
	ds_read_b128 v[162:165], v142 offset:3072
	v_add_u32_e32 v142, s52, v145
	ds_read_b128 v[166:169], v142
	ds_read_b128 v[170:173], v142 offset:1024
	ds_read_b128 v[174:177], v142 offset:2048
	ds_read_b128 v[178:181], v142 offset:3072
	s_add_i32 m0, s36, 0xc000
	ds_read_b128 v[182:185], v148
	ds_read_b128 v[202:205], v148 offset:1024
	ds_read_b128 v[206:209], v148 offset:2048
	ds_read_b128 v[210:213], v148 offset:3072
	ds_read_b128 v[232:235], v148 offset:4096
	ds_read_b128 v[236:239], v148 offset:5120
	ds_read_b128 v[240:243], v148 offset:6144
	ds_read_b128 v[244:247], v148 offset:7168
	global_load_lds_dwordx4 v138, s[22:23]
	s_add_i32 m0, s36, 0xe000
	s_nop 0
	global_load_lds_dwordx4 v140, s[22:23]
	s_waitcnt vmcnt(8) lgkmcnt(0)
	s_barrier
	s_setprio 1
	v_mfma_f32_16x16x32_bf16 v[126:129], v[150:153], v[182:185], v[126:129]
	v_mfma_f32_16x16x32_bf16 v[122:125], v[158:161], v[182:185], v[122:125]
	v_mfma_f32_16x16x32_bf16 v[114:117], v[150:153], v[206:209], v[114:117]
	v_mfma_f32_16x16x32_bf16 v[106:109], v[158:161], v[206:209], v[106:109]
	v_mfma_f32_16x16x32_bf16 v[98:101], v[150:153], v[232:235], v[98:101]
	v_mfma_f32_16x16x32_bf16 v[90:93], v[158:161], v[232:235], v[90:93]
	v_mfma_f32_16x16x32_bf16 v[78:81], v[150:153], v[240:243], v[78:81]
	v_mfma_f32_16x16x32_bf16 v[74:77], v[158:161], v[240:243], v[74:77]
	v_mfma_f32_16x16x32_bf16 v[126:129], v[154:157], v[202:205], v[126:129]
	v_mfma_f32_16x16x32_bf16 v[122:125], v[162:165], v[202:205], v[122:125]
	v_mfma_f32_16x16x32_bf16 v[114:117], v[154:157], v[210:213], v[114:117]
	v_mfma_f32_16x16x32_bf16 v[106:109], v[162:165], v[210:213], v[106:109]
	v_mfma_f32_16x16x32_bf16 v[98:101], v[154:157], v[236:239], v[98:101]
	v_mfma_f32_16x16x32_bf16 v[90:93], v[162:165], v[236:239], v[90:93]
	v_mfma_f32_16x16x32_bf16 v[78:81], v[154:157], v[244:247], v[78:81]
	v_mfma_f32_16x16x32_bf16 v[74:77], v[162:165], v[244:247], v[74:77]
	s_setprio 0
	s_setprio 1
	v_mfma_f32_16x16x32_bf16 v[118:121], v[166:169], v[182:185], v[118:121]
	v_mfma_f32_16x16x32_bf16 v[110:113], v[174:177], v[182:185], v[110:113]
	v_mfma_f32_16x16x32_bf16 v[102:105], v[166:169], v[206:209], v[102:105]
	v_mfma_f32_16x16x32_bf16 v[94:97], v[174:177], v[206:209], v[94:97]
	v_mfma_f32_16x16x32_bf16 v[86:89], v[166:169], v[232:235], v[86:89]
	v_mfma_f32_16x16x32_bf16 v[82:85], v[174:177], v[232:235], v[82:85]
	v_mfma_f32_16x16x32_bf16 v[70:73], v[166:169], v[240:243], v[70:73]
	v_mfma_f32_16x16x32_bf16 v[66:69], v[174:177], v[240:243], v[66:69]
	v_mfma_f32_16x16x32_bf16 v[118:121], v[170:173], v[202:205], v[118:121]
	v_mfma_f32_16x16x32_bf16 v[110:113], v[178:181], v[202:205], v[110:113]
	v_mfma_f32_16x16x32_bf16 v[102:105], v[170:173], v[210:213], v[102:105]
	v_mfma_f32_16x16x32_bf16 v[94:97], v[178:181], v[210:213], v[94:97]
	v_mfma_f32_16x16x32_bf16 v[86:89], v[170:173], v[236:239], v[86:89]
	v_mfma_f32_16x16x32_bf16 v[82:85], v[178:181], v[236:239], v[82:85]
	v_mfma_f32_16x16x32_bf16 v[70:73], v[170:173], v[244:247], v[70:73]
	v_mfma_f32_16x16x32_bf16 v[66:69], v[178:181], v[244:247], v[66:69]
	s_setprio 0
	s_barrier
	s_add_i32 s49, s49, s34
	s_mov_b32 m0, s49
	ds_read_b128 v[182:185], v148 offset:16384
	ds_read_b128 v[202:205], v148 offset:17408
	ds_read_b128 v[206:209], v148 offset:18432
	ds_read_b128 v[210:213], v148 offset:19456
	ds_read_b128 v[232:235], v148 offset:20480
	ds_read_b128 v[236:239], v148 offset:21504
	ds_read_b128 v[240:243], v148 offset:22528
	ds_read_b128 v[244:247], v148 offset:23552
	s_add_u32 s60, s24, 0x80
	s_addc_u32 s61, s25, 0
	s_add_u32 s62, s26, 0x80
	s_addc_u32 s63, s27, 0
	global_load_lds_dwordx4 v134, s[24:25]
	s_add_i32 m0, s49, 0x2000
	s_add_u32 s50, s24, 0x40000
	s_addc_u32 s51, s25, 0
	s_add_i32 s49, s52, s34
	global_load_lds_dwordx4 v130, s[24:25]
	s_mov_b32 m0, s49
	s_nop 0
	global_load_lds_dwordx4 v134, s[50:51]
	s_add_i32 m0, s49, 0x2000
	s_nop 0
	global_load_lds_dwordx4 v130, s[50:51]
	s_mov_b32 m0, s36
	s_nop 0
	global_load_lds_dwordx4 v136, s[26:27]
	s_mov_b32 m0, s37
	s_nop 0
	global_load_lds_dwordx4 v132, s[26:27]
	s_waitcnt vmcnt(8) lgkmcnt(0)
	s_barrier
	s_setprio 1
	v_mfma_f32_16x16x32_bf16 v[62:65], v[150:153], v[182:185], v[62:65]
	v_mfma_f32_16x16x32_bf16 v[58:61], v[158:161], v[182:185], v[58:61]
	v_mfma_f32_16x16x32_bf16 v[46:49], v[150:153], v[206:209], v[46:49]
	v_mfma_f32_16x16x32_bf16 v[42:45], v[158:161], v[206:209], v[42:45]
	v_mfma_f32_16x16x32_bf16 v[30:33], v[150:153], v[232:235], v[30:33]
	v_mfma_f32_16x16x32_bf16 v[26:29], v[158:161], v[232:235], v[26:29]
	v_mfma_f32_16x16x32_bf16 v[14:17], v[150:153], v[240:243], v[14:17]
	v_mfma_f32_16x16x32_bf16 v[10:13], v[158:161], v[240:243], v[10:13]
	v_mfma_f32_16x16x32_bf16 v[62:65], v[154:157], v[202:205], v[62:65]
	v_mfma_f32_16x16x32_bf16 v[58:61], v[162:165], v[202:205], v[58:61]
	v_mfma_f32_16x16x32_bf16 v[46:49], v[154:157], v[210:213], v[46:49]
	v_mfma_f32_16x16x32_bf16 v[42:45], v[162:165], v[210:213], v[42:45]
	v_mfma_f32_16x16x32_bf16 v[30:33], v[154:157], v[236:239], v[30:33]
	v_mfma_f32_16x16x32_bf16 v[26:29], v[162:165], v[236:239], v[26:29]
	v_mfma_f32_16x16x32_bf16 v[14:17], v[154:157], v[244:247], v[14:17]
	v_mfma_f32_16x16x32_bf16 v[10:13], v[162:165], v[244:247], v[10:13]
	s_setprio 0
	s_setprio 1
	v_mfma_f32_16x16x32_bf16 v[54:57], v[166:169], v[182:185], v[54:57]
	v_mfma_f32_16x16x32_bf16 v[50:53], v[174:177], v[182:185], v[50:53]
	v_mfma_f32_16x16x32_bf16 v[38:41], v[166:169], v[206:209], v[38:41]
	v_mfma_f32_16x16x32_bf16 v[34:37], v[174:177], v[206:209], v[34:37]
	v_mfma_f32_16x16x32_bf16 v[22:25], v[166:169], v[232:235], v[22:25]
	v_mfma_f32_16x16x32_bf16 v[18:21], v[174:177], v[232:235], v[18:21]
	v_mfma_f32_16x16x32_bf16 v[6:9], v[166:169], v[240:243], v[6:9]
	v_mfma_f32_16x16x32_bf16 v[2:5], v[174:177], v[240:243], v[2:5]
	v_mfma_f32_16x16x32_bf16 v[54:57], v[170:173], v[202:205], v[54:57]
	v_mfma_f32_16x16x32_bf16 v[50:53], v[178:181], v[202:205], v[50:53]
	v_mfma_f32_16x16x32_bf16 v[38:41], v[170:173], v[210:213], v[38:41]
	v_mfma_f32_16x16x32_bf16 v[34:37], v[178:181], v[210:213], v[34:37]
	v_mfma_f32_16x16x32_bf16 v[22:25], v[170:173], v[236:239], v[22:25]
	v_mfma_f32_16x16x32_bf16 v[18:21], v[178:181], v[236:239], v[18:21]
	v_mfma_f32_16x16x32_bf16 v[6:9], v[170:173], v[244:247], v[6:9]
	v_mfma_f32_16x16x32_bf16 v[2:5], v[178:181], v[244:247], v[2:5]
	s_setprio 0
	s_barrier
; #define PG8_STAGE(bufoff, gbase, voff) do { _Pragma("unroll") for (int _i = 0; _i < 2; ++_i) \
;         __builtin_amdgcn_global_load_lds((const unsigned*)((const char*)(gbase) + (voff)[_i]), (PG8_LAS unsigned*)(lds + (bufoff) + ldsw + _i * 8192), 16, 0, 0); } while (0)
; #define PG8_LDA(dst, b, h) do { _Pragma("unroll") for (int m = 0; m < 4; ++m) _Pragma("unroll") for (int k = 0; k < 2; ++k) dst[m][k] = *(const PG8_LAS bf16x8*)(lds + PG8_SA(b, h) + aoff + m * 2048 + k * 1024); } while (0)
; #define PG8_LDB(dst, b, h) do { _Pragma("unroll") for (int n = 0; n < 2; ++n) _Pragma("unroll") for (int k = 0; k < 2; ++k) dst[n][k] = *(const PG8_LAS bf16x8*)(lds + PG8_SB(b, h) + boff + n * 2048 + k * 1024); } while (0)
; #define PG8_MMA(ai, bj, At, Bt) do { __builtin_amdgcn_s_setprio(1); _Pragma("unroll") for (int m = 0; m < 4; ++m) _Pragma("unroll") for (int n = 0; n < 2; ++n) _Pragma("unroll") for (int k = 0; k < 2; ++k) \
;         acc[ai][bj][m][n] = __builtin_amdgcn_mfma_f32_16x16x32_bf16(Bt[n][k], At[m][k], acc[ai][bj][m][n], 0, 0, 0); __builtin_amdgcn_s_setprio(0); } while (0)
; #define PG8_WAIT_V(n) asm volatile("s_waitcnt vmcnt(" #n ")" ::: "memory")
; #define PG8_WAIT_L(n) asm volatile("s_waitcnt lgkmcnt(" #n ")" ::: "memory")
; #define PG8_BAR __builtin_amdgcn_s_barrier()
; #define PG8_SCHED __builtin_amdgcn_sched_barrier(0)
; template <class Epi, class Sched, bool ALIGN_EPI = false, bool SP2 = false>
; __device__ __forceinline__ void gemm_phase(PG8_LAS unsigned char* lds, const Gemm g, const Sched& S, const Epi& E) {
;     ...
;             PG8_LDB(B0, 1, 0); PG8_LDB(B1, 1, 1); PG8_SCHED; PG8_LDA(At, 1, 0); PG8_STAGE(PG8_SA(0, 1), a2 + hstepA, voffA);
;             PG8_WAIT_V(8); PG8_WAIT_L(0); PG8_BAR; PG8_MMA(0, 0, At, B0); PG8_MMA(0, 1, At, B1); PG8_BAR; PG8_SCHED;
;             PG8_LDA(At, 1, 1); PG8_STAGE(PG8_SB(1, 0), b3, voffB); PG8_STAGE(PG8_SB(1, 1), b3 + hstepB, voffB); PG8_STAGE(PG8_SA(1, 0), a3, voffA);
;             PG8_WAIT_V(8); PG8_WAIT_L(0); PG8_BAR; PG8_MMA(1, 0, At, B0); PG8_MMA(1, 1, At, B1); PG8_BAR; PG8_SCHED;
;     ...
;         }
;         if constexpr (ALIGN_EPI) { if (wr == 0) PG8_BAR; }
	s_add_i32 s49, 0, 0x18000
	v_add_u32_e32 v144, s49, v145
	s_add_i32 s50, 0, 0x1c000
	ds_read_b128 v[150:153], v144
	ds_read_b128 v[154:157], v144 offset:1024
	ds_read_b128 v[158:161], v144 offset:2048
	ds_read_b128 v[162:165], v144 offset:3072
	v_add_u32_e32 v144, s50, v145
	ds_read_b128 v[166:169], v144
	ds_read_b128 v[170:173], v144 offset:1024
	ds_read_b128 v[174:177], v144 offset:2048
	ds_read_b128 v[178:181], v144 offset:3072
	s_add_u32 s26, s26, 0x40000
	s_addc_u32 s27, s27, 0
	s_mov_b32 m0, s38
	ds_read_b128 v[182:185], v148 offset:32768
	ds_read_b128 v[202:205], v148 offset:33792
	ds_read_b128 v[206:209], v148 offset:34816
	ds_read_b128 v[210:213], v148 offset:35840
	ds_read_b128 v[232:235], v148 offset:36864
	ds_read_b128 v[236:239], v148 offset:37888
	ds_read_b128 v[240:243], v148 offset:38912
	ds_read_b128 v[244:247], v148 offset:39936
	global_load_lds_dwordx4 v136, s[26:27]
	s_mov_b32 m0, s39
	s_nop 0
	global_load_lds_dwordx4 v132, s[26:27]
	s_waitcnt vmcnt(8) lgkmcnt(0)
	s_barrier
	s_setprio 1
	v_mfma_f32_16x16x32_bf16 v[126:129], v[150:153], v[182:185], v[126:129]
	v_mfma_f32_16x16x32_bf16 v[122:125], v[158:161], v[182:185], v[122:125]
	v_mfma_f32_16x16x32_bf16 v[114:117], v[150:153], v[206:209], v[114:117]
	v_mfma_f32_16x16x32_bf16 v[106:109], v[158:161], v[206:209], v[106:109]
	v_mfma_f32_16x16x32_bf16 v[98:101], v[150:153], v[232:235], v[98:101]
	v_mfma_f32_16x16x32_bf16 v[90:93], v[158:161], v[232:235], v[90:93]
	v_mfma_f32_16x16x32_bf16 v[78:81], v[150:153], v[240:243], v[78:81]
	v_mfma_f32_16x16x32_bf16 v[74:77], v[158:161], v[240:243], v[74:77]
	v_mfma_f32_16x16x32_bf16 v[126:129], v[154:157], v[202:205], v[126:129]
	v_mfma_f32_16x16x32_bf16 v[122:125], v[162:165], v[202:205], v[122:125]
	v_mfma_f32_16x16x32_bf16 v[114:117], v[154:157], v[210:213], v[114:117]
	v_mfma_f32_16x16x32_bf16 v[106:109], v[162:165], v[210:213], v[106:109]
	v_mfma_f32_16x16x32_bf16 v[98:101], v[154:157], v[236:239], v[98:101]
	v_mfma_f32_16x16x32_bf16 v[90:93], v[162:165], v[236:239], v[90:93]
	v_mfma_f32_16x16x32_bf16 v[78:81], v[154:157], v[244:247], v[78:81]
	v_mfma_f32_16x16x32_bf16 v[74:77], v[162:165], v[244:247], v[74:77]
	s_setprio 0
	s_setprio 1
	v_mfma_f32_16x16x32_bf16 v[118:121], v[166:169], v[182:185], v[118:121]
	v_mfma_f32_16x16x32_bf16 v[110:113], v[174:177], v[182:185], v[110:113]
	v_mfma_f32_16x16x32_bf16 v[102:105], v[166:169], v[206:209], v[102:105]
	v_mfma_f32_16x16x32_bf16 v[94:97], v[174:177], v[206:209], v[94:97]
	v_mfma_f32_16x16x32_bf16 v[86:89], v[166:169], v[232:235], v[86:89]
	v_mfma_f32_16x16x32_bf16 v[82:85], v[174:177], v[232:235], v[82:85]
	v_mfma_f32_16x16x32_bf16 v[70:73], v[166:169], v[240:243], v[70:73]
	v_mfma_f32_16x16x32_bf16 v[66:69], v[174:177], v[240:243], v[66:69]
	v_mfma_f32_16x16x32_bf16 v[118:121], v[170:173], v[202:205], v[118:121]
	v_mfma_f32_16x16x32_bf16 v[110:113], v[178:181], v[202:205], v[110:113]
	v_mfma_f32_16x16x32_bf16 v[102:105], v[170:173], v[210:213], v[102:105]
	v_mfma_f32_16x16x32_bf16 v[94:97], v[178:181], v[210:213], v[94:97]
	v_mfma_f32_16x16x32_bf16 v[86:89], v[170:173], v[236:239], v[86:89]
	v_mfma_f32_16x16x32_bf16 v[82:85], v[178:181], v[236:239], v[82:85]
	v_mfma_f32_16x16x32_bf16 v[70:73], v[170:173], v[244:247], v[70:73]
	v_mfma_f32_16x16x32_bf16 v[66:69], v[178:181], v[244:247], v[66:69]
	s_setprio 0
	s_barrier
	s_add_i32 s26, s49, s34
	s_mov_b32 m0, s26
	ds_read_b128 v[182:185], v148 offset:49152
	ds_read_b128 v[202:205], v148 offset:50176
	ds_read_b128 v[206:209], v148 offset:51200
	ds_read_b128 v[210:213], v148 offset:52224
	ds_read_b128 v[232:235], v148 offset:53248
	ds_read_b128 v[236:239], v148 offset:54272
	ds_read_b128 v[240:243], v148 offset:55296
	ds_read_b128 v[244:247], v148 offset:56320
	global_load_lds_dwordx4 v134, s[60:61]
	s_add_i32 m0, s26, 0x2000
	s_add_u32 s24, s24, 0x40080
	s_addc_u32 s25, s25, 0
	s_add_i32 s26, s50, s34
	global_load_lds_dwordx4 v130, s[60:61]
	s_mov_b32 m0, s26
	s_nop 0
	global_load_lds_dwordx4 v134, s[24:25]
	s_add_i32 m0, s26, 0x2000
	s_nop 0
	global_load_lds_dwordx4 v130, s[24:25]
	s_mov_b32 m0, s40
	s_nop 0
	global_load_lds_dwordx4 v136, s[62:63]
	s_mov_b32 m0, s41
	s_nop 0
	global_load_lds_dwordx4 v132, s[62:63]
	s_waitcnt vmcnt(8) lgkmcnt(0)
	s_barrier
	s_setprio 1
	v_mfma_f32_16x16x32_bf16 v[62:65], v[150:153], v[182:185], v[62:65]
	v_mfma_f32_16x16x32_bf16 v[58:61], v[158:161], v[182:185], v[58:61]
	v_mfma_f32_16x16x32_bf16 v[46:49], v[150:153], v[206:209], v[46:49]
	v_mfma_f32_16x16x32_bf16 v[42:45], v[158:161], v[206:209], v[42:45]
	v_mfma_f32_16x16x32_bf16 v[30:33], v[150:153], v[232:235], v[30:33]
	v_mfma_f32_16x16x32_bf16 v[26:29], v[158:161], v[232:235], v[26:29]
	v_mfma_f32_16x16x32_bf16 v[14:17], v[150:153], v[240:243], v[14:17]
	v_mfma_f32_16x16x32_bf16 v[10:13], v[158:161], v[240:243], v[10:13]
	v_mfma_f32_16x16x32_bf16 v[62:65], v[154:157], v[202:205], v[62:65]
	v_mfma_f32_16x16x32_bf16 v[58:61], v[162:165], v[202:205], v[58:61]
	v_mfma_f32_16x16x32_bf16 v[46:49], v[154:157], v[210:213], v[46:49]
	v_mfma_f32_16x16x32_bf16 v[42:45], v[162:165], v[210:213], v[42:45]
	v_mfma_f32_16x16x32_bf16 v[30:33], v[154:157], v[236:239], v[30:33]
	v_mfma_f32_16x16x32_bf16 v[26:29], v[162:165], v[236:239], v[26:29]
	v_mfma_f32_16x16x32_bf16 v[14:17], v[154:157], v[244:247], v[14:17]
	v_mfma_f32_16x16x32_bf16 v[10:13], v[162:165], v[244:247], v[10:13]
	s_setprio 0
	s_setprio 1
	v_mfma_f32_16x16x32_bf16 v[54:57], v[166:169], v[182:185], v[54:57]
	v_mfma_f32_16x16x32_bf16 v[50:53], v[174:177], v[182:185], v[50:53]
	v_mfma_f32_16x16x32_bf16 v[38:41], v[166:169], v[206:209], v[38:41]
	v_mfma_f32_16x16x32_bf16 v[34:37], v[174:177], v[206:209], v[34:37]
	v_mfma_f32_16x16x32_bf16 v[22:25], v[166:169], v[232:235], v[22:25]
	v_mfma_f32_16x16x32_bf16 v[18:21], v[174:177], v[232:235], v[18:21]
	v_mfma_f32_16x16x32_bf16 v[6:9], v[166:169], v[240:243], v[6:9]
	v_mfma_f32_16x16x32_bf16 v[2:5], v[174:177], v[240:243], v[2:5]
	v_mfma_f32_16x16x32_bf16 v[54:57], v[170:173], v[202:205], v[54:57]
	v_mfma_f32_16x16x32_bf16 v[50:53], v[178:181], v[202:205], v[50:53]
	v_mfma_f32_16x16x32_bf16 v[38:41], v[170:173], v[210:213], v[38:41]
	v_mfma_f32_16x16x32_bf16 v[34:37], v[178:181], v[210:213], v[34:37]
	v_mfma_f32_16x16x32_bf16 v[22:25], v[170:173], v[236:239], v[22:25]
	v_mfma_f32_16x16x32_bf16 v[18:21], v[178:181], v[236:239], v[18:21]
	v_mfma_f32_16x16x32_bf16 v[6:9], v[170:173], v[244:247], v[6:9]
	v_mfma_f32_16x16x32_bf16 v[2:5], v[178:181], v[244:247], v[2:5]
	s_setprio 0
	s_barrier
	s_add_i32 s48, s48, 2
	s_add_u32 s22, s22, 0x100
	s_addc_u32 s23, s23, 0
	s_add_u32 s46, s46, 0x100
	s_addc_u32 s47, s47, 0
	s_cmp_gt_u32 s48, 13
	s_cbranch_scc0 .LBB0_1354
	s_and_b64 vcc, exec, s[10:11]
	s_cbranch_vccz .LBB0_1357
	s_barrier

; #define PG8_STAGE(bufoff, gbase, voff) do { _Pragma("unroll") for (int _i = 0; _i < 2; ++_i) \
;         __builtin_amdgcn_global_load_lds((const unsigned*)((const char*)(gbase) + (voff)[_i]), (PG8_LAS unsigned*)(lds + (bufoff) + ldsw + _i * 8192), 16, 0, 0); } while (0)
; #define PG8_LDA(dst, b, h) do { _Pragma("unroll") for (int m = 0; m < 4; ++m) _Pragma("unroll") for (int k = 0; k < 2; ++k) dst[m][k] = *(const PG8_LAS bf16x8*)(lds + PG8_SA(b, h) + aoff + m * 2048 + k * 1024); } while (0)
; #define PG8_LDB(dst, b, h) do { _Pragma("unroll") for (int n = 0; n < 2; ++n) _Pragma("unroll") for (int k = 0; k < 2; ++k) dst[n][k] = *(const PG8_LAS bf16x8*)(lds + PG8_SB(b, h) + boff + n * 2048 + k * 1024); } while (0)
; #define PG8_MMA(ai, bj, At, Bt) do { __builtin_amdgcn_s_setprio(1); _Pragma("unroll") for (int m = 0; m < 4; ++m) _Pragma("unroll") for (int n = 0; n < 2; ++n) _Pragma("unroll") for (int k = 0; k < 2; ++k) \
;         acc[ai][bj][m][n] = __builtin_amdgcn_mfma_f32_16x16x32_bf16(Bt[n][k], At[m][k], acc[ai][bj][m][n], 0, 0, 0); __builtin_amdgcn_s_setprio(0); } while (0)
; #define PG8_WAIT_V(n) asm volatile("s_waitcnt vmcnt(" #n ")" ::: "memory")
; #define PG8_BAR __builtin_amdgcn_s_barrier()
; template <class Epi, class Sched, bool ALIGN_EPI = false, bool SP2 = false>
; __device__ __forceinline__ void gemm_phase(PG8_LAS unsigned char* lds, const Gemm g, const Sched& S, const Epi& E) {
;     ...
;         for (int t = 0; t < nt; t += 2) {
;             const bool last = (t == nt - 2);
;             const char* a1 = cA + (size_t)(t + 1) * kstep;
;             const char* a2 = last ? nA : cA + (size_t)(t + 2) * kstep; const char* b2 = last ? nB : cB + (size_t)(t + 2) * kstep;
;             const char* a3 = a2 + kstep; const char* b3 = b2 + kstep;
;             if (last && has_next) S.a_ready(nxt);
;             if constexpr (SP2) {
;             PG8_LDB(B0, 0, 0); PG8_LDB(B1, 0, 1); PG8_SCHED; PG8_LDA(At, 0, 0); PG8_STAGE(PG8_SA(1, 1), a1 + hstepA, voffA);
;             PG8_WAIT_V(8); PG8_WAIT_L(0); PG8_BAR; PG8_MMA(0, 0, At, B0); PG8_MMA(0, 1, At, B1); PG8_BAR; PG8_SCHED;
;             PG8_LDA(At, 0, 1); PG8_STAGE(PG8_SB(0, 0), b2, voffB); PG8_STAGE(PG8_SB(0, 1), b2 + hstepB, voffB); PG8_STAGE(PG8_SA(0, 0), a2, voffA);
;             PG8_WAIT_V(8); PG8_WAIT_L(0); PG8_BAR; PG8_MMA(1, 0, At, B0); PG8_MMA(1, 1, At, B1); PG8_BAR; PG8_SCHED;
.LBB0_1438:
	s_add_u32 s20, s18, 0x100
	s_addc_u32 s21, s19, 0
	s_add_i32 s50, 0, 0x10000
	s_cmp_eq_u32 s49, 40
	s_cselect_b32 s25, s9, s21
	s_cselect_b32 s24, s8, s20
	s_cselect_b32 s23, s17, s48
	s_cselect_b32 s22, s16, s47
	s_add_i32 s51, 0, 0x14000
	v_add_u32_e32 v142, s50, v186
	v_add_u32_e32 v172, s51, v186
	ds_read_b128 v[130:133], v142
	ds_read_b128 v[134:137], v142 offset:1024
	ds_read_b128 v[138:141], v142 offset:2048
	ds_read_b128 v[142:145], v142 offset:3072
	ds_read_b128 v[146:149], v172
	ds_read_b128 v[150:153], v172 offset:1024
	ds_read_b128 v[168:171], v172 offset:2048
	ds_read_b128 v[172:175], v172 offset:3072
	s_add_i32 m0, s31, 0xc000
	ds_read_b128 v[176:179], v200
	ds_read_b128 v[180:183], v200 offset:1024
	ds_read_b128 v[202:205], v200 offset:2048
	ds_read_b128 v[206:209], v200 offset:3072
	ds_read_b128 v[210:213], v200 offset:4096
	ds_read_b128 v[232:235], v200 offset:5120
	ds_read_b128 v[236:239], v200 offset:6144
	ds_read_b128 v[240:243], v200 offset:7168
	global_load_lds_dwordx4 v164, s[18:19]
	s_add_i32 m0, s31, 0xe000
	s_nop 0
	global_load_lds_dwordx4 v166, s[18:19]
	s_waitcnt vmcnt(8) lgkmcnt(0)
	s_barrier
	s_setprio 1
	v_mfma_f32_16x16x32_bf16 v[126:129], v[130:133], v[176:179], v[126:129]
	v_mfma_f32_16x16x32_bf16 v[122:125], v[138:141], v[176:179], v[122:125]
	v_mfma_f32_16x16x32_bf16 v[110:113], v[130:133], v[202:205], v[110:113]
	v_mfma_f32_16x16x32_bf16 v[106:109], v[138:141], v[202:205], v[106:109]
	v_mfma_f32_16x16x32_bf16 v[94:97], v[130:133], v[210:213], v[94:97]
	v_mfma_f32_16x16x32_bf16 v[90:93], v[138:141], v[210:213], v[90:93]
	v_mfma_f32_16x16x32_bf16 v[78:81], v[130:133], v[236:239], v[78:81]
	v_mfma_f32_16x16x32_bf16 v[74:77], v[138:141], v[236:239], v[74:77]
	v_mfma_f32_16x16x32_bf16 v[126:129], v[134:137], v[180:183], v[126:129]
	v_mfma_f32_16x16x32_bf16 v[122:125], v[142:145], v[180:183], v[122:125]
	v_mfma_f32_16x16x32_bf16 v[110:113], v[134:137], v[206:209], v[110:113]
	v_mfma_f32_16x16x32_bf16 v[106:109], v[142:145], v[206:209], v[106:109]
	v_mfma_f32_16x16x32_bf16 v[94:97], v[134:137], v[232:235], v[94:97]
	v_mfma_f32_16x16x32_bf16 v[90:93], v[142:145], v[232:235], v[90:93]
	v_mfma_f32_16x16x32_bf16 v[78:81], v[134:137], v[240:243], v[78:81]
	v_mfma_f32_16x16x32_bf16 v[74:77], v[142:145], v[240:243], v[74:77]
	s_setprio 0
	s_setprio 1
	v_mfma_f32_16x16x32_bf16 v[118:121], v[146:149], v[176:179], v[118:121]
	v_mfma_f32_16x16x32_bf16 v[114:117], v[168:171], v[176:179], v[114:117]
	v_mfma_f32_16x16x32_bf16 v[102:105], v[146:149], v[202:205], v[102:105]
	v_mfma_f32_16x16x32_bf16 v[98:101], v[168:171], v[202:205], v[98:101]
	v_mfma_f32_16x16x32_bf16 v[86:89], v[146:149], v[210:213], v[86:89]
	v_mfma_f32_16x16x32_bf16 v[82:85], v[168:171], v[210:213], v[82:85]
	v_mfma_f32_16x16x32_bf16 v[70:73], v[146:149], v[236:239], v[70:73]
	v_mfma_f32_16x16x32_bf16 v[66:69], v[168:171], v[236:239], v[66:69]
	v_mfma_f32_16x16x32_bf16 v[118:121], v[150:153], v[180:183], v[118:121]
	v_mfma_f32_16x16x32_bf16 v[114:117], v[172:175], v[180:183], v[114:117]
	v_mfma_f32_16x16x32_bf16 v[102:105], v[150:153], v[206:209], v[102:105]
	v_mfma_f32_16x16x32_bf16 v[98:101], v[172:175], v[206:209], v[98:101]
	v_mfma_f32_16x16x32_bf16 v[86:89], v[150:153], v[232:235], v[86:89]
	v_mfma_f32_16x16x32_bf16 v[82:85], v[172:175], v[232:235], v[82:85]
	v_mfma_f32_16x16x32_bf16 v[70:73], v[150:153], v[240:243], v[70:73]
	v_mfma_f32_16x16x32_bf16 v[66:69], v[172:175], v[240:243], v[66:69]
	s_setprio 0
	s_barrier
	s_add_i32 s18, s50, s30
	s_mov_b32 m0, s18
	ds_read_b128 v[176:179], v200 offset:16384
	ds_read_b128 v[180:183], v200 offset:17408
	ds_read_b128 v[202:205], v200 offset:18432
	ds_read_b128 v[206:209], v200 offset:19456
	ds_read_b128 v[210:213], v200 offset:20480
	ds_read_b128 v[232:235], v200 offset:21504
	ds_read_b128 v[236:239], v200 offset:22528
	ds_read_b128 v[240:243], v200 offset:23552
	s_add_u32 s60, s22, 0x80
	s_addc_u32 s61, s23, 0
	s_add_u32 s62, s24, 0x80
	s_addc_u32 s63, s25, 0
	global_load_lds_dwordx4 v156, s[22:23]
	s_add_i32 m0, s18, 0x2000
	s_add_u32 s18, s22, 0xb0000
	s_addc_u32 s19, s23, 0
	s_add_i32 s50, s51, s30
	global_load_lds_dwordx4 v160, s[22:23]
	s_mov_b32 m0, s50
	s_nop 0
	global_load_lds_dwordx4 v156, s[18:19]
	s_add_i32 m0, s50, 0x2000
	s_nop 0
	global_load_lds_dwordx4 v160, s[18:19]
	s_mov_b32 m0, s31
	s_nop 0
	global_load_lds_dwordx4 v154, s[24:25]
	s_mov_b32 m0, s34
	s_nop 0
	global_load_lds_dwordx4 v158, s[24:25]
	s_waitcnt vmcnt(8) lgkmcnt(0)
	s_barrier
	s_setprio 1
	v_mfma_f32_16x16x32_bf16 v[62:65], v[130:133], v[176:179], v[62:65]
	v_mfma_f32_16x16x32_bf16 v[58:61], v[138:141], v[176:179], v[58:61]
	v_mfma_f32_16x16x32_bf16 v[46:49], v[130:133], v[202:205], v[46:49]
	v_mfma_f32_16x16x32_bf16 v[42:45], v[138:141], v[202:205], v[42:45]
	v_mfma_f32_16x16x32_bf16 v[30:33], v[130:133], v[210:213], v[30:33]
	v_mfma_f32_16x16x32_bf16 v[26:29], v[138:141], v[210:213], v[26:29]
	v_mfma_f32_16x16x32_bf16 v[14:17], v[130:133], v[236:239], v[14:17]
	v_mfma_f32_16x16x32_bf16 v[10:13], v[138:141], v[236:239], v[10:13]
	v_mfma_f32_16x16x32_bf16 v[62:65], v[134:137], v[180:183], v[62:65]
	v_mfma_f32_16x16x32_bf16 v[58:61], v[142:145], v[180:183], v[58:61]
	v_mfma_f32_16x16x32_bf16 v[46:49], v[134:137], v[206:209], v[46:49]
	v_mfma_f32_16x16x32_bf16 v[42:45], v[142:145], v[206:209], v[42:45]
	v_mfma_f32_16x16x32_bf16 v[30:33], v[134:137], v[232:235], v[30:33]
	v_mfma_f32_16x16x32_bf16 v[26:29], v[142:145], v[232:235], v[26:29]
	v_mfma_f32_16x16x32_bf16 v[14:17], v[134:137], v[240:243], v[14:17]
	v_mfma_f32_16x16x32_bf16 v[10:13], v[142:145], v[240:243], v[10:13]
	s_setprio 0
	s_setprio 1
	v_mfma_f32_16x16x32_bf16 v[54:57], v[146:149], v[176:179], v[54:57]
	v_mfma_f32_16x16x32_bf16 v[50:53], v[168:171], v[176:179], v[50:53]
	v_mfma_f32_16x16x32_bf16 v[38:41], v[146:149], v[202:205], v[38:41]
	v_mfma_f32_16x16x32_bf16 v[34:37], v[168:171], v[202:205], v[34:37]
	v_mfma_f32_16x16x32_bf16 v[22:25], v[146:149], v[210:213], v[22:25]
	v_mfma_f32_16x16x32_bf16 v[18:21], v[168:171], v[210:213], v[18:21]
	v_mfma_f32_16x16x32_bf16 v[6:9], v[146:149], v[236:239], v[6:9]
	v_mfma_f32_16x16x32_bf16 v[2:5], v[168:171], v[236:239], v[2:5]
	v_mfma_f32_16x16x32_bf16 v[54:57], v[150:153], v[180:183], v[54:57]
	v_mfma_f32_16x16x32_bf16 v[50:53], v[172:175], v[180:183], v[50:53]
	v_mfma_f32_16x16x32_bf16 v[38:41], v[150:153], v[206:209], v[38:41]
	v_mfma_f32_16x16x32_bf16 v[34:37], v[172:175], v[206:209], v[34:37]
	v_mfma_f32_16x16x32_bf16 v[22:25], v[150:153], v[232:235], v[22:25]
	v_mfma_f32_16x16x32_bf16 v[18:21], v[172:175], v[232:235], v[18:21]
	v_mfma_f32_16x16x32_bf16 v[6:9], v[150:153], v[240:243], v[6:9]
	v_mfma_f32_16x16x32_bf16 v[2:5], v[172:175], v[240:243], v[2:5]
	s_setprio 0
	s_barrier
; #define PG8_STAGE(bufoff, gbase, voff) do { _Pragma("unroll") for (int _i = 0; _i < 2; ++_i) \
;         __builtin_amdgcn_global_load_lds((const unsigned*)((const char*)(gbase) + (voff)[_i]), (PG8_LAS unsigned*)(lds + (bufoff) + ldsw + _i * 8192), 16, 0, 0); } while (0)
; #define PG8_LDA(dst, b, h) do { _Pragma("unroll") for (int m = 0; m < 4; ++m) _Pragma("unroll") for (int k = 0; k < 2; ++k) dst[m][k] = *(const PG8_LAS bf16x8*)(lds + PG8_SA(b, h) + aoff + m * 2048 + k * 1024); } while (0)
; #define PG8_LDB(dst, b, h) do { _Pragma("unroll") for (int n = 0; n < 2; ++n) _Pragma("unroll") for (int k = 0; k < 2; ++k) dst[n][k] = *(const PG8_LAS bf16x8*)(lds + PG8_SB(b, h) + boff + n * 2048 + k * 1024); } while (0)
; #define PG8_MMA(ai, bj, At, Bt) do { __builtin_amdgcn_s_setprio(1); _Pragma("unroll") for (int m = 0; m < 4; ++m) _Pragma("unroll") for (int n = 0; n < 2; ++n) _Pragma("unroll") for (int k = 0; k < 2; ++k) \
;         acc[ai][bj][m][n] = __builtin_amdgcn_mfma_f32_16x16x32_bf16(Bt[n][k], At[m][k], acc[ai][bj][m][n], 0, 0, 0); __builtin_amdgcn_s_setprio(0); } while (0)
; #define PG8_WAIT_V(n) asm volatile("s_waitcnt vmcnt(" #n ")" ::: "memory")
; #define PG8_WAIT_L(n) asm volatile("s_waitcnt lgkmcnt(" #n ")" ::: "memory")
; #define PG8_BAR __builtin_amdgcn_s_barrier()
; #define PG8_SCHED __builtin_amdgcn_sched_barrier(0)
; template <class Epi, class Sched, bool ALIGN_EPI = false, bool SP2 = false>
; __device__ __forceinline__ void gemm_phase(PG8_LAS unsigned char* lds, const Gemm g, const Sched& S, const Epi& E) {
;     ...
;             PG8_LDB(B0, 1, 0); PG8_LDB(B1, 1, 1); PG8_SCHED; PG8_LDA(At, 1, 0); PG8_STAGE(PG8_SA(0, 1), a2 + hstepA, voffA);
;             PG8_WAIT_V(8); PG8_WAIT_L(0); PG8_BAR; PG8_MMA(0, 0, At, B0); PG8_MMA(0, 1, At, B1); PG8_BAR; PG8_SCHED;
;             PG8_LDA(At, 1, 1); PG8_STAGE(PG8_SB(1, 0), b3, voffB); PG8_STAGE(PG8_SB(1, 1), b3 + hstepB, voffB); PG8_STAGE(PG8_SA(1, 0), a3, voffA);
;             PG8_WAIT_V(8); PG8_WAIT_L(0); PG8_BAR; PG8_MMA(1, 0, At, B0); PG8_MMA(1, 1, At, B1); PG8_BAR; PG8_SCHED;
;     ...
;         }
;         if constexpr (ALIGN_EPI) { if (wr == 0) PG8_BAR; }
	s_add_i32 s50, 0, 0x18000
	s_add_i32 s51, 0, 0x1c000
	v_add_u32_e32 v142, s50, v186
	v_add_u32_e32 v172, s51, v186
	ds_read_b128 v[130:133], v142
	ds_read_b128 v[134:137], v142 offset:1024
	ds_read_b128 v[138:141], v142 offset:2048
	ds_read_b128 v[142:145], v142 offset:3072
	ds_read_b128 v[146:149], v172
	ds_read_b128 v[150:153], v172 offset:1024
	ds_read_b128 v[168:171], v172 offset:2048
	ds_read_b128 v[172:175], v172 offset:3072
	s_add_u32 s18, s24, 0xb0000
	s_addc_u32 s19, s25, 0
	s_mov_b32 m0, s35
	ds_read_b128 v[176:179], v200 offset:32768
	ds_read_b128 v[180:183], v200 offset:33792
	ds_read_b128 v[202:205], v200 offset:34816
	ds_read_b128 v[206:209], v200 offset:35840
	ds_read_b128 v[210:213], v200 offset:36864
	ds_read_b128 v[232:235], v200 offset:37888
	ds_read_b128 v[236:239], v200 offset:38912
	ds_read_b128 v[240:243], v200 offset:39936
	global_load_lds_dwordx4 v154, s[18:19]
	s_mov_b32 m0, s36
	s_nop 0
	global_load_lds_dwordx4 v158, s[18:19]
	s_waitcnt vmcnt(8) lgkmcnt(0)
	s_barrier
	s_setprio 1
	v_mfma_f32_16x16x32_bf16 v[126:129], v[130:133], v[176:179], v[126:129]
	v_mfma_f32_16x16x32_bf16 v[122:125], v[138:141], v[176:179], v[122:125]
	v_mfma_f32_16x16x32_bf16 v[110:113], v[130:133], v[202:205], v[110:113]
	v_mfma_f32_16x16x32_bf16 v[106:109], v[138:141], v[202:205], v[106:109]
	v_mfma_f32_16x16x32_bf16 v[94:97], v[130:133], v[210:213], v[94:97]
	v_mfma_f32_16x16x32_bf16 v[90:93], v[138:141], v[210:213], v[90:93]
	v_mfma_f32_16x16x32_bf16 v[78:81], v[130:133], v[236:239], v[78:81]
	v_mfma_f32_16x16x32_bf16 v[74:77], v[138:141], v[236:239], v[74:77]
	v_mfma_f32_16x16x32_bf16 v[126:129], v[134:137], v[180:183], v[126:129]
	v_mfma_f32_16x16x32_bf16 v[122:125], v[142:145], v[180:183], v[122:125]
	v_mfma_f32_16x16x32_bf16 v[110:113], v[134:137], v[206:209], v[110:113]
	v_mfma_f32_16x16x32_bf16 v[106:109], v[142:145], v[206:209], v[106:109]
	v_mfma_f32_16x16x32_bf16 v[94:97], v[134:137], v[232:235], v[94:97]
	v_mfma_f32_16x16x32_bf16 v[90:93], v[142:145], v[232:235], v[90:93]
	v_mfma_f32_16x16x32_bf16 v[78:81], v[134:137], v[240:243], v[78:81]
	v_mfma_f32_16x16x32_bf16 v[74:77], v[142:145], v[240:243], v[74:77]
	s_setprio 0
	s_setprio 1
	v_mfma_f32_16x16x32_bf16 v[118:121], v[146:149], v[176:179], v[118:121]
	v_mfma_f32_16x16x32_bf16 v[114:117], v[168:171], v[176:179], v[114:117]
	v_mfma_f32_16x16x32_bf16 v[102:105], v[146:149], v[202:205], v[102:105]
	v_mfma_f32_16x16x32_bf16 v[98:101], v[168:171], v[202:205], v[98:101]
	v_mfma_f32_16x16x32_bf16 v[86:89], v[146:149], v[210:213], v[86:89]
	v_mfma_f32_16x16x32_bf16 v[82:85], v[168:171], v[210:213], v[82:85]
	v_mfma_f32_16x16x32_bf16 v[70:73], v[146:149], v[236:239], v[70:73]
	v_mfma_f32_16x16x32_bf16 v[66:69], v[168:171], v[236:239], v[66:69]
	v_mfma_f32_16x16x32_bf16 v[118:121], v[150:153], v[180:183], v[118:121]
	v_mfma_f32_16x16x32_bf16 v[114:117], v[172:175], v[180:183], v[114:117]
	v_mfma_f32_16x16x32_bf16 v[102:105], v[150:153], v[206:209], v[102:105]
	v_mfma_f32_16x16x32_bf16 v[98:101], v[172:175], v[206:209], v[98:101]
	v_mfma_f32_16x16x32_bf16 v[86:89], v[150:153], v[232:235], v[86:89]
	v_mfma_f32_16x16x32_bf16 v[82:85], v[172:175], v[232:235], v[82:85]
	v_mfma_f32_16x16x32_bf16 v[70:73], v[150:153], v[240:243], v[70:73]
	v_mfma_f32_16x16x32_bf16 v[66:69], v[172:175], v[240:243], v[66:69]
	s_setprio 0
	s_barrier
	s_add_i32 s18, s50, s30
	s_mov_b32 m0, s18
	ds_read_b128 v[176:179], v200 offset:49152
	ds_read_b128 v[180:183], v200 offset:50176
	ds_read_b128 v[202:205], v200 offset:51200
	ds_read_b128 v[206:209], v200 offset:52224
	ds_read_b128 v[210:213], v200 offset:53248
	ds_read_b128 v[232:235], v200 offset:54272
	ds_read_b128 v[236:239], v200 offset:55296
	ds_read_b128 v[240:243], v200 offset:56320
	global_load_lds_dwordx4 v156, s[60:61]
	s_add_i32 m0, s18, 0x2000
	s_add_u32 s18, s22, 0xb0080
	s_addc_u32 s19, s23, 0
	s_add_i32 s22, s51, s30
	global_load_lds_dwordx4 v160, s[60:61]
	s_mov_b32 m0, s22
	s_nop 0
	global_load_lds_dwordx4 v156, s[18:19]
	s_add_i32 m0, s22, 0x2000
	s_nop 0
	global_load_lds_dwordx4 v160, s[18:19]
	s_mov_b32 m0, s38
	s_nop 0
	global_load_lds_dwordx4 v154, s[62:63]
	s_mov_b32 m0, s39
	s_nop 0
	global_load_lds_dwordx4 v158, s[62:63]
	s_waitcnt vmcnt(8) lgkmcnt(0)
	s_barrier
	s_setprio 1
	v_mfma_f32_16x16x32_bf16 v[62:65], v[130:133], v[176:179], v[62:65]
	v_mfma_f32_16x16x32_bf16 v[58:61], v[138:141], v[176:179], v[58:61]
	v_mfma_f32_16x16x32_bf16 v[46:49], v[130:133], v[202:205], v[46:49]
	v_mfma_f32_16x16x32_bf16 v[42:45], v[138:141], v[202:205], v[42:45]
	v_mfma_f32_16x16x32_bf16 v[30:33], v[130:133], v[210:213], v[30:33]
	v_mfma_f32_16x16x32_bf16 v[26:29], v[138:141], v[210:213], v[26:29]
	v_mfma_f32_16x16x32_bf16 v[14:17], v[130:133], v[236:239], v[14:17]
	v_mfma_f32_16x16x32_bf16 v[10:13], v[138:141], v[236:239], v[10:13]
	v_mfma_f32_16x16x32_bf16 v[62:65], v[134:137], v[180:183], v[62:65]
	v_mfma_f32_16x16x32_bf16 v[58:61], v[142:145], v[180:183], v[58:61]
	v_mfma_f32_16x16x32_bf16 v[46:49], v[134:137], v[206:209], v[46:49]
	v_mfma_f32_16x16x32_bf16 v[42:45], v[142:145], v[206:209], v[42:45]
	v_mfma_f32_16x16x32_bf16 v[30:33], v[134:137], v[232:235], v[30:33]
	v_mfma_f32_16x16x32_bf16 v[26:29], v[142:145], v[232:235], v[26:29]
	v_mfma_f32_16x16x32_bf16 v[14:17], v[134:137], v[240:243], v[14:17]
	v_mfma_f32_16x16x32_bf16 v[10:13], v[142:145], v[240:243], v[10:13]
	s_setprio 0
	s_setprio 1
	v_mfma_f32_16x16x32_bf16 v[54:57], v[146:149], v[176:179], v[54:57]
	v_mfma_f32_16x16x32_bf16 v[50:53], v[168:171], v[176:179], v[50:53]
	v_mfma_f32_16x16x32_bf16 v[38:41], v[146:149], v[202:205], v[38:41]
	v_mfma_f32_16x16x32_bf16 v[34:37], v[168:171], v[202:205], v[34:37]
	v_mfma_f32_16x16x32_bf16 v[22:25], v[146:149], v[210:213], v[22:25]
	v_mfma_f32_16x16x32_bf16 v[18:21], v[168:171], v[210:213], v[18:21]
	v_mfma_f32_16x16x32_bf16 v[6:9], v[146:149], v[236:239], v[6:9]
	v_mfma_f32_16x16x32_bf16 v[2:5], v[168:171], v[236:239], v[2:5]
	v_mfma_f32_16x16x32_bf16 v[54:57], v[150:153], v[180:183], v[54:57]
	v_mfma_f32_16x16x32_bf16 v[50:53], v[172:175], v[180:183], v[50:53]
	v_mfma_f32_16x16x32_bf16 v[38:41], v[150:153], v[206:209], v[38:41]
	v_mfma_f32_16x16x32_bf16 v[34:37], v[172:175], v[206:209], v[34:37]
	v_mfma_f32_16x16x32_bf16 v[22:25], v[150:153], v[232:235], v[22:25]
	v_mfma_f32_16x16x32_bf16 v[18:21], v[172:175], v[232:235], v[18:21]
	v_mfma_f32_16x16x32_bf16 v[6:9], v[150:153], v[240:243], v[6:9]
	v_mfma_f32_16x16x32_bf16 v[2:5], v[172:175], v[240:243], v[2:5]
	s_setprio 0
	s_barrier
	s_add_i32 s49, s49, 2
	s_add_u32 s47, s47, 0x100
	s_addc_u32 s48, s48, 0
	s_cmp_gt_u32 s49, 41
	s_mov_b64 s[18:19], s[20:21]
	s_cbranch_scc0 .LBB0_1438
	s_and_b64 vcc, exec, s[14:15]
	s_cbranch_vccz .LBB0_1441
	s_barrier
